# bf16 staging: two values share one v_cvt_pk (ds_write_b16 + _d16_hi); retention output stores with scalar base + 32-bit row offsets instead of 64-bit address math per store
# speedup vs baseline: 1.0905x; 1.0038x over previous
.LBB0_299:
	v_lshl_or_b32 v134, v145, 5, v1
	v_mul_lo_u32 v135, v144, s3
	v_lshl_add_u32 v118, v134, 1, v135
	v_cvt_pk_bf16_f32 v114, v139, v141
	ds_write_b16 v118, v114
	ds_write_b16_d16_hi v118, v114 offset:32
	v_cvt_pk_bf16_f32 v114, v138, v140
	ds_write_b16 v118, v114 offset:256
	v_or_b32_e32 v136, 1, v144
	ds_write_b16_d16_hi v118, v114 offset:288
	v_lshl_add_u32 v114, v136, 2, v220
	v_mov_b32_e32 v130, v213
	v_mov_b32_e32 v118, v127
	v_mov_b32_e32 v114, v123
	s_cmp_gt_i32 s7, 1
	s_mov_b64 s[10:11], -1
	v_pk_mul_f32 v[126:127], v[118:119], v[130:131] op_sel_hi:[1,0]
	v_mov_b32_e32 v118, v123
	v_pk_mul_f32 v[122:123], v[114:115], v[130:131] op_sel_hi:[1,0]
	v_pk_mul_f32 v[118:119], v[118:119], v[130:131] op_sel_hi:[1,0]
	v_mov_b32_e32 v114, v126
	v_mov_b32_e32 v115, v123
	s_cbranch_scc0 .LBB0_301
	v_mul_f32_e32 v130, 0xbfb8aa3b, v123
	v_exp_f32_e32 v130, v130
	v_mul_f32_e32 v131, 0xbfb8aa3b, v119
	v_exp_f32_e32 v131, v131
	v_mul_f32_e32 v133, 0xbfb8aa3b, v118
	v_add_f32_e32 v130, 1.0, v130
	v_exp_f32_e32 v137, v133
	v_add_f32_e32 v132, 1.0, v131
	v_rcp_f32_e32 v131, v130
	v_mul_f32_e32 v130, 0xbfb8aa3b, v126
	v_exp_f32_e32 v130, v130
	v_rcp_f32_e32 v133, v132
	v_add_f32_e32 v132, 1.0, v137
	v_rcp_f32_e32 v132, v132
	v_add_f32_e32 v130, 1.0, v130
	v_rcp_f32_e32 v130, v130
	s_mov_b64 s[10:11], 0
	v_pk_mul_f32 v[132:133], v[118:119], v[132:133]
	v_pk_mul_f32 v[130:131], v[114:115], v[130:131]

.LBB0_307:
	v_add_u32_e32 v135, 0x210, v135
	v_lshl_add_u32 v115, v134, 1, v135
	v_cvt_pk_bf16_f32 v114, v131, v133
	ds_write_b16 v115, v114
	ds_write_b16_d16_hi v115, v114 offset:32
	v_cvt_pk_bf16_f32 v114, v130, v132
	ds_write_b16 v115, v114 offset:256
	v_or_b32_e32 v136, 2, v144
	ds_write_b16_d16_hi v115, v114 offset:288
	v_lshl_add_u32 v114, v136, 2, v220
	v_mov_b32_e32 v114, v214
	v_mov_b32_e32 v118, v128
	v_mov_b32_e32 v119, v120
	v_mov_b32_e32 v126, v124
	v_mov_b32_e32 v127, v120
	v_mov_b32_e32 v130, v124
	v_mov_b32_e32 v131, v116
	v_pk_mul_f32 v[122:123], v[118:119], v[114:115] op_sel_hi:[1,0]
	v_pk_mul_f32 v[118:119], v[126:127], v[114:115] op_sel_hi:[1,0]
	v_pk_mul_f32 v[126:127], v[130:131], v[114:115] op_sel_hi:[1,0]
	v_mov_b32_e32 v114, v122
	v_mov_b32_e32 v115, v127
	s_cmp_gt_i32 s7, 1
	s_mov_b64 s[10:11], -1
	s_cbranch_scc0 .LBB0_309
	v_mul_f32_e32 v116, 0xbfb8aa3b, v127
	v_exp_f32_e32 v116, v116
	v_mul_f32_e32 v120, 0xbfb8aa3b, v119
	v_mul_f32_e32 v124, 0xbfb8aa3b, v118
	v_exp_f32_e32 v120, v120
	v_add_f32_e32 v116, 1.0, v116
	v_rcp_f32_e32 v131, v116
	v_mul_f32_e32 v116, 0xbfb8aa3b, v122
	v_exp_f32_e32 v116, v116
	v_exp_f32_e32 v124, v124
	v_add_f32_e32 v120, 1.0, v120
	v_rcp_f32_e32 v133, v120
	v_add_f32_e32 v116, 1.0, v116
	v_rcp_f32_e32 v130, v116
	v_add_f32_e32 v116, 1.0, v124
	v_rcp_f32_e32 v132, v116
	s_mov_b64 s[10:11], 0
	v_pk_mul_f32 v[130:131], v[114:115], v[130:131]
	v_pk_mul_f32 v[132:133], v[118:119], v[132:133]

.LBB0_315:
	v_add_u32_e32 v126, 0x210, v135
	v_lshl_add_u32 v115, v134, 1, v126
	v_cvt_pk_bf16_f32 v114, v131, v133
	ds_write_b16 v115, v114
	ds_write_b16_d16_hi v115, v114 offset:32
	v_cvt_pk_bf16_f32 v114, v130, v132
	ds_write_b16 v115, v114 offset:256
	v_or_b32_e32 v127, 3, v144
	ds_write_b16_d16_hi v115, v114 offset:288
	v_lshl_add_u32 v114, v127, 2, v220
	v_mov_b32_e32 v114, v215
	v_mov_b32_e32 v120, v129
	v_mov_b32_e32 v116, v125
	s_cmp_gt_i32 s7, 1
	s_mov_b64 s[10:11], -1
	v_pk_mul_f32 v[118:119], v[120:121], v[114:115] op_sel_hi:[1,0]
	v_mov_b32_e32 v120, v125
	v_pk_mul_f32 v[122:123], v[116:117], v[114:115] op_sel_hi:[1,0]
	v_pk_mul_f32 v[116:117], v[120:121], v[114:115] op_sel_hi:[1,0]
	v_mov_b32_e32 v114, v118
	v_mov_b32_e32 v115, v123
	s_cbranch_scc0 .LBB0_317
	v_mul_f32_e32 v120, 0xbfb8aa3b, v123
	v_exp_f32_e32 v120, v120
	v_mul_f32_e32 v121, 0xbfb8aa3b, v117
	v_exp_f32_e32 v121, v121
	v_mul_f32_e32 v125, 0xbfb8aa3b, v116
	v_add_f32_e32 v120, 1.0, v120
	v_exp_f32_e32 v128, v125
	v_add_f32_e32 v124, 1.0, v121
	v_rcp_f32_e32 v121, v120
	v_mul_f32_e32 v120, 0xbfb8aa3b, v118
	v_exp_f32_e32 v120, v120
	v_rcp_f32_e32 v125, v124
	v_add_f32_e32 v124, 1.0, v128
	v_rcp_f32_e32 v124, v124
	v_add_f32_e32 v120, 1.0, v120
	v_rcp_f32_e32 v120, v120
	s_mov_b64 s[10:11], 0
	v_pk_mul_f32 v[124:125], v[116:117], v[124:125]
	v_pk_mul_f32 v[120:121], v[114:115], v[120:121]

.LBB0_323:
	v_add_u32_e32 v126, 0x210, v126
	v_lshl_add_u32 v115, v134, 1, v126
	v_cvt_pk_bf16_f32 v114, v121, v125
	ds_write_b16 v115, v114
	ds_write_b16_d16_hi v115, v114 offset:32
	v_cvt_pk_bf16_f32 v114, v120, v124
	ds_write_b16 v115, v114 offset:256
	v_or_b32_e32 v127, 16, v144
	ds_write_b16_d16_hi v115, v114 offset:288
	v_lshl_add_u32 v114, v127, 2, v220
	v_mov_b32_e32 v114, v224
	v_mov_b32_e32 v116, v110
	v_mov_b32_e32 v117, v102
	v_mov_b32_e32 v120, v106
	v_mov_b32_e32 v121, v102
	v_mov_b32_e32 v122, v106
	v_mov_b32_e32 v123, v98
	v_pk_mul_f32 v[118:119], v[116:117], v[114:115] op_sel_hi:[1,0]
	v_pk_mul_f32 v[116:117], v[120:121], v[114:115] op_sel_hi:[1,0]
	v_pk_mul_f32 v[120:121], v[122:123], v[114:115] op_sel_hi:[1,0]
	v_mov_b32_e32 v114, v118
	v_mov_b32_e32 v115, v121
	s_cmp_gt_i32 s7, 1
	s_mov_b64 s[10:11], -1
	s_cbranch_scc0 .LBB0_325
	v_mul_f32_e32 v98, 0xbfb8aa3b, v121
	v_exp_f32_e32 v98, v98
	v_mul_f32_e32 v102, 0xbfb8aa3b, v117
	v_mul_f32_e32 v106, 0xbfb8aa3b, v116
	v_exp_f32_e32 v102, v102
	v_add_f32_e32 v98, 1.0, v98
	v_rcp_f32_e32 v123, v98
	v_mul_f32_e32 v98, 0xbfb8aa3b, v118
	v_exp_f32_e32 v98, v98
	v_exp_f32_e32 v106, v106
	v_add_f32_e32 v102, 1.0, v102
	v_rcp_f32_e32 v125, v102
	v_add_f32_e32 v98, 1.0, v98
	v_rcp_f32_e32 v122, v98
	v_add_f32_e32 v98, 1.0, v106
	v_rcp_f32_e32 v124, v98
	s_mov_b64 s[10:11], 0
	v_pk_mul_f32 v[122:123], v[114:115], v[122:123]
	v_pk_mul_f32 v[124:125], v[116:117], v[124:125]

.LBB0_331:
	v_add_u32_e32 v118, 0x1ad0, v126
	v_lshl_add_u32 v102, v134, 1, v118
	v_cvt_pk_bf16_f32 v98, v123, v125
	ds_write_b16 v102, v98
	ds_write_b16_d16_hi v102, v98 offset:32
	v_cvt_pk_bf16_f32 v98, v122, v124
	ds_write_b16 v102, v98 offset:256
	v_or_b32_e32 v119, 17, v144
	ds_write_b16_d16_hi v102, v98 offset:288
	v_lshl_add_u32 v98, v119, 2, v220
	v_mov_b32_e32 v114, v225
	v_mov_b32_e32 v102, v111
	v_mov_b32_e32 v98, v107
	s_cmp_gt_i32 s7, 1
	s_mov_b64 s[10:11], -1
	v_pk_mul_f32 v[110:111], v[102:103], v[114:115] op_sel_hi:[1,0]
	v_mov_b32_e32 v102, v107
	v_pk_mul_f32 v[106:107], v[98:99], v[114:115] op_sel_hi:[1,0]
	v_pk_mul_f32 v[102:103], v[102:103], v[114:115] op_sel_hi:[1,0]
	v_mov_b32_e32 v98, v110
	v_mov_b32_e32 v99, v107
	s_cbranch_scc0 .LBB0_333
	v_mul_f32_e32 v114, 0xbfb8aa3b, v107
	v_exp_f32_e32 v114, v114
	v_mul_f32_e32 v115, 0xbfb8aa3b, v103
	v_exp_f32_e32 v115, v115
	v_mul_f32_e32 v117, 0xbfb8aa3b, v102
	v_add_f32_e32 v114, 1.0, v114
	v_exp_f32_e32 v120, v117
	v_add_f32_e32 v116, 1.0, v115
	v_rcp_f32_e32 v115, v114
	v_mul_f32_e32 v114, 0xbfb8aa3b, v110
	v_exp_f32_e32 v114, v114
	v_rcp_f32_e32 v117, v116
	v_add_f32_e32 v116, 1.0, v120
	v_rcp_f32_e32 v116, v116
	v_add_f32_e32 v114, 1.0, v114
	v_rcp_f32_e32 v114, v114
	s_mov_b64 s[10:11], 0
	v_pk_mul_f32 v[116:117], v[102:103], v[116:117]
	v_pk_mul_f32 v[114:115], v[98:99], v[114:115]

.LBB0_339:
	v_add_u32_e32 v118, 0x210, v118
	v_lshl_add_u32 v99, v134, 1, v118
	v_cvt_pk_bf16_f32 v98, v115, v117
	ds_write_b16 v99, v98
	ds_write_b16_d16_hi v99, v98 offset:32
	v_cvt_pk_bf16_f32 v98, v114, v116
	ds_write_b16 v99, v98 offset:256
	v_or_b32_e32 v119, 18, v144
	ds_write_b16_d16_hi v99, v98 offset:288
	v_lshl_add_u32 v98, v119, 2, v220
	v_mov_b32_e32 v98, v226
	v_mov_b32_e32 v102, v112
	v_mov_b32_e32 v103, v104
	v_mov_b32_e32 v110, v108
	v_mov_b32_e32 v111, v104
	v_mov_b32_e32 v114, v108
	v_mov_b32_e32 v115, v100
	v_pk_mul_f32 v[106:107], v[102:103], v[98:99] op_sel_hi:[1,0]
	v_pk_mul_f32 v[102:103], v[110:111], v[98:99] op_sel_hi:[1,0]
	v_pk_mul_f32 v[110:111], v[114:115], v[98:99] op_sel_hi:[1,0]
	v_mov_b32_e32 v98, v106
	v_mov_b32_e32 v99, v111
	s_cmp_gt_i32 s7, 1
	s_mov_b64 s[10:11], -1
	s_cbranch_scc0 .LBB0_341
	v_mul_f32_e32 v100, 0xbfb8aa3b, v111
	v_exp_f32_e32 v100, v100
	v_mul_f32_e32 v104, 0xbfb8aa3b, v103
	v_mul_f32_e32 v108, 0xbfb8aa3b, v102
	v_exp_f32_e32 v104, v104
	v_add_f32_e32 v100, 1.0, v100
	v_rcp_f32_e32 v115, v100
	v_mul_f32_e32 v100, 0xbfb8aa3b, v106
	v_exp_f32_e32 v100, v100
	v_exp_f32_e32 v108, v108
	v_add_f32_e32 v104, 1.0, v104
	v_rcp_f32_e32 v117, v104
	v_add_f32_e32 v100, 1.0, v100
	v_rcp_f32_e32 v114, v100
	v_add_f32_e32 v100, 1.0, v108
	v_rcp_f32_e32 v116, v100
	s_mov_b64 s[10:11], 0
	v_pk_mul_f32 v[114:115], v[98:99], v[114:115]
	v_pk_mul_f32 v[116:117], v[102:103], v[116:117]

.LBB0_347:
	v_add_u32_e32 v110, 0x210, v118
	v_lshl_add_u32 v99, v134, 1, v110
	v_cvt_pk_bf16_f32 v98, v115, v117
	ds_write_b16 v99, v98
	ds_write_b16_d16_hi v99, v98 offset:32
	v_cvt_pk_bf16_f32 v98, v114, v116
	ds_write_b16 v99, v98 offset:256
	v_or_b32_e32 v111, 19, v144
	ds_write_b16_d16_hi v99, v98 offset:288
	v_lshl_add_u32 v98, v111, 2, v220
	v_mov_b32_e32 v98, v227
	v_mov_b32_e32 v104, v113
	v_mov_b32_e32 v100, v109
	s_cmp_gt_i32 s7, 1
	s_mov_b64 s[10:11], -1
	v_pk_mul_f32 v[102:103], v[104:105], v[98:99] op_sel_hi:[1,0]
	v_mov_b32_e32 v104, v109
	v_pk_mul_f32 v[106:107], v[100:101], v[98:99] op_sel_hi:[1,0]
	v_pk_mul_f32 v[100:101], v[104:105], v[98:99] op_sel_hi:[1,0]
	v_mov_b32_e32 v98, v102
	v_mov_b32_e32 v99, v107
	s_cbranch_scc0 .LBB0_349
	v_mul_f32_e32 v104, 0xbfb8aa3b, v107
	v_exp_f32_e32 v104, v104
	v_mul_f32_e32 v105, 0xbfb8aa3b, v101
	v_exp_f32_e32 v105, v105
	v_mul_f32_e32 v109, 0xbfb8aa3b, v100
	v_add_f32_e32 v104, 1.0, v104
	v_exp_f32_e32 v112, v109
	v_add_f32_e32 v108, 1.0, v105
	v_rcp_f32_e32 v105, v104
	v_mul_f32_e32 v104, 0xbfb8aa3b, v102
	v_exp_f32_e32 v104, v104
	v_rcp_f32_e32 v109, v108
	v_add_f32_e32 v108, 1.0, v112
	v_rcp_f32_e32 v108, v108
	v_add_f32_e32 v104, 1.0, v104
	v_rcp_f32_e32 v104, v104
	s_mov_b64 s[10:11], 0
	v_pk_mul_f32 v[108:109], v[100:101], v[108:109]
	v_pk_mul_f32 v[104:105], v[98:99], v[104:105]

.LBB0_355:
	v_add_u32_e32 v110, 0x210, v110
	v_lshl_add_u32 v99, v134, 1, v110
	v_cvt_pk_bf16_f32 v98, v105, v109
	ds_write_b16 v99, v98
	ds_write_b16_d16_hi v99, v98 offset:32
	v_cvt_pk_bf16_f32 v98, v104, v108
	ds_write_b16 v99, v98 offset:256
	v_or_b32_e32 v111, 32, v144
	ds_write_b16_d16_hi v99, v98 offset:288
	v_lshl_add_u32 v98, v111, 2, v220
	v_mov_b32_e32 v98, v228
	v_mov_b32_e32 v100, v94
	v_mov_b32_e32 v101, v86
	v_mov_b32_e32 v104, v90
	v_mov_b32_e32 v105, v86
	v_mov_b32_e32 v106, v90
	v_mov_b32_e32 v107, v82
	v_pk_mul_f32 v[102:103], v[100:101], v[98:99] op_sel_hi:[1,0]
	v_pk_mul_f32 v[100:101], v[104:105], v[98:99] op_sel_hi:[1,0]
	v_pk_mul_f32 v[104:105], v[106:107], v[98:99] op_sel_hi:[1,0]
	v_mov_b32_e32 v98, v102
	v_mov_b32_e32 v99, v105
	s_cmp_gt_i32 s7, 1
	s_mov_b64 s[10:11], -1
	s_cbranch_scc0 .LBB0_357
	v_mul_f32_e32 v82, 0xbfb8aa3b, v105
	v_exp_f32_e32 v82, v82
	v_mul_f32_e32 v86, 0xbfb8aa3b, v101
	v_mul_f32_e32 v90, 0xbfb8aa3b, v100
	v_exp_f32_e32 v86, v86
	v_add_f32_e32 v82, 1.0, v82
	v_rcp_f32_e32 v107, v82
	v_mul_f32_e32 v82, 0xbfb8aa3b, v102
	v_exp_f32_e32 v82, v82
	v_exp_f32_e32 v90, v90
	v_add_f32_e32 v86, 1.0, v86
	v_rcp_f32_e32 v109, v86
	v_add_f32_e32 v82, 1.0, v82
	v_rcp_f32_e32 v106, v82
	v_add_f32_e32 v82, 1.0, v90
	v_rcp_f32_e32 v108, v82
	s_mov_b64 s[10:11], 0
	v_pk_mul_f32 v[106:107], v[98:99], v[106:107]
	v_pk_mul_f32 v[108:109], v[100:101], v[108:109]

.LBB0_363:
	v_add_u32_e32 v102, 0x1ad0, v110
	v_lshl_add_u32 v86, v134, 1, v102
	v_cvt_pk_bf16_f32 v82, v107, v109
	ds_write_b16 v86, v82
	ds_write_b16_d16_hi v86, v82 offset:32
	v_cvt_pk_bf16_f32 v82, v106, v108
	ds_write_b16 v86, v82 offset:256
	v_or_b32_e32 v103, 33, v144
	ds_write_b16_d16_hi v86, v82 offset:288
	v_lshl_add_u32 v82, v103, 2, v220
	v_mov_b32_e32 v98, v229
	v_mov_b32_e32 v86, v95
	v_mov_b32_e32 v82, v91
	s_cmp_gt_i32 s7, 1
	s_mov_b64 s[10:11], -1
	v_pk_mul_f32 v[94:95], v[86:87], v[98:99] op_sel_hi:[1,0]
	v_mov_b32_e32 v86, v91
	v_pk_mul_f32 v[90:91], v[82:83], v[98:99] op_sel_hi:[1,0]
	v_pk_mul_f32 v[86:87], v[86:87], v[98:99] op_sel_hi:[1,0]
	v_mov_b32_e32 v82, v94
	v_mov_b32_e32 v83, v91
	s_cbranch_scc0 .LBB0_365
	v_mul_f32_e32 v98, 0xbfb8aa3b, v91
	v_exp_f32_e32 v98, v98
	v_mul_f32_e32 v99, 0xbfb8aa3b, v87
	v_exp_f32_e32 v99, v99
	v_mul_f32_e32 v101, 0xbfb8aa3b, v86
	v_add_f32_e32 v98, 1.0, v98
	v_exp_f32_e32 v104, v101
	v_add_f32_e32 v100, 1.0, v99
	v_rcp_f32_e32 v99, v98
	v_mul_f32_e32 v98, 0xbfb8aa3b, v94
	v_exp_f32_e32 v98, v98
	v_rcp_f32_e32 v101, v100
	v_add_f32_e32 v100, 1.0, v104
	v_rcp_f32_e32 v100, v100
	v_add_f32_e32 v98, 1.0, v98
	v_rcp_f32_e32 v98, v98
	s_mov_b64 s[10:11], 0
	v_pk_mul_f32 v[100:101], v[86:87], v[100:101]
	v_pk_mul_f32 v[98:99], v[82:83], v[98:99]

.LBB0_371:
	v_add_u32_e32 v102, 0x210, v102
	v_lshl_add_u32 v83, v134, 1, v102
	v_cvt_pk_bf16_f32 v82, v99, v101
	ds_write_b16 v83, v82
	ds_write_b16_d16_hi v83, v82 offset:32
	v_cvt_pk_bf16_f32 v82, v98, v100
	ds_write_b16 v83, v82 offset:256
	v_or_b32_e32 v103, 34, v144
	ds_write_b16_d16_hi v83, v82 offset:288
	v_lshl_add_u32 v82, v103, 2, v220
	v_mov_b32_e32 v82, v230
	v_mov_b32_e32 v86, v96
	v_mov_b32_e32 v87, v88
	v_mov_b32_e32 v94, v92
	v_mov_b32_e32 v95, v88
	v_mov_b32_e32 v98, v92
	v_mov_b32_e32 v99, v84
	v_pk_mul_f32 v[90:91], v[86:87], v[82:83] op_sel_hi:[1,0]
	v_pk_mul_f32 v[86:87], v[94:95], v[82:83] op_sel_hi:[1,0]
	v_pk_mul_f32 v[94:95], v[98:99], v[82:83] op_sel_hi:[1,0]
	v_mov_b32_e32 v82, v90
	v_mov_b32_e32 v83, v95
	s_cmp_gt_i32 s7, 1
	s_mov_b64 s[10:11], -1
	s_cbranch_scc0 .LBB0_373
	v_mul_f32_e32 v84, 0xbfb8aa3b, v95
	v_exp_f32_e32 v84, v84
	v_mul_f32_e32 v88, 0xbfb8aa3b, v87
	v_mul_f32_e32 v92, 0xbfb8aa3b, v86
	v_exp_f32_e32 v88, v88
	v_add_f32_e32 v84, 1.0, v84
	v_rcp_f32_e32 v99, v84
	v_mul_f32_e32 v84, 0xbfb8aa3b, v90
	v_exp_f32_e32 v84, v84
	v_exp_f32_e32 v92, v92
	v_add_f32_e32 v88, 1.0, v88
	v_rcp_f32_e32 v101, v88
	v_add_f32_e32 v84, 1.0, v84
	v_rcp_f32_e32 v98, v84
	v_add_f32_e32 v84, 1.0, v92
	v_rcp_f32_e32 v100, v84
	s_mov_b64 s[10:11], 0
	v_pk_mul_f32 v[98:99], v[82:83], v[98:99]
	v_pk_mul_f32 v[100:101], v[86:87], v[100:101]

.LBB0_379:
	v_add_u32_e32 v94, 0x210, v102
	v_lshl_add_u32 v83, v134, 1, v94
	v_cvt_pk_bf16_f32 v82, v99, v101
	ds_write_b16 v83, v82
	ds_write_b16_d16_hi v83, v82 offset:32
	v_cvt_pk_bf16_f32 v82, v98, v100
	ds_write_b16 v83, v82 offset:256
	v_or_b32_e32 v95, 35, v144
	ds_write_b16_d16_hi v83, v82 offset:288
	v_lshl_add_u32 v82, v95, 2, v220
	v_mov_b32_e32 v82, v231
	v_mov_b32_e32 v88, v97
	v_mov_b32_e32 v84, v93
	s_cmp_gt_i32 s7, 1
	s_mov_b64 s[10:11], -1
	v_pk_mul_f32 v[86:87], v[88:89], v[82:83] op_sel_hi:[1,0]
	v_mov_b32_e32 v88, v93
	v_pk_mul_f32 v[90:91], v[84:85], v[82:83] op_sel_hi:[1,0]
	v_pk_mul_f32 v[84:85], v[88:89], v[82:83] op_sel_hi:[1,0]
	v_mov_b32_e32 v82, v86
	v_mov_b32_e32 v83, v91
	s_cbranch_scc0 .LBB0_381
	v_mul_f32_e32 v88, 0xbfb8aa3b, v91
	v_exp_f32_e32 v88, v88
	v_mul_f32_e32 v89, 0xbfb8aa3b, v85
	v_exp_f32_e32 v89, v89
	v_mul_f32_e32 v93, 0xbfb8aa3b, v84
	v_add_f32_e32 v88, 1.0, v88
	v_exp_f32_e32 v96, v93
	v_add_f32_e32 v92, 1.0, v89
	v_rcp_f32_e32 v89, v88
	v_mul_f32_e32 v88, 0xbfb8aa3b, v86
	v_exp_f32_e32 v88, v88
	v_rcp_f32_e32 v93, v92
	v_add_f32_e32 v92, 1.0, v96
	v_rcp_f32_e32 v92, v92
	v_add_f32_e32 v88, 1.0, v88
	v_rcp_f32_e32 v88, v88
	s_mov_b64 s[10:11], 0
	v_pk_mul_f32 v[92:93], v[84:85], v[92:93]
	v_pk_mul_f32 v[88:89], v[82:83], v[88:89]

.LBB0_387:
	v_add_u32_e32 v94, 0x210, v94
	v_lshl_add_u32 v83, v134, 1, v94
	v_cvt_pk_bf16_f32 v82, v89, v93
	ds_write_b16 v83, v82
	ds_write_b16_d16_hi v83, v82 offset:32
	v_cvt_pk_bf16_f32 v82, v88, v92
	ds_write_b16 v83, v82 offset:256
	v_or_b32_e32 v95, 48, v144
	ds_write_b16_d16_hi v83, v82 offset:288
	v_lshl_add_u32 v82, v95, 2, v220
	v_mov_b32_e32 v82, v232
	v_mov_b32_e32 v84, v78
	v_mov_b32_e32 v85, v70
	v_mov_b32_e32 v88, v74
	v_mov_b32_e32 v89, v70
	v_mov_b32_e32 v90, v74
	v_mov_b32_e32 v91, v66
	v_pk_mul_f32 v[86:87], v[84:85], v[82:83] op_sel_hi:[1,0]
	v_pk_mul_f32 v[84:85], v[88:89], v[82:83] op_sel_hi:[1,0]
	v_pk_mul_f32 v[88:89], v[90:91], v[82:83] op_sel_hi:[1,0]
	v_mov_b32_e32 v82, v86
	v_mov_b32_e32 v83, v89
	s_cmp_gt_i32 s7, 1
	s_mov_b64 s[10:11], -1
	s_cbranch_scc0 .LBB0_389
	v_mul_f32_e32 v66, 0xbfb8aa3b, v89
	v_exp_f32_e32 v66, v66
	v_mul_f32_e32 v70, 0xbfb8aa3b, v85
	v_mul_f32_e32 v74, 0xbfb8aa3b, v84
	v_exp_f32_e32 v70, v70
	v_add_f32_e32 v66, 1.0, v66
	v_rcp_f32_e32 v91, v66
	v_mul_f32_e32 v66, 0xbfb8aa3b, v86
	v_exp_f32_e32 v66, v66
	v_exp_f32_e32 v74, v74
	v_add_f32_e32 v70, 1.0, v70
	v_rcp_f32_e32 v93, v70
	v_add_f32_e32 v66, 1.0, v66
	v_rcp_f32_e32 v90, v66
	v_add_f32_e32 v66, 1.0, v74
	v_rcp_f32_e32 v92, v66
	s_mov_b64 s[10:11], 0
	v_pk_mul_f32 v[90:91], v[82:83], v[90:91]
	v_pk_mul_f32 v[92:93], v[84:85], v[92:93]

.LBB0_395:
	v_add_u32_e32 v86, 0x1ad0, v94
	v_lshl_add_u32 v70, v134, 1, v86
	v_cvt_pk_bf16_f32 v66, v91, v93
	ds_write_b16 v70, v66
	ds_write_b16_d16_hi v70, v66 offset:32
	v_cvt_pk_bf16_f32 v66, v90, v92
	ds_write_b16 v70, v66 offset:256
	v_or_b32_e32 v87, 49, v144
	ds_write_b16_d16_hi v70, v66 offset:288
	v_lshl_add_u32 v66, v87, 2, v220
	v_mov_b32_e32 v82, v233
	v_mov_b32_e32 v70, v79
	v_mov_b32_e32 v66, v75
	s_cmp_gt_i32 s7, 1
	s_mov_b64 s[10:11], -1
	v_pk_mul_f32 v[78:79], v[70:71], v[82:83] op_sel_hi:[1,0]
	v_mov_b32_e32 v70, v75
	v_pk_mul_f32 v[74:75], v[66:67], v[82:83] op_sel_hi:[1,0]
	v_pk_mul_f32 v[70:71], v[70:71], v[82:83] op_sel_hi:[1,0]
	v_mov_b32_e32 v66, v78
	v_mov_b32_e32 v67, v75
	s_cbranch_scc0 .LBB0_397
	v_mul_f32_e32 v82, 0xbfb8aa3b, v75
	v_exp_f32_e32 v82, v82
	v_mul_f32_e32 v83, 0xbfb8aa3b, v71
	v_exp_f32_e32 v83, v83
	v_mul_f32_e32 v85, 0xbfb8aa3b, v70
	v_add_f32_e32 v82, 1.0, v82
	v_exp_f32_e32 v88, v85
	v_add_f32_e32 v84, 1.0, v83
	v_rcp_f32_e32 v83, v82
	v_mul_f32_e32 v82, 0xbfb8aa3b, v78
	v_exp_f32_e32 v82, v82
	v_rcp_f32_e32 v85, v84
	v_add_f32_e32 v84, 1.0, v88
	v_rcp_f32_e32 v84, v84
	v_add_f32_e32 v82, 1.0, v82
	v_rcp_f32_e32 v82, v82
	s_mov_b64 s[10:11], 0
	v_pk_mul_f32 v[84:85], v[70:71], v[84:85]
	v_pk_mul_f32 v[82:83], v[66:67], v[82:83]

.LBB0_403:
	v_add_u32_e32 v86, 0x210, v86
	v_lshl_add_u32 v67, v134, 1, v86
	v_cvt_pk_bf16_f32 v66, v83, v85
	ds_write_b16 v67, v66
	ds_write_b16_d16_hi v67, v66 offset:32
	v_cvt_pk_bf16_f32 v66, v82, v84
	ds_write_b16 v67, v66 offset:256
	v_or_b32_e32 v87, 50, v144
	ds_write_b16_d16_hi v67, v66 offset:288
	v_lshl_add_u32 v66, v87, 2, v220
	v_mov_b32_e32 v66, v234
	v_mov_b32_e32 v70, v80
	v_mov_b32_e32 v71, v72
	v_mov_b32_e32 v78, v76
	v_mov_b32_e32 v79, v72
	v_mov_b32_e32 v82, v76
	v_mov_b32_e32 v83, v68
	v_pk_mul_f32 v[74:75], v[70:71], v[66:67] op_sel_hi:[1,0]
	v_pk_mul_f32 v[70:71], v[78:79], v[66:67] op_sel_hi:[1,0]
	v_pk_mul_f32 v[78:79], v[82:83], v[66:67] op_sel_hi:[1,0]
	v_mov_b32_e32 v66, v74
	v_mov_b32_e32 v67, v79
	s_cmp_gt_i32 s7, 1
	s_mov_b64 s[10:11], -1
	s_cbranch_scc0 .LBB0_405
	v_mul_f32_e32 v68, 0xbfb8aa3b, v79
	v_exp_f32_e32 v68, v68
	v_mul_f32_e32 v72, 0xbfb8aa3b, v71
	v_mul_f32_e32 v76, 0xbfb8aa3b, v70
	v_exp_f32_e32 v72, v72
	v_add_f32_e32 v68, 1.0, v68
	v_rcp_f32_e32 v83, v68
	v_mul_f32_e32 v68, 0xbfb8aa3b, v74
	v_exp_f32_e32 v68, v68
	v_exp_f32_e32 v76, v76
	v_add_f32_e32 v72, 1.0, v72
	v_rcp_f32_e32 v85, v72
	v_add_f32_e32 v68, 1.0, v68
	v_rcp_f32_e32 v82, v68
	v_add_f32_e32 v68, 1.0, v76
	v_rcp_f32_e32 v84, v68
	s_mov_b64 s[10:11], 0
	v_pk_mul_f32 v[82:83], v[66:67], v[82:83]
	v_pk_mul_f32 v[84:85], v[70:71], v[84:85]

.LBB0_411:
	v_add_u32_e32 v78, 0x210, v86
	v_lshl_add_u32 v67, v134, 1, v78
	v_cvt_pk_bf16_f32 v66, v83, v85
	ds_write_b16 v67, v66
	ds_write_b16_d16_hi v67, v66 offset:32
	v_cvt_pk_bf16_f32 v66, v82, v84
	ds_write_b16 v67, v66 offset:256
	v_or_b32_e32 v79, 51, v144
	ds_write_b16_d16_hi v67, v66 offset:288
	v_lshl_add_u32 v66, v79, 2, v220
	v_mov_b32_e32 v66, v235
	v_mov_b32_e32 v72, v81
	v_mov_b32_e32 v68, v77
	s_cmp_gt_i32 s7, 1
	s_mov_b64 s[10:11], -1
	v_pk_mul_f32 v[70:71], v[72:73], v[66:67] op_sel_hi:[1,0]
	v_mov_b32_e32 v72, v77
	v_pk_mul_f32 v[74:75], v[68:69], v[66:67] op_sel_hi:[1,0]
	v_pk_mul_f32 v[68:69], v[72:73], v[66:67] op_sel_hi:[1,0]
	v_mov_b32_e32 v66, v70
	v_mov_b32_e32 v67, v75
	s_cbranch_scc0 .LBB0_413
	v_mul_f32_e32 v72, 0xbfb8aa3b, v75
	v_exp_f32_e32 v72, v72
	v_mul_f32_e32 v73, 0xbfb8aa3b, v69
	v_exp_f32_e32 v73, v73
	v_mul_f32_e32 v77, 0xbfb8aa3b, v68
	v_add_f32_e32 v72, 1.0, v72
	v_exp_f32_e32 v80, v77
	v_add_f32_e32 v76, 1.0, v73
	v_rcp_f32_e32 v73, v72
	v_mul_f32_e32 v72, 0xbfb8aa3b, v70
	v_exp_f32_e32 v72, v72
	v_rcp_f32_e32 v77, v76
	v_add_f32_e32 v76, 1.0, v80
	v_rcp_f32_e32 v76, v76
	v_add_f32_e32 v72, 1.0, v72
	v_rcp_f32_e32 v72, v72
	s_mov_b64 s[10:11], 0
	v_pk_mul_f32 v[76:77], v[68:69], v[76:77]
	v_pk_mul_f32 v[72:73], v[66:67], v[72:73]

.LBB0_419:
	v_add_u32_e32 v78, 0x210, v78
	v_lshl_add_u32 v67, v134, 1, v78
	v_cvt_pk_bf16_f32 v66, v73, v77
	ds_write_b16 v67, v66
	ds_write_b16_d16_hi v67, v66 offset:32
	v_cvt_pk_bf16_f32 v66, v72, v76
	ds_write_b16 v67, v66 offset:256
	ds_write_b16_d16_hi v67, v66 offset:288
	v_mov_b32_e32 v66, v236
	v_mov_b32_e32 v68, v62
	v_mov_b32_e32 v69, v54
	v_mov_b32_e32 v72, v58
	v_mov_b32_e32 v73, v54
	v_mov_b32_e32 v74, v58
	v_mov_b32_e32 v75, v50
	v_pk_mul_f32 v[70:71], v[68:69], v[66:67] op_sel_hi:[1,0]
	v_pk_mul_f32 v[68:69], v[72:73], v[66:67] op_sel_hi:[1,0]
	v_pk_mul_f32 v[72:73], v[74:75], v[66:67] op_sel_hi:[1,0]
	v_mov_b32_e32 v66, v70
	v_mov_b32_e32 v67, v73
	s_cmp_gt_i32 s7, 1
	s_mov_b64 s[10:11], -1
	s_cbranch_scc0 .LBB0_421
	v_mul_f32_e32 v50, 0xbfb8aa3b, v73
	v_exp_f32_e32 v50, v50
	v_mul_f32_e32 v54, 0xbfb8aa3b, v69
	v_mul_f32_e32 v58, 0xbfb8aa3b, v68
	v_exp_f32_e32 v54, v54
	v_add_f32_e32 v50, 1.0, v50
	v_rcp_f32_e32 v75, v50
	v_mul_f32_e32 v50, 0xbfb8aa3b, v70
	v_exp_f32_e32 v50, v50
	v_exp_f32_e32 v58, v58
	v_add_f32_e32 v54, 1.0, v54
	v_rcp_f32_e32 v77, v54
	v_add_f32_e32 v50, 1.0, v50
	v_rcp_f32_e32 v74, v50
	v_add_f32_e32 v50, 1.0, v58
	v_rcp_f32_e32 v76, v50
	s_mov_b64 s[10:11], 0
	v_pk_mul_f32 v[74:75], v[66:67], v[74:75]
	v_pk_mul_f32 v[76:77], v[68:69], v[76:77]

.LBB0_427:
	v_add_u32_e32 v70, 0x9ed0, v78
	v_lshl_add_u32 v54, v134, 1, v70
	v_mov_b32_e32 v66, v237
	v_cvt_pk_bf16_f32 v50, v75, v77
	ds_write_b16 v54, v50
	ds_write_b16_d16_hi v54, v50 offset:32
	v_cvt_pk_bf16_f32 v50, v74, v76
	ds_write_b16 v54, v50 offset:256
	ds_write_b16_d16_hi v54, v50 offset:288
	v_mov_b32_e32 v54, v63
	v_mov_b32_e32 v50, v59
	v_pk_mul_f32 v[62:63], v[54:55], v[66:67] op_sel_hi:[1,0]
	v_mov_b32_e32 v54, v59
	v_pk_mul_f32 v[58:59], v[50:51], v[66:67] op_sel_hi:[1,0]
	v_pk_mul_f32 v[54:55], v[54:55], v[66:67] op_sel_hi:[1,0]
	v_mov_b32_e32 v50, v62
	v_mov_b32_e32 v51, v59
	s_cmp_gt_i32 s7, 1
	s_mov_b64 s[10:11], -1
	s_cbranch_scc0 .LBB0_429
	v_mul_f32_e32 v66, 0xbfb8aa3b, v59
	v_exp_f32_e32 v66, v66
	v_mul_f32_e32 v67, 0xbfb8aa3b, v55
	v_exp_f32_e32 v67, v67
	v_mul_f32_e32 v69, 0xbfb8aa3b, v54
	v_add_f32_e32 v66, 1.0, v66
	v_exp_f32_e32 v71, v69
	v_add_f32_e32 v68, 1.0, v67
	v_rcp_f32_e32 v67, v66
	v_mul_f32_e32 v66, 0xbfb8aa3b, v62
	v_exp_f32_e32 v66, v66
	v_rcp_f32_e32 v69, v68
	v_add_f32_e32 v68, 1.0, v71
	v_rcp_f32_e32 v68, v68
	v_add_f32_e32 v66, 1.0, v66
	v_rcp_f32_e32 v66, v66
	s_mov_b64 s[10:11], 0
	v_pk_mul_f32 v[68:69], v[54:55], v[68:69]
	v_pk_mul_f32 v[66:67], v[50:51], v[66:67]

.LBB0_435:
	v_add_u32_e32 v70, 0x210, v70
	v_lshl_add_u32 v51, v134, 1, v70
	v_cvt_pk_bf16_f32 v50, v67, v69
	ds_write_b16 v51, v50
	ds_write_b16_d16_hi v51, v50 offset:32
	v_cvt_pk_bf16_f32 v50, v66, v68
	ds_write_b16 v51, v50 offset:256
	ds_write_b16_d16_hi v51, v50 offset:288
	v_mov_b32_e32 v50, v238
	v_mov_b32_e32 v54, v64
	v_mov_b32_e32 v55, v56
	v_mov_b32_e32 v62, v60
	v_mov_b32_e32 v63, v56
	v_mov_b32_e32 v66, v60
	v_mov_b32_e32 v67, v52
	v_pk_mul_f32 v[58:59], v[54:55], v[50:51] op_sel_hi:[1,0]
	v_pk_mul_f32 v[54:55], v[62:63], v[50:51] op_sel_hi:[1,0]
	v_pk_mul_f32 v[62:63], v[66:67], v[50:51] op_sel_hi:[1,0]
	v_mov_b32_e32 v50, v58
	v_mov_b32_e32 v51, v63
	s_cmp_gt_i32 s7, 1
	s_mov_b64 s[10:11], -1
	s_cbranch_scc0 .LBB0_437
	v_mul_f32_e32 v52, 0xbfb8aa3b, v63
	v_exp_f32_e32 v52, v52
	v_mul_f32_e32 v56, 0xbfb8aa3b, v55
	v_mul_f32_e32 v60, 0xbfb8aa3b, v54
	v_exp_f32_e32 v56, v56
	v_add_f32_e32 v52, 1.0, v52
	v_rcp_f32_e32 v67, v52
	v_mul_f32_e32 v52, 0xbfb8aa3b, v58
	v_exp_f32_e32 v52, v52
	v_exp_f32_e32 v60, v60
	v_add_f32_e32 v56, 1.0, v56
	v_rcp_f32_e32 v69, v56
	v_add_f32_e32 v52, 1.0, v52
	v_rcp_f32_e32 v66, v52
	v_add_f32_e32 v52, 1.0, v60
	v_rcp_f32_e32 v68, v52
	s_mov_b64 s[10:11], 0
	v_pk_mul_f32 v[66:67], v[50:51], v[66:67]
	v_pk_mul_f32 v[68:69], v[54:55], v[68:69]

.LBB0_443:
	v_add_u32_e32 v62, 0x210, v70
	v_lshl_add_u32 v51, v134, 1, v62
	v_cvt_pk_bf16_f32 v50, v67, v69
	ds_write_b16 v51, v50
	ds_write_b16_d16_hi v51, v50 offset:32
	v_cvt_pk_bf16_f32 v50, v66, v68
	ds_write_b16 v51, v50 offset:256
	ds_write_b16_d16_hi v51, v50 offset:288
	v_mov_b32_e32 v50, v239
	v_mov_b32_e32 v56, v65
	v_mov_b32_e32 v52, v61
	s_cmp_gt_i32 s7, 1
	s_mov_b64 s[10:11], -1
	v_pk_mul_f32 v[54:55], v[56:57], v[50:51] op_sel_hi:[1,0]
	v_mov_b32_e32 v56, v61
	v_pk_mul_f32 v[58:59], v[52:53], v[50:51] op_sel_hi:[1,0]
	v_pk_mul_f32 v[52:53], v[56:57], v[50:51] op_sel_hi:[1,0]
	v_mov_b32_e32 v50, v54
	v_mov_b32_e32 v51, v59
	s_cbranch_scc0 .LBB0_445
	v_mul_f32_e32 v56, 0xbfb8aa3b, v59
	v_exp_f32_e32 v56, v56
	v_mul_f32_e32 v57, 0xbfb8aa3b, v53
	v_exp_f32_e32 v57, v57
	v_mul_f32_e32 v61, 0xbfb8aa3b, v52
	v_add_f32_e32 v56, 1.0, v56
	v_exp_f32_e32 v63, v61
	v_add_f32_e32 v60, 1.0, v57
	v_rcp_f32_e32 v57, v56
	v_mul_f32_e32 v56, 0xbfb8aa3b, v54
	v_exp_f32_e32 v56, v56
	v_rcp_f32_e32 v61, v60
	v_add_f32_e32 v60, 1.0, v63
	v_rcp_f32_e32 v60, v60
	v_add_f32_e32 v56, 1.0, v56
	v_rcp_f32_e32 v56, v56
	s_mov_b64 s[10:11], 0
	v_pk_mul_f32 v[60:61], v[52:53], v[60:61]
	v_pk_mul_f32 v[56:57], v[50:51], v[56:57]

.LBB0_451:
	v_add_u32_e32 v62, 0x210, v62
	v_lshl_add_u32 v51, v134, 1, v62
	v_cvt_pk_bf16_f32 v50, v57, v61
	ds_write_b16 v51, v50
	ds_write_b16_d16_hi v51, v50 offset:32
	v_cvt_pk_bf16_f32 v50, v56, v60
	ds_write_b16 v51, v50 offset:256
	ds_write_b16_d16_hi v51, v50 offset:288
	v_mov_b32_e32 v50, v240
	v_mov_b32_e32 v52, v46
	v_mov_b32_e32 v53, v38
	v_mov_b32_e32 v56, v42
	v_mov_b32_e32 v57, v38
	v_mov_b32_e32 v58, v42
	v_mov_b32_e32 v59, v34
	v_pk_mul_f32 v[54:55], v[52:53], v[50:51] op_sel_hi:[1,0]
	v_pk_mul_f32 v[52:53], v[56:57], v[50:51] op_sel_hi:[1,0]
	v_pk_mul_f32 v[56:57], v[58:59], v[50:51] op_sel_hi:[1,0]
	v_mov_b32_e32 v50, v54
	v_mov_b32_e32 v51, v57
	s_cmp_gt_i32 s7, 1
	s_mov_b64 s[10:11], -1
	s_cbranch_scc0 .LBB0_453
	v_mul_f32_e32 v34, 0xbfb8aa3b, v57
	v_exp_f32_e32 v34, v34
	v_mul_f32_e32 v38, 0xbfb8aa3b, v53
	v_mul_f32_e32 v42, 0xbfb8aa3b, v52
	v_exp_f32_e32 v38, v38
	v_add_f32_e32 v34, 1.0, v34
	v_rcp_f32_e32 v59, v34
	v_mul_f32_e32 v34, 0xbfb8aa3b, v54
	v_exp_f32_e32 v34, v34
	v_exp_f32_e32 v42, v42
	v_add_f32_e32 v38, 1.0, v38
	v_rcp_f32_e32 v61, v38
	v_add_f32_e32 v34, 1.0, v34
	v_rcp_f32_e32 v58, v34
	v_add_f32_e32 v34, 1.0, v42
	v_rcp_f32_e32 v60, v34
	s_mov_b64 s[10:11], 0
	v_pk_mul_f32 v[58:59], v[50:51], v[58:59]
	v_pk_mul_f32 v[60:61], v[52:53], v[60:61]

.LBB0_459:
	v_add_u32_e32 v54, 0x1ad0, v62
	v_lshl_add_u32 v38, v134, 1, v54
	v_mov_b32_e32 v50, v241
	v_cvt_pk_bf16_f32 v34, v59, v61
	ds_write_b16 v38, v34
	ds_write_b16_d16_hi v38, v34 offset:32
	v_cvt_pk_bf16_f32 v34, v58, v60
	ds_write_b16 v38, v34 offset:256
	ds_write_b16_d16_hi v38, v34 offset:288
	v_mov_b32_e32 v38, v47
	v_mov_b32_e32 v34, v43
	v_pk_mul_f32 v[46:47], v[38:39], v[50:51] op_sel_hi:[1,0]
	v_mov_b32_e32 v38, v43
	v_pk_mul_f32 v[42:43], v[34:35], v[50:51] op_sel_hi:[1,0]
	v_pk_mul_f32 v[38:39], v[38:39], v[50:51] op_sel_hi:[1,0]
	v_mov_b32_e32 v34, v46
	v_mov_b32_e32 v35, v43
	s_cmp_gt_i32 s7, 1
	s_mov_b64 s[10:11], -1
	s_cbranch_scc0 .LBB0_461
	v_mul_f32_e32 v50, 0xbfb8aa3b, v43
	v_exp_f32_e32 v50, v50
	v_mul_f32_e32 v51, 0xbfb8aa3b, v39
	v_exp_f32_e32 v51, v51
	v_mul_f32_e32 v53, 0xbfb8aa3b, v38
	v_add_f32_e32 v50, 1.0, v50
	v_exp_f32_e32 v55, v53
	v_add_f32_e32 v52, 1.0, v51
	v_rcp_f32_e32 v51, v50
	v_mul_f32_e32 v50, 0xbfb8aa3b, v46
	v_exp_f32_e32 v50, v50
	v_rcp_f32_e32 v53, v52
	v_add_f32_e32 v52, 1.0, v55
	v_rcp_f32_e32 v52, v52
	v_add_f32_e32 v50, 1.0, v50
	v_rcp_f32_e32 v50, v50
	s_mov_b64 s[10:11], 0
	v_pk_mul_f32 v[52:53], v[38:39], v[52:53]
	v_pk_mul_f32 v[50:51], v[34:35], v[50:51]

.LBB0_467:
	v_add_u32_e32 v54, 0x210, v54
	v_lshl_add_u32 v35, v134, 1, v54
	v_cvt_pk_bf16_f32 v34, v51, v53
	ds_write_b16 v35, v34
	ds_write_b16_d16_hi v35, v34 offset:32
	v_cvt_pk_bf16_f32 v34, v50, v52
	ds_write_b16 v35, v34 offset:256
	ds_write_b16_d16_hi v35, v34 offset:288
	v_mov_b32_e32 v34, v242
	v_mov_b32_e32 v38, v48
	v_mov_b32_e32 v39, v40
	v_mov_b32_e32 v46, v44
	v_mov_b32_e32 v47, v40
	v_mov_b32_e32 v50, v44
	v_mov_b32_e32 v51, v36
	v_pk_mul_f32 v[42:43], v[38:39], v[34:35] op_sel_hi:[1,0]
	v_pk_mul_f32 v[38:39], v[46:47], v[34:35] op_sel_hi:[1,0]
	v_pk_mul_f32 v[46:47], v[50:51], v[34:35] op_sel_hi:[1,0]
	v_mov_b32_e32 v34, v42
	v_mov_b32_e32 v35, v47
	s_cmp_gt_i32 s7, 1
	s_mov_b64 s[10:11], -1
	s_cbranch_scc0 .LBB0_469
	v_mul_f32_e32 v36, 0xbfb8aa3b, v47
	v_exp_f32_e32 v36, v36
	v_mul_f32_e32 v40, 0xbfb8aa3b, v39
	v_mul_f32_e32 v44, 0xbfb8aa3b, v38
	v_exp_f32_e32 v40, v40
	v_add_f32_e32 v36, 1.0, v36
	v_rcp_f32_e32 v51, v36
	v_mul_f32_e32 v36, 0xbfb8aa3b, v42
	v_exp_f32_e32 v36, v36
	v_exp_f32_e32 v44, v44
	v_add_f32_e32 v40, 1.0, v40
	v_rcp_f32_e32 v53, v40
	v_add_f32_e32 v36, 1.0, v36
	v_rcp_f32_e32 v50, v36
	v_add_f32_e32 v36, 1.0, v44
	v_rcp_f32_e32 v52, v36
	s_mov_b64 s[10:11], 0
	v_pk_mul_f32 v[50:51], v[34:35], v[50:51]
	v_pk_mul_f32 v[52:53], v[38:39], v[52:53]

.LBB0_475:
	v_add_u32_e32 v46, 0x210, v54
	v_lshl_add_u32 v35, v134, 1, v46
	v_cvt_pk_bf16_f32 v34, v51, v53
	ds_write_b16 v35, v34
	ds_write_b16_d16_hi v35, v34 offset:32
	v_cvt_pk_bf16_f32 v34, v50, v52
	ds_write_b16 v35, v34 offset:256
	ds_write_b16_d16_hi v35, v34 offset:288
	v_mov_b32_e32 v34, v243
	v_mov_b32_e32 v40, v49
	v_mov_b32_e32 v36, v45
	s_cmp_gt_i32 s7, 1
	s_mov_b64 s[10:11], -1
	v_pk_mul_f32 v[38:39], v[40:41], v[34:35] op_sel_hi:[1,0]
	v_mov_b32_e32 v40, v45
	v_pk_mul_f32 v[42:43], v[36:37], v[34:35] op_sel_hi:[1,0]
	v_pk_mul_f32 v[36:37], v[40:41], v[34:35] op_sel_hi:[1,0]
	v_mov_b32_e32 v34, v38
	v_mov_b32_e32 v35, v43
	s_cbranch_scc0 .LBB0_477
	v_mul_f32_e32 v40, 0xbfb8aa3b, v43
	v_exp_f32_e32 v40, v40
	v_mul_f32_e32 v41, 0xbfb8aa3b, v37
	v_exp_f32_e32 v41, v41
	v_mul_f32_e32 v45, 0xbfb8aa3b, v36
	v_add_f32_e32 v40, 1.0, v40
	v_exp_f32_e32 v47, v45
	v_add_f32_e32 v44, 1.0, v41
	v_rcp_f32_e32 v41, v40
	v_mul_f32_e32 v40, 0xbfb8aa3b, v38
	v_exp_f32_e32 v40, v40
	v_rcp_f32_e32 v45, v44
	v_add_f32_e32 v44, 1.0, v47
	v_rcp_f32_e32 v44, v44
	v_add_f32_e32 v40, 1.0, v40
	v_rcp_f32_e32 v40, v40
	s_mov_b64 s[10:11], 0
	v_pk_mul_f32 v[44:45], v[36:37], v[44:45]
	v_pk_mul_f32 v[40:41], v[34:35], v[40:41]

.LBB0_483:
	v_add_u32_e32 v46, 0x210, v46
	v_lshl_add_u32 v35, v134, 1, v46
	v_cvt_pk_bf16_f32 v34, v41, v45
	ds_write_b16 v35, v34
	ds_write_b16_d16_hi v35, v34 offset:32
	v_cvt_pk_bf16_f32 v34, v40, v44
	ds_write_b16 v35, v34 offset:256
	ds_write_b16_d16_hi v35, v34 offset:288
	v_mov_b32_e32 v34, v244
	v_mov_b32_e32 v36, v30
	v_mov_b32_e32 v37, v22
	v_mov_b32_e32 v40, v26
	v_mov_b32_e32 v41, v22
	v_mov_b32_e32 v42, v26
	v_mov_b32_e32 v43, v18
	v_pk_mul_f32 v[38:39], v[36:37], v[34:35] op_sel_hi:[1,0]
	v_pk_mul_f32 v[36:37], v[40:41], v[34:35] op_sel_hi:[1,0]
	v_pk_mul_f32 v[40:41], v[42:43], v[34:35] op_sel_hi:[1,0]
	v_mov_b32_e32 v34, v38
	v_mov_b32_e32 v35, v41
	s_cmp_gt_i32 s7, 1
	s_mov_b64 s[10:11], -1
	s_cbranch_scc0 .LBB0_485
	v_mul_f32_e32 v18, 0xbfb8aa3b, v41
	v_exp_f32_e32 v18, v18
	v_mul_f32_e32 v22, 0xbfb8aa3b, v37
	v_mul_f32_e32 v26, 0xbfb8aa3b, v36
	v_exp_f32_e32 v22, v22
	v_add_f32_e32 v18, 1.0, v18
	v_rcp_f32_e32 v43, v18
	v_mul_f32_e32 v18, 0xbfb8aa3b, v38
	v_exp_f32_e32 v18, v18
	v_exp_f32_e32 v26, v26
	v_add_f32_e32 v22, 1.0, v22
	v_rcp_f32_e32 v45, v22
	v_add_f32_e32 v18, 1.0, v18
	v_rcp_f32_e32 v42, v18
	v_add_f32_e32 v18, 1.0, v26
	v_rcp_f32_e32 v44, v18
	s_mov_b64 s[10:11], 0
	v_pk_mul_f32 v[42:43], v[34:35], v[42:43]
	v_pk_mul_f32 v[44:45], v[36:37], v[44:45]

.LBB0_491:
	v_add_u32_e32 v38, 0x1ad0, v46
	v_lshl_add_u32 v22, v134, 1, v38
	v_mov_b32_e32 v34, v245
	v_cvt_pk_bf16_f32 v18, v43, v45
	ds_write_b16 v22, v18
	ds_write_b16_d16_hi v22, v18 offset:32
	v_cvt_pk_bf16_f32 v18, v42, v44
	ds_write_b16 v22, v18 offset:256
	ds_write_b16_d16_hi v22, v18 offset:288
	v_mov_b32_e32 v22, v31
	v_mov_b32_e32 v18, v27
	v_pk_mul_f32 v[30:31], v[22:23], v[34:35] op_sel_hi:[1,0]
	v_mov_b32_e32 v22, v27
	v_pk_mul_f32 v[26:27], v[18:19], v[34:35] op_sel_hi:[1,0]
	v_pk_mul_f32 v[22:23], v[22:23], v[34:35] op_sel_hi:[1,0]
	v_mov_b32_e32 v18, v30
	v_mov_b32_e32 v19, v27
	s_cmp_gt_i32 s7, 1
	s_mov_b64 s[10:11], -1
	s_cbranch_scc0 .LBB0_493
	v_mul_f32_e32 v34, 0xbfb8aa3b, v27
	v_exp_f32_e32 v34, v34
	v_mul_f32_e32 v35, 0xbfb8aa3b, v23
	v_exp_f32_e32 v35, v35
	v_mul_f32_e32 v37, 0xbfb8aa3b, v22
	v_add_f32_e32 v34, 1.0, v34
	v_exp_f32_e32 v39, v37
	v_add_f32_e32 v36, 1.0, v35
	v_rcp_f32_e32 v35, v34
	v_mul_f32_e32 v34, 0xbfb8aa3b, v30
	v_exp_f32_e32 v34, v34
	v_rcp_f32_e32 v37, v36
	v_add_f32_e32 v36, 1.0, v39
	v_rcp_f32_e32 v36, v36
	v_add_f32_e32 v34, 1.0, v34
	v_rcp_f32_e32 v34, v34
	s_mov_b64 s[10:11], 0
	v_pk_mul_f32 v[36:37], v[22:23], v[36:37]
	v_pk_mul_f32 v[34:35], v[18:19], v[34:35]

.LBB0_499:
	v_add_u32_e32 v38, 0x210, v38
	v_lshl_add_u32 v19, v134, 1, v38
	v_cvt_pk_bf16_f32 v18, v35, v37
	ds_write_b16 v19, v18
	ds_write_b16_d16_hi v19, v18 offset:32
	v_cvt_pk_bf16_f32 v18, v34, v36
	ds_write_b16 v19, v18 offset:256
	ds_write_b16_d16_hi v19, v18 offset:288
	v_mov_b32_e32 v18, v246
	v_mov_b32_e32 v22, v32
	v_mov_b32_e32 v23, v24
	v_mov_b32_e32 v30, v28
	v_mov_b32_e32 v31, v24
	v_mov_b32_e32 v34, v28
	v_mov_b32_e32 v35, v20
	v_pk_mul_f32 v[26:27], v[22:23], v[18:19] op_sel_hi:[1,0]
	v_pk_mul_f32 v[22:23], v[30:31], v[18:19] op_sel_hi:[1,0]
	v_pk_mul_f32 v[30:31], v[34:35], v[18:19] op_sel_hi:[1,0]
	v_mov_b32_e32 v18, v26
	v_mov_b32_e32 v19, v31
	s_cmp_gt_i32 s7, 1
	s_mov_b64 s[10:11], -1
	s_cbranch_scc0 .LBB0_501
	v_mul_f32_e32 v20, 0xbfb8aa3b, v31
	v_exp_f32_e32 v20, v20
	v_mul_f32_e32 v24, 0xbfb8aa3b, v23
	v_mul_f32_e32 v28, 0xbfb8aa3b, v22
	v_exp_f32_e32 v24, v24
	v_add_f32_e32 v20, 1.0, v20
	v_rcp_f32_e32 v35, v20
	v_mul_f32_e32 v20, 0xbfb8aa3b, v26
	v_exp_f32_e32 v20, v20
	v_exp_f32_e32 v28, v28
	v_add_f32_e32 v24, 1.0, v24
	v_rcp_f32_e32 v37, v24
	v_add_f32_e32 v20, 1.0, v20
	v_rcp_f32_e32 v34, v20
	v_add_f32_e32 v20, 1.0, v28
	v_rcp_f32_e32 v36, v20
	s_mov_b64 s[10:11], 0
	v_pk_mul_f32 v[34:35], v[18:19], v[34:35]
	v_pk_mul_f32 v[36:37], v[22:23], v[36:37]

.LBB0_507:
	v_add_u32_e32 v30, 0x210, v38
	v_lshl_add_u32 v19, v134, 1, v30
	v_cvt_pk_bf16_f32 v18, v35, v37
	ds_write_b16 v19, v18
	ds_write_b16_d16_hi v19, v18 offset:32
	v_cvt_pk_bf16_f32 v18, v34, v36
	ds_write_b16 v19, v18 offset:256
	ds_write_b16_d16_hi v19, v18 offset:288
	v_mov_b32_e32 v18, v247
	v_mov_b32_e32 v24, v33
	v_mov_b32_e32 v20, v29
	s_cmp_gt_i32 s7, 1
	s_mov_b64 s[10:11], -1
	v_pk_mul_f32 v[22:23], v[24:25], v[18:19] op_sel_hi:[1,0]
	v_mov_b32_e32 v24, v29
	v_pk_mul_f32 v[26:27], v[20:21], v[18:19] op_sel_hi:[1,0]
	v_pk_mul_f32 v[20:21], v[24:25], v[18:19] op_sel_hi:[1,0]
	v_mov_b32_e32 v18, v22
	v_mov_b32_e32 v19, v27
	s_cbranch_scc0 .LBB0_509
	v_mul_f32_e32 v24, 0xbfb8aa3b, v27
	v_exp_f32_e32 v24, v24
	v_mul_f32_e32 v25, 0xbfb8aa3b, v21
	v_exp_f32_e32 v25, v25
	v_mul_f32_e32 v29, 0xbfb8aa3b, v20
	v_add_f32_e32 v24, 1.0, v24
	v_exp_f32_e32 v31, v29
	v_add_f32_e32 v28, 1.0, v25
	v_rcp_f32_e32 v25, v24
	v_mul_f32_e32 v24, 0xbfb8aa3b, v22
	v_exp_f32_e32 v24, v24
	v_rcp_f32_e32 v29, v28
	v_add_f32_e32 v28, 1.0, v31
	v_rcp_f32_e32 v28, v28
	v_add_f32_e32 v24, 1.0, v24
	v_rcp_f32_e32 v24, v24
	s_mov_b64 s[10:11], 0
	v_pk_mul_f32 v[28:29], v[20:21], v[28:29]
	v_pk_mul_f32 v[24:25], v[18:19], v[24:25]

.LBB0_515:
	v_add_u32_e32 v30, 0x210, v30
	v_lshl_add_u32 v19, v134, 1, v30
	v_cvt_pk_bf16_f32 v18, v25, v29
	ds_write_b16 v19, v18
	ds_write_b16_d16_hi v19, v18 offset:32
	v_cvt_pk_bf16_f32 v18, v24, v28
	ds_write_b16 v19, v18 offset:256
	ds_write_b16_d16_hi v19, v18 offset:288
	v_mov_b32_e32 v18, v248
	v_mov_b32_e32 v20, v14
	v_mov_b32_e32 v21, v6
	v_mov_b32_e32 v24, v10
	v_mov_b32_e32 v25, v6
	v_mov_b32_e32 v26, v10
	v_mov_b32_e32 v27, v2
	v_pk_mul_f32 v[22:23], v[20:21], v[18:19] op_sel_hi:[1,0]
	v_pk_mul_f32 v[20:21], v[24:25], v[18:19] op_sel_hi:[1,0]
	v_pk_mul_f32 v[24:25], v[26:27], v[18:19] op_sel_hi:[1,0]
	v_mov_b32_e32 v18, v22
	v_mov_b32_e32 v19, v25
	s_cmp_gt_i32 s7, 1
	s_mov_b64 s[10:11], -1
	s_cbranch_scc0 .LBB0_517
	v_mul_f32_e32 v2, 0xbfb8aa3b, v25
	v_exp_f32_e32 v2, v2
	v_mul_f32_e32 v6, 0xbfb8aa3b, v21
	v_mul_f32_e32 v10, 0xbfb8aa3b, v20
	v_exp_f32_e32 v6, v6
	v_add_f32_e32 v2, 1.0, v2
	v_rcp_f32_e32 v27, v2
	v_mul_f32_e32 v2, 0xbfb8aa3b, v22
	v_exp_f32_e32 v2, v2
	v_exp_f32_e32 v10, v10
	v_add_f32_e32 v6, 1.0, v6
	v_rcp_f32_e32 v29, v6
	v_add_f32_e32 v2, 1.0, v2
	v_rcp_f32_e32 v26, v2
	v_add_f32_e32 v2, 1.0, v10
	v_rcp_f32_e32 v28, v2
	s_mov_b64 s[10:11], 0
	v_pk_mul_f32 v[26:27], v[18:19], v[26:27]
	v_pk_mul_f32 v[28:29], v[20:21], v[28:29]

.LBB0_523:
	v_add_u32_e32 v22, 0x1ad0, v30
	v_lshl_add_u32 v6, v134, 1, v22
	v_mov_b32_e32 v18, v249
	v_cvt_pk_bf16_f32 v2, v27, v29
	ds_write_b16 v6, v2
	ds_write_b16_d16_hi v6, v2 offset:32
	v_cvt_pk_bf16_f32 v2, v26, v28
	ds_write_b16 v6, v2 offset:256
	ds_write_b16_d16_hi v6, v2 offset:288
	v_mov_b32_e32 v6, v15
	v_mov_b32_e32 v2, v11
	v_pk_mul_f32 v[14:15], v[6:7], v[18:19] op_sel_hi:[1,0]
	v_mov_b32_e32 v6, v11
	v_pk_mul_f32 v[10:11], v[2:3], v[18:19] op_sel_hi:[1,0]
	v_pk_mul_f32 v[6:7], v[6:7], v[18:19] op_sel_hi:[1,0]
	v_mov_b32_e32 v2, v14
	v_mov_b32_e32 v3, v11
	s_cmp_gt_i32 s7, 1
	s_mov_b64 s[10:11], -1
	s_cbranch_scc0 .LBB0_525
	v_mul_f32_e32 v18, 0xbfb8aa3b, v11
	v_exp_f32_e32 v18, v18
	v_mul_f32_e32 v19, 0xbfb8aa3b, v7
	v_exp_f32_e32 v19, v19
	v_mul_f32_e32 v21, 0xbfb8aa3b, v6
	v_add_f32_e32 v18, 1.0, v18
	v_exp_f32_e32 v23, v21
	v_add_f32_e32 v20, 1.0, v19
	v_rcp_f32_e32 v19, v18
	v_mul_f32_e32 v18, 0xbfb8aa3b, v14
	v_exp_f32_e32 v18, v18
	v_rcp_f32_e32 v21, v20
	v_add_f32_e32 v20, 1.0, v23
	v_rcp_f32_e32 v20, v20
	v_add_f32_e32 v18, 1.0, v18
	v_rcp_f32_e32 v18, v18
	s_mov_b64 s[10:11], 0
	v_pk_mul_f32 v[20:21], v[6:7], v[20:21]
	v_pk_mul_f32 v[18:19], v[2:3], v[18:19]

.LBB0_531:
	v_add_u32_e32 v22, 0x210, v22
	v_lshl_add_u32 v3, v134, 1, v22
	v_cvt_pk_bf16_f32 v2, v19, v21
	ds_write_b16 v3, v2
	ds_write_b16_d16_hi v3, v2 offset:32
	v_cvt_pk_bf16_f32 v2, v18, v20
	ds_write_b16 v3, v2 offset:256
	ds_write_b16_d16_hi v3, v2 offset:288
	v_mov_b32_e32 v2, v250
	v_mov_b32_e32 v6, v16
	v_mov_b32_e32 v7, v8
	v_mov_b32_e32 v14, v12
	v_mov_b32_e32 v15, v8
	v_mov_b32_e32 v18, v12
	v_mov_b32_e32 v19, v4
	v_pk_mul_f32 v[10:11], v[6:7], v[2:3] op_sel_hi:[1,0]
	v_pk_mul_f32 v[6:7], v[14:15], v[2:3] op_sel_hi:[1,0]
	v_pk_mul_f32 v[14:15], v[18:19], v[2:3] op_sel_hi:[1,0]
	v_mov_b32_e32 v2, v10
	v_mov_b32_e32 v3, v15
	s_cmp_gt_i32 s7, 1
	s_mov_b64 s[10:11], -1
	s_cbranch_scc0 .LBB0_533
	v_mul_f32_e32 v4, 0xbfb8aa3b, v15
	v_exp_f32_e32 v4, v4
	v_mul_f32_e32 v8, 0xbfb8aa3b, v7
	v_mul_f32_e32 v12, 0xbfb8aa3b, v6
	v_exp_f32_e32 v8, v8
	v_add_f32_e32 v4, 1.0, v4
	v_rcp_f32_e32 v19, v4
	v_mul_f32_e32 v4, 0xbfb8aa3b, v10
	v_exp_f32_e32 v4, v4
	v_exp_f32_e32 v12, v12
	v_add_f32_e32 v8, 1.0, v8
	v_rcp_f32_e32 v21, v8
	v_add_f32_e32 v4, 1.0, v4
	v_rcp_f32_e32 v18, v4
	v_add_f32_e32 v4, 1.0, v12
	v_rcp_f32_e32 v20, v4
	s_mov_b64 s[10:11], 0
	v_pk_mul_f32 v[18:19], v[2:3], v[18:19]
	v_pk_mul_f32 v[20:21], v[6:7], v[20:21]

.LBB0_539:
	v_add_u32_e32 v3, 0x210, v22
	v_lshl_add_u32 v14, v134, 1, v3
	v_cvt_pk_bf16_f32 v2, v19, v21
	ds_write_b16 v14, v2
	ds_write_b16_d16_hi v14, v2 offset:32
	v_cvt_pk_bf16_f32 v2, v18, v20
	ds_write_b16 v14, v2 offset:256
	ds_write_b16_d16_hi v14, v2 offset:288
	v_mov_b32_e32 v2, v251
	v_mov_b32_e32 v8, v17
	v_mov_b32_e32 v4, v13
	s_cmp_gt_i32 s7, 1
	s_mov_b64 s[10:11], -1
	v_pk_mul_f32 v[6:7], v[8:9], v[2:3] op_sel_hi:[1,0]
	v_mov_b32_e32 v8, v13
	v_pk_mul_f32 v[10:11], v[4:5], v[2:3] op_sel_hi:[1,0]
	v_pk_mul_f32 v[4:5], v[8:9], v[2:3] op_sel_hi:[1,0]
	v_mov_b32_e32 v2, v6
	v_mov_b32_e32 v3, v11
	s_cbranch_scc0 .LBB0_541
	v_mul_f32_e32 v8, 0xbfb8aa3b, v11
	v_exp_f32_e32 v8, v8
	v_mul_f32_e32 v9, 0xbfb8aa3b, v5
	v_exp_f32_e32 v9, v9
	v_mul_f32_e32 v13, 0xbfb8aa3b, v4
	v_add_f32_e32 v8, 1.0, v8
	v_exp_f32_e32 v15, v13
	v_add_f32_e32 v12, 1.0, v9
	v_rcp_f32_e32 v9, v8
	v_mul_f32_e32 v8, 0xbfb8aa3b, v6
	v_exp_f32_e32 v8, v8
	v_rcp_f32_e32 v13, v12
	v_add_f32_e32 v12, 1.0, v15
	v_rcp_f32_e32 v12, v12
	v_add_f32_e32 v8, 1.0, v8
	v_rcp_f32_e32 v8, v8
	s_mov_b64 s[10:11], 0
	v_pk_mul_f32 v[12:13], v[4:5], v[12:13]
	v_pk_mul_f32 v[8:9], v[2:3], v[8:9]

.LBB0_547:
	v_cvt_pk_bf16_f32 v1, v9, v13
	ds_write_b16 v14, v1 offset:528
	ds_write_b16_d16_hi v14, v1 offset:560
	v_cvt_pk_bf16_f32 v1, v8, v12
	ds_write_b16 v14, v1 offset:784
	ds_write_b16_d16_hi v14, v1 offset:816
	v_mov_b32_e32 v1, v210
	s_lshl_b64 s[0:1], s[8:9], 1
	s_waitcnt lgkmcnt(0)
	s_barrier
	s_add_u32 s0, s23, s0
	v_lshlrev_b32_e32 v2, 4, v1
	v_and_b32_e32 v2, 0x1f0, v2
	s_addc_u32 s1, s24, s1
	v_mov_b32_e32 v3, v0
	v_lshl_add_u64 v[4:5], s[0:1], 0, v[2:3]
	s_mov_b32 s0, 0

.LBB0_856:
	v_or_b32_e32 v130, v139, v1
	v_mul_lo_u32 v131, v138, s3
	v_lshl_add_u32 v118, v130, 1, v131
	v_cvt_pk_bf16_f32 v114, v137, v136
	ds_write_b16 v118, v114
	ds_write_b16_d16_hi v118, v114 offset:32
	v_cvt_pk_bf16_f32 v114, v135, v134
	ds_write_b16 v118, v114 offset:256
	v_or_b32_e32 v132, 1, v138
	ds_write_b16_d16_hi v118, v114 offset:288
	v_lshl_add_u32 v114, v132, 2, v220
	v_mov_b32_e32 v118, v213
	v_mov_b32_e32 v114, v119
	v_mov_b32_e32 v122, v127
	s_cmp_gt_i32 s5, 1
	s_mov_b64 s[8:9], -1
	v_pk_mul_f32 v[114:115], v[114:115], v[118:119] op_sel_hi:[1,0]
	v_pk_mul_f32 v[118:119], v[122:123], v[118:119] op_sel_hi:[1,0]
	s_cbranch_scc0 .LBB0_858
	v_mul_f32_e32 v122, 0xbfb8aa3b, v115
	v_exp_f32_e32 v122, v122
	v_mul_f32_e32 v123, 0xbfb8aa3b, v114
	v_exp_f32_e32 v123, v123
	s_mov_b64 s[8:9], 0
	v_add_f32_e32 v122, 1.0, v122
	v_add_f32_e32 v126, 1.0, v123
	v_rcp_f32_e32 v123, v122
	v_mul_f32_e32 v122, 0xbfb8aa3b, v119
	v_exp_f32_e32 v127, v122
	v_mul_f32_e32 v122, 0xbfb8aa3b, v118
	v_exp_f32_e32 v133, v122
	v_rcp_f32_e32 v122, v126
	v_add_f32_e32 v126, 1.0, v127
	v_rcp_f32_e32 v135, v126
	v_add_f32_e32 v126, 1.0, v133
	v_rcp_f32_e32 v134, v126
	v_pk_mul_f32 v[126:127], v[114:115], v[122:123]
	v_pk_mul_f32 v[122:123], v[118:119], v[134:135]

.LBB0_862:
	v_add_u32_e32 v131, 0x210, v131
	v_lshl_add_u32 v115, v130, 1, v131
	v_cvt_pk_bf16_f32 v114, v127, v126
	ds_write_b16 v115, v114
	ds_write_b16_d16_hi v115, v114 offset:32
	v_cvt_pk_bf16_f32 v114, v123, v122
	ds_write_b16 v115, v114 offset:256
	v_or_b32_e32 v132, 2, v138
	ds_write_b16_d16_hi v115, v114 offset:288
	v_lshl_add_u32 v114, v132, 2, v220
	v_mov_b32_e32 v118, v214
	v_mov_b32_e32 v114, v120
	v_mov_b32_e32 v115, v116
	v_mov_b32_e32 v122, v128
	v_mov_b32_e32 v123, v124
	v_pk_mul_f32 v[114:115], v[114:115], v[118:119] op_sel_hi:[1,0]
	v_pk_mul_f32 v[118:119], v[122:123], v[118:119] op_sel_hi:[1,0]
	s_cmp_gt_i32 s5, 1
	s_mov_b64 s[8:9], -1
	s_cbranch_scc0 .LBB0_864
	v_mul_f32_e32 v116, 0xbfb8aa3b, v115
	v_exp_f32_e32 v116, v116
	v_mul_f32_e32 v120, 0xbfb8aa3b, v114
	v_mul_f32_e32 v122, 0xbfb8aa3b, v118
	v_exp_f32_e32 v120, v120
	v_add_f32_e32 v116, 1.0, v116
	v_rcp_f32_e32 v123, v116
	v_mul_f32_e32 v116, 0xbfb8aa3b, v119
	v_exp_f32_e32 v116, v116
	v_exp_f32_e32 v124, v122
	v_add_f32_e32 v120, 1.0, v120
	v_rcp_f32_e32 v122, v120
	v_add_f32_e32 v116, 1.0, v116
	v_rcp_f32_e32 v135, v116
	v_add_f32_e32 v116, 1.0, v124
	v_rcp_f32_e32 v134, v116
	v_pk_mul_f32 v[126:127], v[114:115], v[122:123]
	s_mov_b64 s[8:9], 0
	v_pk_mul_f32 v[122:123], v[118:119], v[134:135]

.LBB0_868:
	v_cvt_pk_bf16_f32 v114, v127, s0
	v_add_u32_e32 v127, 0x210, v131
	v_lshl_add_u32 v115, v130, 1, v127
	ds_write_b16 v115, v114
	v_cvt_pk_bf16_f32 v114, v126, v123
	ds_write_b16 v115, v114 offset:32
	ds_write_b16_d16_hi v115, v114 offset:256
	v_cvt_pk_bf16_f32 v114, v122, s0
	v_or_b32_e32 v122, 3, v138
	ds_write_b16 v115, v114 offset:288
	v_lshl_add_u32 v114, v122, 2, v220
	v_mov_b32_e32 v118, v215
	v_mov_b32_e32 v116, v121
	v_mov_b32_e32 v124, v129
	s_cmp_gt_i32 s5, 1
	s_mov_b64 s[8:9], -1
	v_pk_mul_f32 v[114:115], v[116:117], v[118:119] op_sel_hi:[1,0]
	v_pk_mul_f32 v[116:117], v[124:125], v[118:119] op_sel_hi:[1,0]
	s_cbranch_scc0 .LBB0_870
	v_mul_f32_e32 v118, 0xbfb8aa3b, v115
	v_exp_f32_e32 v118, v118
	v_mul_f32_e32 v119, 0xbfb8aa3b, v114
	v_exp_f32_e32 v119, v119
	s_mov_b64 s[8:9], 0
	v_add_f32_e32 v118, 1.0, v118
	v_add_f32_e32 v120, 1.0, v119
	v_rcp_f32_e32 v119, v118
	v_mul_f32_e32 v118, 0xbfb8aa3b, v117
	v_exp_f32_e32 v121, v118
	v_mul_f32_e32 v118, 0xbfb8aa3b, v116
	v_exp_f32_e32 v123, v118
	v_rcp_f32_e32 v118, v120
	v_add_f32_e32 v120, 1.0, v121
	v_rcp_f32_e32 v125, v120
	v_add_f32_e32 v120, 1.0, v123
	v_rcp_f32_e32 v124, v120
	v_pk_mul_f32 v[120:121], v[114:115], v[118:119]
	v_pk_mul_f32 v[118:119], v[116:117], v[124:125]

.LBB0_874:
	v_add_u32_e32 v122, 0x210, v127
	v_lshl_add_u32 v115, v130, 1, v122
	v_cvt_pk_bf16_f32 v114, v121, v120
	ds_write_b16 v115, v114
	ds_write_b16_d16_hi v115, v114 offset:32
	v_cvt_pk_bf16_f32 v114, v119, v118
	ds_write_b16 v115, v114 offset:256
	v_or_b32_e32 v123, 16, v138
	ds_write_b16_d16_hi v115, v114 offset:288
	v_lshl_add_u32 v114, v123, 2, v220
	v_mov_b32_e32 v116, v224
	v_mov_b32_e32 v114, v102
	v_mov_b32_e32 v115, v98
	v_mov_b32_e32 v118, v110
	v_mov_b32_e32 v119, v106
	v_pk_mul_f32 v[114:115], v[114:115], v[116:117] op_sel_hi:[1,0]
	v_pk_mul_f32 v[116:117], v[118:119], v[116:117] op_sel_hi:[1,0]
	s_cmp_gt_i32 s5, 1
	s_mov_b64 s[8:9], -1
	s_cbranch_scc0 .LBB0_876
	v_mul_f32_e32 v98, 0xbfb8aa3b, v115
	v_exp_f32_e32 v98, v98
	v_mul_f32_e32 v102, 0xbfb8aa3b, v114
	v_mul_f32_e32 v106, 0xbfb8aa3b, v116
	v_exp_f32_e32 v102, v102
	v_add_f32_e32 v98, 1.0, v98
	v_rcp_f32_e32 v119, v98
	v_mul_f32_e32 v98, 0xbfb8aa3b, v117
	v_exp_f32_e32 v98, v98
	v_exp_f32_e32 v106, v106
	v_add_f32_e32 v102, 1.0, v102
	v_rcp_f32_e32 v118, v102
	v_add_f32_e32 v98, 1.0, v98
	v_rcp_f32_e32 v125, v98
	v_add_f32_e32 v98, 1.0, v106
	v_rcp_f32_e32 v124, v98
	v_pk_mul_f32 v[120:121], v[114:115], v[118:119]
	s_mov_b64 s[8:9], 0
	v_pk_mul_f32 v[118:119], v[116:117], v[124:125]

.LBB0_880:
	v_add_u32_e32 v114, 0x1ad0, v122
	v_lshl_add_u32 v102, v130, 1, v114
	v_cvt_pk_bf16_f32 v98, v121, v120
	ds_write_b16 v102, v98
	ds_write_b16_d16_hi v102, v98 offset:32
	v_cvt_pk_bf16_f32 v98, v119, v118
	ds_write_b16 v102, v98 offset:256
	v_or_b32_e32 v115, 17, v138
	ds_write_b16_d16_hi v102, v98 offset:288
	v_lshl_add_u32 v98, v115, 2, v220
	v_mov_b32_e32 v102, v225
	v_mov_b32_e32 v98, v103
	v_mov_b32_e32 v106, v111
	s_cmp_gt_i32 s5, 1
	s_mov_b64 s[8:9], -1
	v_pk_mul_f32 v[98:99], v[98:99], v[102:103] op_sel_hi:[1,0]
	v_pk_mul_f32 v[102:103], v[106:107], v[102:103] op_sel_hi:[1,0]
	s_cbranch_scc0 .LBB0_882
	v_mul_f32_e32 v106, 0xbfb8aa3b, v99
	v_exp_f32_e32 v106, v106
	v_mul_f32_e32 v107, 0xbfb8aa3b, v98
	v_exp_f32_e32 v107, v107
	s_mov_b64 s[8:9], 0
	v_add_f32_e32 v106, 1.0, v106
	v_add_f32_e32 v110, 1.0, v107
	v_rcp_f32_e32 v107, v106
	v_mul_f32_e32 v106, 0xbfb8aa3b, v103
	v_exp_f32_e32 v111, v106
	v_mul_f32_e32 v106, 0xbfb8aa3b, v102
	v_exp_f32_e32 v116, v106
	v_rcp_f32_e32 v106, v110
	v_add_f32_e32 v110, 1.0, v111
	v_rcp_f32_e32 v117, v110
	v_add_f32_e32 v110, 1.0, v116
	v_rcp_f32_e32 v116, v110
	v_pk_mul_f32 v[110:111], v[98:99], v[106:107]
	v_pk_mul_f32 v[106:107], v[102:103], v[116:117]

.LBB0_886:
	v_add_u32_e32 v114, 0x210, v114
	v_lshl_add_u32 v99, v130, 1, v114
	v_cvt_pk_bf16_f32 v98, v111, v110
	ds_write_b16 v99, v98
	ds_write_b16_d16_hi v99, v98 offset:32
	v_cvt_pk_bf16_f32 v98, v107, v106
	ds_write_b16 v99, v98 offset:256
	v_or_b32_e32 v115, 18, v138
	ds_write_b16_d16_hi v99, v98 offset:288
	v_lshl_add_u32 v98, v115, 2, v220
	v_mov_b32_e32 v102, v226
	v_mov_b32_e32 v98, v104
	v_mov_b32_e32 v99, v100
	v_mov_b32_e32 v106, v112
	v_mov_b32_e32 v107, v108
	v_pk_mul_f32 v[98:99], v[98:99], v[102:103] op_sel_hi:[1,0]
	v_pk_mul_f32 v[102:103], v[106:107], v[102:103] op_sel_hi:[1,0]
	s_cmp_gt_i32 s5, 1
	s_mov_b64 s[8:9], -1
	s_cbranch_scc0 .LBB0_888
	v_mul_f32_e32 v100, 0xbfb8aa3b, v99
	v_exp_f32_e32 v100, v100
	v_mul_f32_e32 v104, 0xbfb8aa3b, v98
	v_mul_f32_e32 v106, 0xbfb8aa3b, v102
	v_exp_f32_e32 v104, v104
	v_add_f32_e32 v100, 1.0, v100
	v_rcp_f32_e32 v107, v100
	v_mul_f32_e32 v100, 0xbfb8aa3b, v103
	v_exp_f32_e32 v100, v100
	v_exp_f32_e32 v108, v106
	v_add_f32_e32 v104, 1.0, v104
	v_rcp_f32_e32 v106, v104
	v_add_f32_e32 v100, 1.0, v100
	v_rcp_f32_e32 v117, v100
	v_add_f32_e32 v100, 1.0, v108
	v_rcp_f32_e32 v116, v100
	v_pk_mul_f32 v[110:111], v[98:99], v[106:107]
	s_mov_b64 s[8:9], 0
	v_pk_mul_f32 v[106:107], v[102:103], v[116:117]

.LBB0_892:
	v_cvt_pk_bf16_f32 v98, v111, s0
	v_add_u32_e32 v111, 0x210, v114
	v_lshl_add_u32 v99, v130, 1, v111
	ds_write_b16 v99, v98
	v_cvt_pk_bf16_f32 v98, v110, v107
	ds_write_b16 v99, v98 offset:32
	ds_write_b16_d16_hi v99, v98 offset:256
	v_cvt_pk_bf16_f32 v98, v106, s0
	v_or_b32_e32 v106, 19, v138
	ds_write_b16 v99, v98 offset:288
	v_lshl_add_u32 v98, v106, 2, v220
	v_mov_b32_e32 v102, v227
	v_mov_b32_e32 v100, v105
	v_mov_b32_e32 v108, v113
	s_cmp_gt_i32 s5, 1
	s_mov_b64 s[8:9], -1
	v_pk_mul_f32 v[98:99], v[100:101], v[102:103] op_sel_hi:[1,0]
	v_pk_mul_f32 v[100:101], v[108:109], v[102:103] op_sel_hi:[1,0]
	s_cbranch_scc0 .LBB0_894
	v_mul_f32_e32 v102, 0xbfb8aa3b, v99
	v_exp_f32_e32 v102, v102
	v_mul_f32_e32 v103, 0xbfb8aa3b, v98
	v_exp_f32_e32 v103, v103
	s_mov_b64 s[8:9], 0
	v_add_f32_e32 v102, 1.0, v102
	v_add_f32_e32 v104, 1.0, v103
	v_rcp_f32_e32 v103, v102
	v_mul_f32_e32 v102, 0xbfb8aa3b, v101
	v_exp_f32_e32 v105, v102
	v_mul_f32_e32 v102, 0xbfb8aa3b, v100
	v_exp_f32_e32 v107, v102
	v_rcp_f32_e32 v102, v104
	v_add_f32_e32 v104, 1.0, v105
	v_rcp_f32_e32 v109, v104
	v_add_f32_e32 v104, 1.0, v107
	v_rcp_f32_e32 v108, v104
	v_pk_mul_f32 v[104:105], v[98:99], v[102:103]
	v_pk_mul_f32 v[102:103], v[100:101], v[108:109]

.LBB0_898:
	v_add_u32_e32 v106, 0x210, v111
	v_lshl_add_u32 v99, v130, 1, v106
	v_cvt_pk_bf16_f32 v98, v105, v104
	ds_write_b16 v99, v98
	ds_write_b16_d16_hi v99, v98 offset:32
	v_cvt_pk_bf16_f32 v98, v103, v102
	ds_write_b16 v99, v98 offset:256
	v_or_b32_e32 v107, 32, v138
	ds_write_b16_d16_hi v99, v98 offset:288
	v_lshl_add_u32 v98, v107, 2, v220
	v_mov_b32_e32 v100, v228
	v_mov_b32_e32 v98, v86
	v_mov_b32_e32 v99, v82
	v_mov_b32_e32 v102, v94
	v_mov_b32_e32 v103, v90
	v_pk_mul_f32 v[98:99], v[98:99], v[100:101] op_sel_hi:[1,0]
	v_pk_mul_f32 v[100:101], v[102:103], v[100:101] op_sel_hi:[1,0]
	s_cmp_gt_i32 s5, 1
	s_mov_b64 s[8:9], -1
	s_cbranch_scc0 .LBB0_900
	v_mul_f32_e32 v82, 0xbfb8aa3b, v99
	v_exp_f32_e32 v82, v82
	v_mul_f32_e32 v86, 0xbfb8aa3b, v98
	v_mul_f32_e32 v90, 0xbfb8aa3b, v100
	v_exp_f32_e32 v86, v86
	v_add_f32_e32 v82, 1.0, v82
	v_rcp_f32_e32 v103, v82
	v_mul_f32_e32 v82, 0xbfb8aa3b, v101
	v_exp_f32_e32 v82, v82
	v_exp_f32_e32 v90, v90
	v_add_f32_e32 v86, 1.0, v86
	v_rcp_f32_e32 v102, v86
	v_add_f32_e32 v82, 1.0, v82
	v_rcp_f32_e32 v109, v82
	v_add_f32_e32 v82, 1.0, v90
	v_rcp_f32_e32 v108, v82
	v_pk_mul_f32 v[104:105], v[98:99], v[102:103]
	s_mov_b64 s[8:9], 0
	v_pk_mul_f32 v[102:103], v[100:101], v[108:109]

.LBB0_904:
	v_add_u32_e32 v98, 0x1ad0, v106
	v_lshl_add_u32 v86, v130, 1, v98
	v_cvt_pk_bf16_f32 v82, v105, v104
	ds_write_b16 v86, v82
	ds_write_b16_d16_hi v86, v82 offset:32
	v_cvt_pk_bf16_f32 v82, v103, v102
	ds_write_b16 v86, v82 offset:256
	v_or_b32_e32 v99, 33, v138
	ds_write_b16_d16_hi v86, v82 offset:288
	v_lshl_add_u32 v82, v99, 2, v220
	v_mov_b32_e32 v86, v229
	v_mov_b32_e32 v82, v87
	v_mov_b32_e32 v90, v95
	s_cmp_gt_i32 s5, 1
	s_mov_b64 s[8:9], -1
	v_pk_mul_f32 v[82:83], v[82:83], v[86:87] op_sel_hi:[1,0]
	v_pk_mul_f32 v[86:87], v[90:91], v[86:87] op_sel_hi:[1,0]
	s_cbranch_scc0 .LBB0_906
	v_mul_f32_e32 v90, 0xbfb8aa3b, v83
	v_exp_f32_e32 v90, v90
	v_mul_f32_e32 v91, 0xbfb8aa3b, v82
	v_exp_f32_e32 v91, v91
	s_mov_b64 s[8:9], 0
	v_add_f32_e32 v90, 1.0, v90
	v_add_f32_e32 v94, 1.0, v91
	v_rcp_f32_e32 v91, v90
	v_mul_f32_e32 v90, 0xbfb8aa3b, v87
	v_exp_f32_e32 v95, v90
	v_mul_f32_e32 v90, 0xbfb8aa3b, v86
	v_exp_f32_e32 v100, v90
	v_rcp_f32_e32 v90, v94
	v_add_f32_e32 v94, 1.0, v95
	v_rcp_f32_e32 v101, v94
	v_add_f32_e32 v94, 1.0, v100
	v_rcp_f32_e32 v100, v94
	v_pk_mul_f32 v[94:95], v[82:83], v[90:91]
	v_pk_mul_f32 v[90:91], v[86:87], v[100:101]

.LBB0_910:
	v_add_u32_e32 v98, 0x210, v98
	v_lshl_add_u32 v83, v130, 1, v98
	v_cvt_pk_bf16_f32 v82, v95, v94
	ds_write_b16 v83, v82
	ds_write_b16_d16_hi v83, v82 offset:32
	v_cvt_pk_bf16_f32 v82, v91, v90
	ds_write_b16 v83, v82 offset:256
	v_or_b32_e32 v99, 34, v138
	ds_write_b16_d16_hi v83, v82 offset:288
	v_lshl_add_u32 v82, v99, 2, v220
	v_mov_b32_e32 v86, v230
	v_mov_b32_e32 v82, v88
	v_mov_b32_e32 v83, v84
	v_mov_b32_e32 v90, v96
	v_mov_b32_e32 v91, v92
	v_pk_mul_f32 v[82:83], v[82:83], v[86:87] op_sel_hi:[1,0]
	v_pk_mul_f32 v[86:87], v[90:91], v[86:87] op_sel_hi:[1,0]
	s_cmp_gt_i32 s5, 1
	s_mov_b64 s[8:9], -1
	s_cbranch_scc0 .LBB0_912
	v_mul_f32_e32 v84, 0xbfb8aa3b, v83
	v_exp_f32_e32 v84, v84
	v_mul_f32_e32 v88, 0xbfb8aa3b, v82
	v_mul_f32_e32 v90, 0xbfb8aa3b, v86
	v_exp_f32_e32 v88, v88
	v_add_f32_e32 v84, 1.0, v84
	v_rcp_f32_e32 v91, v84
	v_mul_f32_e32 v84, 0xbfb8aa3b, v87
	v_exp_f32_e32 v84, v84
	v_exp_f32_e32 v92, v90
	v_add_f32_e32 v88, 1.0, v88
	v_rcp_f32_e32 v90, v88
	v_add_f32_e32 v84, 1.0, v84
	v_rcp_f32_e32 v101, v84
	v_add_f32_e32 v84, 1.0, v92
	v_rcp_f32_e32 v100, v84
	v_pk_mul_f32 v[94:95], v[82:83], v[90:91]
	s_mov_b64 s[8:9], 0
	v_pk_mul_f32 v[90:91], v[86:87], v[100:101]

.LBB0_916:
	v_cvt_pk_bf16_f32 v82, v95, s0
	v_add_u32_e32 v95, 0x210, v98
	v_lshl_add_u32 v83, v130, 1, v95
	ds_write_b16 v83, v82
	v_cvt_pk_bf16_f32 v82, v94, v91
	ds_write_b16 v83, v82 offset:32
	ds_write_b16_d16_hi v83, v82 offset:256
	v_cvt_pk_bf16_f32 v82, v90, s0
	v_or_b32_e32 v90, 35, v138
	ds_write_b16 v83, v82 offset:288
	v_lshl_add_u32 v82, v90, 2, v220
	v_mov_b32_e32 v86, v231
	v_mov_b32_e32 v84, v89
	v_mov_b32_e32 v92, v97
	s_cmp_gt_i32 s5, 1
	s_mov_b64 s[8:9], -1
	v_pk_mul_f32 v[82:83], v[84:85], v[86:87] op_sel_hi:[1,0]
	v_pk_mul_f32 v[84:85], v[92:93], v[86:87] op_sel_hi:[1,0]
	s_cbranch_scc0 .LBB0_918
	v_mul_f32_e32 v86, 0xbfb8aa3b, v83
	v_exp_f32_e32 v86, v86
	v_mul_f32_e32 v87, 0xbfb8aa3b, v82
	v_exp_f32_e32 v87, v87
	s_mov_b64 s[8:9], 0
	v_add_f32_e32 v86, 1.0, v86
	v_add_f32_e32 v88, 1.0, v87
	v_rcp_f32_e32 v87, v86
	v_mul_f32_e32 v86, 0xbfb8aa3b, v85
	v_exp_f32_e32 v89, v86
	v_mul_f32_e32 v86, 0xbfb8aa3b, v84
	v_exp_f32_e32 v91, v86
	v_rcp_f32_e32 v86, v88
	v_add_f32_e32 v88, 1.0, v89
	v_rcp_f32_e32 v93, v88
	v_add_f32_e32 v88, 1.0, v91
	v_rcp_f32_e32 v92, v88
	v_pk_mul_f32 v[88:89], v[82:83], v[86:87]
	v_pk_mul_f32 v[86:87], v[84:85], v[92:93]

.LBB0_922:
	v_add_u32_e32 v90, 0x210, v95
	v_lshl_add_u32 v83, v130, 1, v90
	v_cvt_pk_bf16_f32 v82, v89, v88
	ds_write_b16 v83, v82
	ds_write_b16_d16_hi v83, v82 offset:32
	v_cvt_pk_bf16_f32 v82, v87, v86
	ds_write_b16 v83, v82 offset:256
	v_or_b32_e32 v91, 48, v138
	ds_write_b16_d16_hi v83, v82 offset:288
	v_lshl_add_u32 v82, v91, 2, v220
	v_mov_b32_e32 v84, v232
	v_mov_b32_e32 v82, v70
	v_mov_b32_e32 v83, v66
	v_mov_b32_e32 v86, v78
	v_mov_b32_e32 v87, v74
	v_pk_mul_f32 v[82:83], v[82:83], v[84:85] op_sel_hi:[1,0]
	v_pk_mul_f32 v[84:85], v[86:87], v[84:85] op_sel_hi:[1,0]
	s_cmp_gt_i32 s5, 1
	s_mov_b64 s[8:9], -1
	s_cbranch_scc0 .LBB0_924
	v_mul_f32_e32 v66, 0xbfb8aa3b, v83
	v_exp_f32_e32 v66, v66
	v_mul_f32_e32 v70, 0xbfb8aa3b, v82
	v_mul_f32_e32 v74, 0xbfb8aa3b, v84
	v_exp_f32_e32 v70, v70
	v_add_f32_e32 v66, 1.0, v66
	v_rcp_f32_e32 v87, v66
	v_mul_f32_e32 v66, 0xbfb8aa3b, v85
	v_exp_f32_e32 v66, v66
	v_exp_f32_e32 v74, v74
	v_add_f32_e32 v70, 1.0, v70
	v_rcp_f32_e32 v86, v70
	v_add_f32_e32 v66, 1.0, v66
	v_rcp_f32_e32 v93, v66
	v_add_f32_e32 v66, 1.0, v74
	v_rcp_f32_e32 v92, v66
	v_pk_mul_f32 v[88:89], v[82:83], v[86:87]
	s_mov_b64 s[8:9], 0
	v_pk_mul_f32 v[86:87], v[84:85], v[92:93]

.LBB0_928:
	v_add_u32_e32 v82, 0x1ad0, v90
	v_lshl_add_u32 v70, v130, 1, v82
	v_cvt_pk_bf16_f32 v66, v89, v88
	ds_write_b16 v70, v66
	ds_write_b16_d16_hi v70, v66 offset:32
	v_cvt_pk_bf16_f32 v66, v87, v86
	ds_write_b16 v70, v66 offset:256
	v_or_b32_e32 v83, 49, v138
	ds_write_b16_d16_hi v70, v66 offset:288
	v_lshl_add_u32 v66, v83, 2, v220
	v_mov_b32_e32 v70, v233
	v_mov_b32_e32 v66, v71
	v_mov_b32_e32 v74, v79
	s_cmp_gt_i32 s5, 1
	s_mov_b64 s[8:9], -1
	v_pk_mul_f32 v[66:67], v[66:67], v[70:71] op_sel_hi:[1,0]
	v_pk_mul_f32 v[70:71], v[74:75], v[70:71] op_sel_hi:[1,0]
	s_cbranch_scc0 .LBB0_930
	v_mul_f32_e32 v74, 0xbfb8aa3b, v67
	v_exp_f32_e32 v74, v74
	v_mul_f32_e32 v75, 0xbfb8aa3b, v66
	v_exp_f32_e32 v75, v75
	s_mov_b64 s[8:9], 0
	v_add_f32_e32 v74, 1.0, v74
	v_add_f32_e32 v78, 1.0, v75
	v_rcp_f32_e32 v75, v74
	v_mul_f32_e32 v74, 0xbfb8aa3b, v71
	v_exp_f32_e32 v79, v74
	v_mul_f32_e32 v74, 0xbfb8aa3b, v70
	v_exp_f32_e32 v84, v74
	v_rcp_f32_e32 v74, v78
	v_add_f32_e32 v78, 1.0, v79
	v_rcp_f32_e32 v85, v78
	v_add_f32_e32 v78, 1.0, v84
	v_rcp_f32_e32 v84, v78
	v_pk_mul_f32 v[78:79], v[66:67], v[74:75]
	v_pk_mul_f32 v[74:75], v[70:71], v[84:85]

.LBB0_934:
	v_add_u32_e32 v82, 0x210, v82
	v_lshl_add_u32 v67, v130, 1, v82
	v_cvt_pk_bf16_f32 v66, v79, v78
	ds_write_b16 v67, v66
	ds_write_b16_d16_hi v67, v66 offset:32
	v_cvt_pk_bf16_f32 v66, v75, v74
	ds_write_b16 v67, v66 offset:256
	v_or_b32_e32 v83, 50, v138
	ds_write_b16_d16_hi v67, v66 offset:288
	v_lshl_add_u32 v66, v83, 2, v220
	v_mov_b32_e32 v70, v234
	v_mov_b32_e32 v66, v72
	v_mov_b32_e32 v67, v68
	v_mov_b32_e32 v74, v80
	v_mov_b32_e32 v75, v76
	v_pk_mul_f32 v[66:67], v[66:67], v[70:71] op_sel_hi:[1,0]
	v_pk_mul_f32 v[70:71], v[74:75], v[70:71] op_sel_hi:[1,0]
	s_cmp_gt_i32 s5, 1
	s_mov_b64 s[8:9], -1
	s_cbranch_scc0 .LBB0_936
	v_mul_f32_e32 v68, 0xbfb8aa3b, v67
	v_exp_f32_e32 v68, v68
	v_mul_f32_e32 v72, 0xbfb8aa3b, v66
	v_mul_f32_e32 v74, 0xbfb8aa3b, v70
	v_exp_f32_e32 v72, v72
	v_add_f32_e32 v68, 1.0, v68
	v_rcp_f32_e32 v75, v68
	v_mul_f32_e32 v68, 0xbfb8aa3b, v71
	v_exp_f32_e32 v68, v68
	v_exp_f32_e32 v76, v74
	v_add_f32_e32 v72, 1.0, v72
	v_rcp_f32_e32 v74, v72
	v_add_f32_e32 v68, 1.0, v68
	v_rcp_f32_e32 v85, v68
	v_add_f32_e32 v68, 1.0, v76
	v_rcp_f32_e32 v84, v68
	v_pk_mul_f32 v[78:79], v[66:67], v[74:75]
	s_mov_b64 s[8:9], 0
	v_pk_mul_f32 v[74:75], v[70:71], v[84:85]

.LBB0_940:
	v_cvt_pk_bf16_f32 v66, v79, s0
	v_add_u32_e32 v79, 0x210, v82
	v_lshl_add_u32 v67, v130, 1, v79
	ds_write_b16 v67, v66
	v_cvt_pk_bf16_f32 v66, v78, v75
	ds_write_b16 v67, v66 offset:32
	ds_write_b16_d16_hi v67, v66 offset:256
	v_cvt_pk_bf16_f32 v66, v74, s0
	v_or_b32_e32 v74, 51, v138
	ds_write_b16 v67, v66 offset:288
	v_lshl_add_u32 v66, v74, 2, v220
	v_mov_b32_e32 v70, v235
	v_mov_b32_e32 v68, v73
	v_mov_b32_e32 v76, v81
	s_cmp_gt_i32 s5, 1
	s_mov_b64 s[8:9], -1
	v_pk_mul_f32 v[66:67], v[68:69], v[70:71] op_sel_hi:[1,0]
	v_pk_mul_f32 v[68:69], v[76:77], v[70:71] op_sel_hi:[1,0]
	s_cbranch_scc0 .LBB0_942
	v_mul_f32_e32 v70, 0xbfb8aa3b, v67
	v_exp_f32_e32 v70, v70
	v_mul_f32_e32 v71, 0xbfb8aa3b, v66
	v_exp_f32_e32 v71, v71
	s_mov_b64 s[8:9], 0
	v_add_f32_e32 v70, 1.0, v70
	v_add_f32_e32 v72, 1.0, v71
	v_rcp_f32_e32 v71, v70
	v_mul_f32_e32 v70, 0xbfb8aa3b, v69
	v_exp_f32_e32 v73, v70
	v_mul_f32_e32 v70, 0xbfb8aa3b, v68
	v_exp_f32_e32 v75, v70
	v_rcp_f32_e32 v70, v72
	v_add_f32_e32 v72, 1.0, v73
	v_rcp_f32_e32 v77, v72
	v_add_f32_e32 v72, 1.0, v75
	v_rcp_f32_e32 v76, v72
	v_pk_mul_f32 v[72:73], v[66:67], v[70:71]
	v_pk_mul_f32 v[70:71], v[68:69], v[76:77]

.LBB0_946:
	v_add_u32_e32 v74, 0x210, v79
	v_lshl_add_u32 v67, v130, 1, v74
	v_mov_b32_e32 v68, v236
	v_cvt_pk_bf16_f32 v66, v73, v72
	ds_write_b16 v67, v66
	ds_write_b16_d16_hi v67, v66 offset:32
	v_cvt_pk_bf16_f32 v66, v71, v70
	ds_write_b16 v67, v66 offset:256
	ds_write_b16_d16_hi v67, v66 offset:288
	v_mov_b32_e32 v66, v54
	v_mov_b32_e32 v67, v50
	v_mov_b32_e32 v70, v62
	v_mov_b32_e32 v71, v58
	v_pk_mul_f32 v[66:67], v[66:67], v[68:69] op_sel_hi:[1,0]
	v_pk_mul_f32 v[68:69], v[70:71], v[68:69] op_sel_hi:[1,0]
	s_cmp_gt_i32 s5, 1
	s_mov_b64 s[8:9], -1
	s_cbranch_scc0 .LBB0_948
	v_mul_f32_e32 v50, 0xbfb8aa3b, v67
	v_exp_f32_e32 v50, v50
	v_mul_f32_e32 v54, 0xbfb8aa3b, v66
	v_mul_f32_e32 v58, 0xbfb8aa3b, v68
	v_exp_f32_e32 v54, v54
	v_add_f32_e32 v50, 1.0, v50
	v_rcp_f32_e32 v71, v50
	v_mul_f32_e32 v50, 0xbfb8aa3b, v69
	v_exp_f32_e32 v50, v50
	v_exp_f32_e32 v58, v58
	v_add_f32_e32 v54, 1.0, v54
	v_rcp_f32_e32 v70, v54
	v_add_f32_e32 v50, 1.0, v50
	v_rcp_f32_e32 v77, v50
	v_add_f32_e32 v50, 1.0, v58
	v_rcp_f32_e32 v76, v50
	v_pk_mul_f32 v[72:73], v[66:67], v[70:71]
	s_mov_b64 s[8:9], 0
	v_pk_mul_f32 v[70:71], v[68:69], v[76:77]

.LBB0_952:
	v_add_u32_e32 v66, 0x9ed0, v74
	v_lshl_add_u32 v54, v130, 1, v66
	v_cvt_pk_bf16_f32 v50, v73, v72
	ds_write_b16 v54, v50
	ds_write_b16_d16_hi v54, v50 offset:32
	v_cvt_pk_bf16_f32 v50, v71, v70
	ds_write_b16 v54, v50 offset:256
	ds_write_b16_d16_hi v54, v50 offset:288
	v_mov_b32_e32 v54, v237
	v_mov_b32_e32 v50, v55
	v_mov_b32_e32 v58, v63
	s_cmp_gt_i32 s5, 1
	s_mov_b64 s[8:9], -1
	v_pk_mul_f32 v[50:51], v[50:51], v[54:55] op_sel_hi:[1,0]
	v_pk_mul_f32 v[54:55], v[58:59], v[54:55] op_sel_hi:[1,0]
	s_cbranch_scc0 .LBB0_954
	v_mul_f32_e32 v58, 0xbfb8aa3b, v51
	v_exp_f32_e32 v58, v58
	v_mul_f32_e32 v59, 0xbfb8aa3b, v50
	v_exp_f32_e32 v59, v59
	s_mov_b64 s[8:9], 0
	v_add_f32_e32 v58, 1.0, v58
	v_add_f32_e32 v62, 1.0, v59
	v_rcp_f32_e32 v59, v58
	v_mul_f32_e32 v58, 0xbfb8aa3b, v55
	v_exp_f32_e32 v63, v58
	v_mul_f32_e32 v58, 0xbfb8aa3b, v54
	v_exp_f32_e32 v67, v58
	v_rcp_f32_e32 v58, v62
	v_add_f32_e32 v62, 1.0, v63
	v_rcp_f32_e32 v69, v62
	v_add_f32_e32 v62, 1.0, v67
	v_rcp_f32_e32 v68, v62
	v_pk_mul_f32 v[62:63], v[50:51], v[58:59]
	v_pk_mul_f32 v[58:59], v[54:55], v[68:69]

.LBB0_958:
	v_add_u32_e32 v66, 0x210, v66
	v_lshl_add_u32 v51, v130, 1, v66
	v_mov_b32_e32 v54, v238
	v_cvt_pk_bf16_f32 v50, v63, v62
	ds_write_b16 v51, v50
	ds_write_b16_d16_hi v51, v50 offset:32
	v_cvt_pk_bf16_f32 v50, v59, v58
	ds_write_b16 v51, v50 offset:256
	ds_write_b16_d16_hi v51, v50 offset:288
	v_mov_b32_e32 v50, v56
	v_mov_b32_e32 v51, v52
	v_mov_b32_e32 v58, v64
	v_mov_b32_e32 v59, v60
	v_pk_mul_f32 v[50:51], v[50:51], v[54:55] op_sel_hi:[1,0]
	v_pk_mul_f32 v[54:55], v[58:59], v[54:55] op_sel_hi:[1,0]
	s_cmp_gt_i32 s5, 1
	s_mov_b64 s[8:9], -1
	s_cbranch_scc0 .LBB0_960
	v_mul_f32_e32 v52, 0xbfb8aa3b, v51
	v_exp_f32_e32 v52, v52
	v_mul_f32_e32 v56, 0xbfb8aa3b, v50
	v_mul_f32_e32 v58, 0xbfb8aa3b, v54
	v_exp_f32_e32 v56, v56
	v_add_f32_e32 v52, 1.0, v52
	v_rcp_f32_e32 v59, v52
	v_mul_f32_e32 v52, 0xbfb8aa3b, v55
	v_exp_f32_e32 v52, v52
	v_exp_f32_e32 v60, v58
	v_add_f32_e32 v56, 1.0, v56
	v_rcp_f32_e32 v58, v56
	v_add_f32_e32 v52, 1.0, v52
	v_rcp_f32_e32 v69, v52
	v_add_f32_e32 v52, 1.0, v60
	v_rcp_f32_e32 v68, v52
	v_pk_mul_f32 v[62:63], v[50:51], v[58:59]
	s_mov_b64 s[8:9], 0
	v_pk_mul_f32 v[58:59], v[54:55], v[68:69]

.LBB0_964:
	v_cvt_pk_bf16_f32 v50, v63, s0
	v_add_u32_e32 v63, 0x210, v66
	v_mov_b32_e32 v54, v239
	v_lshl_add_u32 v51, v130, 1, v63
	ds_write_b16 v51, v50
	v_cvt_pk_bf16_f32 v50, v62, v59
	ds_write_b16 v51, v50 offset:32
	ds_write_b16_d16_hi v51, v50 offset:256
	v_cvt_pk_bf16_f32 v50, v58, s0
	v_mov_b32_e32 v52, v57
	v_mov_b32_e32 v60, v65
	ds_write_b16 v51, v50 offset:288
	s_cmp_gt_i32 s5, 1
	v_pk_mul_f32 v[50:51], v[52:53], v[54:55] op_sel_hi:[1,0]
	v_pk_mul_f32 v[52:53], v[60:61], v[54:55] op_sel_hi:[1,0]
	s_mov_b64 s[8:9], -1
	s_cbranch_scc0 .LBB0_966
	v_mul_f32_e32 v54, 0xbfb8aa3b, v51
	v_exp_f32_e32 v54, v54
	v_mul_f32_e32 v55, 0xbfb8aa3b, v50
	v_exp_f32_e32 v55, v55
	s_mov_b64 s[8:9], 0
	v_add_f32_e32 v54, 1.0, v54
	v_add_f32_e32 v56, 1.0, v55
	v_rcp_f32_e32 v55, v54
	v_mul_f32_e32 v54, 0xbfb8aa3b, v53
	v_exp_f32_e32 v57, v54
	v_mul_f32_e32 v54, 0xbfb8aa3b, v52
	v_exp_f32_e32 v58, v54
	v_rcp_f32_e32 v54, v56
	v_add_f32_e32 v56, 1.0, v57
	v_rcp_f32_e32 v59, v56
	v_add_f32_e32 v56, 1.0, v58
	v_rcp_f32_e32 v58, v56
	v_pk_mul_f32 v[56:57], v[50:51], v[54:55]
	v_pk_mul_f32 v[54:55], v[52:53], v[58:59]

.LBB0_970:
	v_add_u32_e32 v58, 0x210, v63
	v_lshl_add_u32 v51, v130, 1, v58
	v_mov_b32_e32 v52, v240
	v_cvt_pk_bf16_f32 v50, v57, v56
	ds_write_b16 v51, v50
	ds_write_b16_d16_hi v51, v50 offset:32
	v_cvt_pk_bf16_f32 v50, v55, v54
	ds_write_b16 v51, v50 offset:256
	ds_write_b16_d16_hi v51, v50 offset:288
	v_mov_b32_e32 v50, v38
	v_mov_b32_e32 v51, v34
	v_mov_b32_e32 v54, v46
	v_mov_b32_e32 v55, v42
	v_pk_mul_f32 v[50:51], v[50:51], v[52:53] op_sel_hi:[1,0]
	v_pk_mul_f32 v[52:53], v[54:55], v[52:53] op_sel_hi:[1,0]
	s_cmp_gt_i32 s5, 1
	s_mov_b64 s[8:9], -1
	s_cbranch_scc0 .LBB0_972
	v_mul_f32_e32 v34, 0xbfb8aa3b, v51
	v_exp_f32_e32 v34, v34
	v_mul_f32_e32 v38, 0xbfb8aa3b, v50
	v_mul_f32_e32 v42, 0xbfb8aa3b, v52
	v_exp_f32_e32 v38, v38
	v_add_f32_e32 v34, 1.0, v34
	v_rcp_f32_e32 v55, v34
	v_mul_f32_e32 v34, 0xbfb8aa3b, v53
	v_exp_f32_e32 v34, v34
	v_exp_f32_e32 v42, v42
	v_add_f32_e32 v38, 1.0, v38
	v_rcp_f32_e32 v54, v38
	v_add_f32_e32 v34, 1.0, v34
	v_rcp_f32_e32 v61, v34
	v_add_f32_e32 v34, 1.0, v42
	v_rcp_f32_e32 v60, v34
	v_pk_mul_f32 v[56:57], v[50:51], v[54:55]
	s_mov_b64 s[8:9], 0
	v_pk_mul_f32 v[54:55], v[52:53], v[60:61]

.LBB0_976:
	v_add_u32_e32 v50, 0x1ad0, v58
	v_lshl_add_u32 v38, v130, 1, v50
	v_cvt_pk_bf16_f32 v34, v57, v56
	ds_write_b16 v38, v34
	ds_write_b16_d16_hi v38, v34 offset:32
	v_cvt_pk_bf16_f32 v34, v55, v54
	ds_write_b16 v38, v34 offset:256
	ds_write_b16_d16_hi v38, v34 offset:288
	v_mov_b32_e32 v38, v241
	v_mov_b32_e32 v34, v39
	v_mov_b32_e32 v42, v47
	s_cmp_gt_i32 s5, 1
	s_mov_b64 s[8:9], -1
	v_pk_mul_f32 v[34:35], v[34:35], v[38:39] op_sel_hi:[1,0]
	v_pk_mul_f32 v[38:39], v[42:43], v[38:39] op_sel_hi:[1,0]
	s_cbranch_scc0 .LBB0_978
	v_mul_f32_e32 v42, 0xbfb8aa3b, v35
	v_exp_f32_e32 v42, v42
	v_mul_f32_e32 v43, 0xbfb8aa3b, v34
	v_exp_f32_e32 v43, v43
	s_mov_b64 s[8:9], 0
	v_add_f32_e32 v42, 1.0, v42
	v_add_f32_e32 v46, 1.0, v43
	v_rcp_f32_e32 v43, v42
	v_mul_f32_e32 v42, 0xbfb8aa3b, v39
	v_exp_f32_e32 v47, v42
	v_mul_f32_e32 v42, 0xbfb8aa3b, v38
	v_exp_f32_e32 v51, v42
	v_rcp_f32_e32 v42, v46
	v_add_f32_e32 v46, 1.0, v47
	v_rcp_f32_e32 v53, v46
	v_add_f32_e32 v46, 1.0, v51
	v_rcp_f32_e32 v52, v46
	v_pk_mul_f32 v[46:47], v[34:35], v[42:43]
	v_pk_mul_f32 v[42:43], v[38:39], v[52:53]

.LBB0_982:
	v_add_u32_e32 v50, 0x210, v50
	v_lshl_add_u32 v35, v130, 1, v50
	v_mov_b32_e32 v38, v242
	v_cvt_pk_bf16_f32 v34, v47, v46
	ds_write_b16 v35, v34
	ds_write_b16_d16_hi v35, v34 offset:32
	v_cvt_pk_bf16_f32 v34, v43, v42
	ds_write_b16 v35, v34 offset:256
	ds_write_b16_d16_hi v35, v34 offset:288
	v_mov_b32_e32 v34, v40
	v_mov_b32_e32 v35, v36
	v_mov_b32_e32 v42, v48
	v_mov_b32_e32 v43, v44
	v_pk_mul_f32 v[34:35], v[34:35], v[38:39] op_sel_hi:[1,0]
	v_pk_mul_f32 v[38:39], v[42:43], v[38:39] op_sel_hi:[1,0]
	s_cmp_gt_i32 s5, 1
	s_mov_b64 s[8:9], -1
	s_cbranch_scc0 .LBB0_984
	v_mul_f32_e32 v36, 0xbfb8aa3b, v35
	v_exp_f32_e32 v36, v36
	v_mul_f32_e32 v40, 0xbfb8aa3b, v34
	v_mul_f32_e32 v42, 0xbfb8aa3b, v38
	v_exp_f32_e32 v40, v40
	v_add_f32_e32 v36, 1.0, v36
	v_rcp_f32_e32 v43, v36
	v_mul_f32_e32 v36, 0xbfb8aa3b, v39
	v_exp_f32_e32 v36, v36
	v_exp_f32_e32 v44, v42
	v_add_f32_e32 v40, 1.0, v40
	v_rcp_f32_e32 v42, v40
	v_add_f32_e32 v36, 1.0, v36
	v_rcp_f32_e32 v53, v36
	v_add_f32_e32 v36, 1.0, v44
	v_rcp_f32_e32 v52, v36
	v_pk_mul_f32 v[46:47], v[34:35], v[42:43]
	s_mov_b64 s[8:9], 0
	v_pk_mul_f32 v[42:43], v[38:39], v[52:53]

.LBB0_988:
	v_cvt_pk_bf16_f32 v34, v47, s0
	v_add_u32_e32 v47, 0x210, v50
	v_mov_b32_e32 v38, v243
	v_lshl_add_u32 v35, v130, 1, v47
	ds_write_b16 v35, v34
	v_cvt_pk_bf16_f32 v34, v46, v43
	ds_write_b16 v35, v34 offset:32
	ds_write_b16_d16_hi v35, v34 offset:256
	v_cvt_pk_bf16_f32 v34, v42, s0
	v_mov_b32_e32 v36, v41
	v_mov_b32_e32 v44, v49
	ds_write_b16 v35, v34 offset:288
	s_cmp_gt_i32 s5, 1
	v_pk_mul_f32 v[34:35], v[36:37], v[38:39] op_sel_hi:[1,0]
	v_pk_mul_f32 v[36:37], v[44:45], v[38:39] op_sel_hi:[1,0]
	s_mov_b64 s[8:9], -1
	s_cbranch_scc0 .LBB0_990
	v_mul_f32_e32 v38, 0xbfb8aa3b, v35
	v_exp_f32_e32 v38, v38
	v_mul_f32_e32 v39, 0xbfb8aa3b, v34
	v_exp_f32_e32 v39, v39
	s_mov_b64 s[8:9], 0
	v_add_f32_e32 v38, 1.0, v38
	v_add_f32_e32 v40, 1.0, v39
	v_rcp_f32_e32 v39, v38
	v_mul_f32_e32 v38, 0xbfb8aa3b, v37
	v_exp_f32_e32 v41, v38
	v_mul_f32_e32 v38, 0xbfb8aa3b, v36
	v_exp_f32_e32 v42, v38
	v_rcp_f32_e32 v38, v40
	v_add_f32_e32 v40, 1.0, v41
	v_rcp_f32_e32 v43, v40
	v_add_f32_e32 v40, 1.0, v42
	v_rcp_f32_e32 v42, v40
	v_pk_mul_f32 v[40:41], v[34:35], v[38:39]
	v_pk_mul_f32 v[38:39], v[36:37], v[42:43]

.LBB0_994:
	v_add_u32_e32 v42, 0x210, v47
	v_lshl_add_u32 v35, v130, 1, v42
	v_mov_b32_e32 v36, v244
	v_cvt_pk_bf16_f32 v34, v41, v40
	ds_write_b16 v35, v34
	ds_write_b16_d16_hi v35, v34 offset:32
	v_cvt_pk_bf16_f32 v34, v39, v38
	ds_write_b16 v35, v34 offset:256
	ds_write_b16_d16_hi v35, v34 offset:288
	v_mov_b32_e32 v34, v22
	v_mov_b32_e32 v35, v18
	v_mov_b32_e32 v38, v30
	v_mov_b32_e32 v39, v26
	v_pk_mul_f32 v[34:35], v[34:35], v[36:37] op_sel_hi:[1,0]
	v_pk_mul_f32 v[36:37], v[38:39], v[36:37] op_sel_hi:[1,0]
	s_cmp_gt_i32 s5, 1
	s_mov_b64 s[8:9], -1
	s_cbranch_scc0 .LBB0_996
	v_mul_f32_e32 v18, 0xbfb8aa3b, v35
	v_exp_f32_e32 v18, v18
	v_mul_f32_e32 v22, 0xbfb8aa3b, v34
	v_mul_f32_e32 v26, 0xbfb8aa3b, v36
	v_exp_f32_e32 v22, v22
	v_add_f32_e32 v18, 1.0, v18
	v_rcp_f32_e32 v39, v18
	v_mul_f32_e32 v18, 0xbfb8aa3b, v37
	v_exp_f32_e32 v18, v18
	v_exp_f32_e32 v26, v26
	v_add_f32_e32 v22, 1.0, v22
	v_rcp_f32_e32 v38, v22
	v_add_f32_e32 v18, 1.0, v18
	v_rcp_f32_e32 v45, v18
	v_add_f32_e32 v18, 1.0, v26
	v_rcp_f32_e32 v44, v18
	v_pk_mul_f32 v[40:41], v[34:35], v[38:39]
	s_mov_b64 s[8:9], 0
	v_pk_mul_f32 v[38:39], v[36:37], v[44:45]

.LBB0_1000:
	v_add_u32_e32 v34, 0x1ad0, v42
	v_lshl_add_u32 v22, v130, 1, v34
	v_cvt_pk_bf16_f32 v18, v41, v40
	ds_write_b16 v22, v18
	ds_write_b16_d16_hi v22, v18 offset:32
	v_cvt_pk_bf16_f32 v18, v39, v38
	ds_write_b16 v22, v18 offset:256
	ds_write_b16_d16_hi v22, v18 offset:288
	v_mov_b32_e32 v22, v245
	v_mov_b32_e32 v18, v23
	v_mov_b32_e32 v26, v31
	s_cmp_gt_i32 s5, 1
	s_mov_b64 s[8:9], -1
	v_pk_mul_f32 v[18:19], v[18:19], v[22:23] op_sel_hi:[1,0]
	v_pk_mul_f32 v[22:23], v[26:27], v[22:23] op_sel_hi:[1,0]
	s_cbranch_scc0 .LBB0_1002
	v_mul_f32_e32 v26, 0xbfb8aa3b, v19
	v_exp_f32_e32 v26, v26
	v_mul_f32_e32 v27, 0xbfb8aa3b, v18
	v_exp_f32_e32 v27, v27
	s_mov_b64 s[8:9], 0
	v_add_f32_e32 v26, 1.0, v26
	v_add_f32_e32 v30, 1.0, v27
	v_rcp_f32_e32 v27, v26
	v_mul_f32_e32 v26, 0xbfb8aa3b, v23
	v_exp_f32_e32 v31, v26
	v_mul_f32_e32 v26, 0xbfb8aa3b, v22
	v_exp_f32_e32 v35, v26
	v_rcp_f32_e32 v26, v30
	v_add_f32_e32 v30, 1.0, v31
	v_rcp_f32_e32 v37, v30
	v_add_f32_e32 v30, 1.0, v35
	v_rcp_f32_e32 v36, v30
	v_pk_mul_f32 v[30:31], v[18:19], v[26:27]
	v_pk_mul_f32 v[26:27], v[22:23], v[36:37]

.LBB0_1006:
	v_add_u32_e32 v34, 0x210, v34
	v_lshl_add_u32 v19, v130, 1, v34
	v_mov_b32_e32 v22, v246
	v_cvt_pk_bf16_f32 v18, v31, v30
	ds_write_b16 v19, v18
	ds_write_b16_d16_hi v19, v18 offset:32
	v_cvt_pk_bf16_f32 v18, v27, v26
	ds_write_b16 v19, v18 offset:256
	ds_write_b16_d16_hi v19, v18 offset:288
	v_mov_b32_e32 v18, v24
	v_mov_b32_e32 v19, v20
	v_mov_b32_e32 v26, v32
	v_mov_b32_e32 v27, v28
	v_pk_mul_f32 v[18:19], v[18:19], v[22:23] op_sel_hi:[1,0]
	v_pk_mul_f32 v[22:23], v[26:27], v[22:23] op_sel_hi:[1,0]
	s_cmp_gt_i32 s5, 1
	s_mov_b64 s[8:9], -1
	s_cbranch_scc0 .LBB0_1008
	v_mul_f32_e32 v20, 0xbfb8aa3b, v19
	v_exp_f32_e32 v20, v20
	v_mul_f32_e32 v24, 0xbfb8aa3b, v18
	v_mul_f32_e32 v26, 0xbfb8aa3b, v22
	v_exp_f32_e32 v24, v24
	v_add_f32_e32 v20, 1.0, v20
	v_rcp_f32_e32 v27, v20
	v_mul_f32_e32 v20, 0xbfb8aa3b, v23
	v_exp_f32_e32 v20, v20
	v_exp_f32_e32 v28, v26
	v_add_f32_e32 v24, 1.0, v24
	v_rcp_f32_e32 v26, v24
	v_add_f32_e32 v20, 1.0, v20
	v_rcp_f32_e32 v37, v20
	v_add_f32_e32 v20, 1.0, v28
	v_rcp_f32_e32 v36, v20
	v_pk_mul_f32 v[30:31], v[18:19], v[26:27]
	s_mov_b64 s[8:9], 0
	v_pk_mul_f32 v[26:27], v[22:23], v[36:37]

.LBB0_1012:
	v_cvt_pk_bf16_f32 v18, v31, s0
	v_add_u32_e32 v31, 0x210, v34
	v_mov_b32_e32 v22, v247
	v_lshl_add_u32 v19, v130, 1, v31
	ds_write_b16 v19, v18
	v_cvt_pk_bf16_f32 v18, v30, v27
	ds_write_b16 v19, v18 offset:32
	ds_write_b16_d16_hi v19, v18 offset:256
	v_cvt_pk_bf16_f32 v18, v26, s0
	v_mov_b32_e32 v20, v25
	v_mov_b32_e32 v28, v33
	ds_write_b16 v19, v18 offset:288
	s_cmp_gt_i32 s5, 1
	v_pk_mul_f32 v[18:19], v[20:21], v[22:23] op_sel_hi:[1,0]
	v_pk_mul_f32 v[20:21], v[28:29], v[22:23] op_sel_hi:[1,0]
	s_mov_b64 s[8:9], -1
	s_cbranch_scc0 .LBB0_1014
	v_mul_f32_e32 v22, 0xbfb8aa3b, v19
	v_exp_f32_e32 v22, v22
	v_mul_f32_e32 v23, 0xbfb8aa3b, v18
	v_exp_f32_e32 v23, v23
	s_mov_b64 s[8:9], 0
	v_add_f32_e32 v22, 1.0, v22
	v_add_f32_e32 v24, 1.0, v23
	v_rcp_f32_e32 v23, v22
	v_mul_f32_e32 v22, 0xbfb8aa3b, v21
	v_exp_f32_e32 v25, v22
	v_mul_f32_e32 v22, 0xbfb8aa3b, v20
	v_exp_f32_e32 v26, v22
	v_rcp_f32_e32 v22, v24
	v_add_f32_e32 v24, 1.0, v25
	v_rcp_f32_e32 v27, v24
	v_add_f32_e32 v24, 1.0, v26
	v_rcp_f32_e32 v26, v24
	v_pk_mul_f32 v[24:25], v[18:19], v[22:23]
	v_pk_mul_f32 v[22:23], v[20:21], v[26:27]

.LBB0_1018:
	v_add_u32_e32 v26, 0x210, v31
	v_lshl_add_u32 v19, v130, 1, v26
	v_mov_b32_e32 v20, v248
	v_cvt_pk_bf16_f32 v18, v25, v24
	ds_write_b16 v19, v18
	ds_write_b16_d16_hi v19, v18 offset:32
	v_cvt_pk_bf16_f32 v18, v23, v22
	ds_write_b16 v19, v18 offset:256
	ds_write_b16_d16_hi v19, v18 offset:288
	v_mov_b32_e32 v18, v6
	v_mov_b32_e32 v19, v2
	v_mov_b32_e32 v22, v14
	v_mov_b32_e32 v23, v10
	v_pk_mul_f32 v[18:19], v[18:19], v[20:21] op_sel_hi:[1,0]
	v_pk_mul_f32 v[20:21], v[22:23], v[20:21] op_sel_hi:[1,0]
	s_cmp_gt_i32 s5, 1
	s_mov_b64 s[8:9], -1
	s_cbranch_scc0 .LBB0_1020
	v_mul_f32_e32 v2, 0xbfb8aa3b, v19
	v_exp_f32_e32 v2, v2
	v_mul_f32_e32 v6, 0xbfb8aa3b, v18
	v_mul_f32_e32 v10, 0xbfb8aa3b, v20
	v_exp_f32_e32 v6, v6
	v_add_f32_e32 v2, 1.0, v2
	v_rcp_f32_e32 v23, v2
	v_mul_f32_e32 v2, 0xbfb8aa3b, v21
	v_exp_f32_e32 v2, v2
	v_exp_f32_e32 v10, v10
	v_add_f32_e32 v6, 1.0, v6
	v_rcp_f32_e32 v22, v6
	v_add_f32_e32 v2, 1.0, v2
	v_rcp_f32_e32 v29, v2
	v_add_f32_e32 v2, 1.0, v10
	v_rcp_f32_e32 v28, v2
	v_pk_mul_f32 v[24:25], v[18:19], v[22:23]
	s_mov_b64 s[8:9], 0
	v_pk_mul_f32 v[22:23], v[20:21], v[28:29]

.LBB0_1024:
	v_add_u32_e32 v18, 0x1ad0, v26
	v_lshl_add_u32 v6, v130, 1, v18
	v_cvt_pk_bf16_f32 v2, v25, v24
	ds_write_b16 v6, v2
	ds_write_b16_d16_hi v6, v2 offset:32
	v_cvt_pk_bf16_f32 v2, v23, v22
	ds_write_b16 v6, v2 offset:256
	ds_write_b16_d16_hi v6, v2 offset:288
	v_mov_b32_e32 v6, v249
	v_mov_b32_e32 v2, v7
	v_mov_b32_e32 v10, v15
	s_cmp_gt_i32 s5, 1
	s_mov_b64 s[8:9], -1
	v_pk_mul_f32 v[2:3], v[2:3], v[6:7] op_sel_hi:[1,0]
	v_pk_mul_f32 v[6:7], v[10:11], v[6:7] op_sel_hi:[1,0]
	s_cbranch_scc0 .LBB0_1026
	v_mul_f32_e32 v10, 0xbfb8aa3b, v3
	v_exp_f32_e32 v10, v10
	v_mul_f32_e32 v11, 0xbfb8aa3b, v2
	v_exp_f32_e32 v11, v11
	s_mov_b64 s[8:9], 0
	v_add_f32_e32 v10, 1.0, v10
	v_add_f32_e32 v14, 1.0, v11
	v_rcp_f32_e32 v11, v10
	v_mul_f32_e32 v10, 0xbfb8aa3b, v7
	v_exp_f32_e32 v15, v10
	v_mul_f32_e32 v10, 0xbfb8aa3b, v6
	v_exp_f32_e32 v19, v10
	v_rcp_f32_e32 v10, v14
	v_add_f32_e32 v14, 1.0, v15
	v_rcp_f32_e32 v21, v14
	v_add_f32_e32 v14, 1.0, v19
	v_rcp_f32_e32 v20, v14
	v_pk_mul_f32 v[14:15], v[2:3], v[10:11]
	v_pk_mul_f32 v[10:11], v[6:7], v[20:21]

.LBB0_1030:
	v_add_u32_e32 v18, 0x210, v18
	v_lshl_add_u32 v3, v130, 1, v18
	v_mov_b32_e32 v6, v250
	v_cvt_pk_bf16_f32 v2, v15, v14
	ds_write_b16 v3, v2
	ds_write_b16_d16_hi v3, v2 offset:32
	v_cvt_pk_bf16_f32 v2, v11, v10
	ds_write_b16 v3, v2 offset:256
	ds_write_b16_d16_hi v3, v2 offset:288
	v_mov_b32_e32 v2, v8
	v_mov_b32_e32 v3, v4
	v_mov_b32_e32 v10, v16
	v_mov_b32_e32 v11, v12
	v_pk_mul_f32 v[2:3], v[2:3], v[6:7] op_sel_hi:[1,0]
	v_pk_mul_f32 v[6:7], v[10:11], v[6:7] op_sel_hi:[1,0]
	s_cmp_gt_i32 s5, 1
	s_mov_b64 s[8:9], -1
	s_cbranch_scc0 .LBB0_1032
	v_mul_f32_e32 v4, 0xbfb8aa3b, v3
	v_exp_f32_e32 v4, v4
	v_mul_f32_e32 v8, 0xbfb8aa3b, v2
	v_mul_f32_e32 v10, 0xbfb8aa3b, v6
	v_exp_f32_e32 v8, v8
	v_add_f32_e32 v4, 1.0, v4
	v_rcp_f32_e32 v11, v4
	v_mul_f32_e32 v4, 0xbfb8aa3b, v7
	v_exp_f32_e32 v4, v4
	v_exp_f32_e32 v12, v10
	v_add_f32_e32 v8, 1.0, v8
	v_rcp_f32_e32 v10, v8
	v_add_f32_e32 v4, 1.0, v4
	v_rcp_f32_e32 v21, v4
	v_add_f32_e32 v4, 1.0, v12
	v_rcp_f32_e32 v20, v4
	v_pk_mul_f32 v[14:15], v[2:3], v[10:11]
	s_mov_b64 s[8:9], 0
	v_pk_mul_f32 v[10:11], v[6:7], v[20:21]

.LBB0_1036:
	v_add_u32_e32 v3, 0x210, v18
	v_mov_b32_e32 v6, v251
	v_cvt_pk_bf16_f32 v2, v15, s0
	v_lshl_add_u32 v15, v130, 1, v3
	ds_write_b16 v15, v2
	v_cvt_pk_bf16_f32 v2, v14, v11
	ds_write_b16 v15, v2 offset:32
	ds_write_b16_d16_hi v15, v2 offset:256
	v_cvt_pk_bf16_f32 v2, v10, s0
	v_mov_b32_e32 v4, v9
	v_mov_b32_e32 v12, v17
	ds_write_b16 v15, v2 offset:288
	s_cmp_gt_i32 s5, 1
	v_pk_mul_f32 v[2:3], v[4:5], v[6:7] op_sel_hi:[1,0]
	v_pk_mul_f32 v[4:5], v[12:13], v[6:7] op_sel_hi:[1,0]
	s_mov_b64 s[8:9], -1
	s_cbranch_scc0 .LBB0_1038
	v_mul_f32_e32 v6, 0xbfb8aa3b, v3
	v_exp_f32_e32 v6, v6
	v_mul_f32_e32 v7, 0xbfb8aa3b, v2
	v_exp_f32_e32 v7, v7
	s_mov_b64 s[8:9], 0
	v_add_f32_e32 v6, 1.0, v6
	v_add_f32_e32 v8, 1.0, v7
	v_rcp_f32_e32 v7, v6
	v_mul_f32_e32 v6, 0xbfb8aa3b, v5
	v_exp_f32_e32 v9, v6
	v_mul_f32_e32 v6, 0xbfb8aa3b, v4
	v_exp_f32_e32 v10, v6
	v_rcp_f32_e32 v6, v8
	v_add_f32_e32 v8, 1.0, v9
	v_rcp_f32_e32 v11, v8
	v_add_f32_e32 v8, 1.0, v10
	v_rcp_f32_e32 v10, v8
	v_pk_mul_f32 v[8:9], v[2:3], v[6:7]
	v_pk_mul_f32 v[6:7], v[4:5], v[10:11]

.LBB0_1042:
	v_cvt_pk_bf16_f32 v1, v9, v8
	ds_write_b16 v15, v1 offset:528
	ds_write_b16_d16_hi v15, v1 offset:560
	v_cvt_pk_bf16_f32 v1, v7, v6
	ds_write_b16 v15, v1 offset:784
	ds_write_b16_d16_hi v15, v1 offset:816
	v_mov_b32_e32 v1, v210
	s_lshl_b64 s[6:7], s[6:7], 1
	s_waitcnt lgkmcnt(0)
	s_barrier
	s_add_u32 s6, s25, s6
	v_lshlrev_b32_e32 v2, 4, v1
	v_and_b32_e32 v2, 0x1f0, v2
	s_addc_u32 s7, s26, s7
	v_mov_b32_e32 v3, v0
	v_lshl_add_u64 v[4:5], s[6:7], 0, v[2:3]
	s_mov_b32 s5, 0

.LBB0_1189:
	v_mov_b32_e32 v1, v0
	s_barrier
	v_lshl_add_u32 v1, v1, 1, v176
	v_cvt_pk_bf16_f32 v2, v64, v65
	ds_write_b16 v1, v2
	ds_write_b16_d16_hi v1, v2 offset:528
	v_cvt_pk_bf16_f32 v2, v66, v67
	ds_write_b16 v1, v2 offset:1056
	ds_write_b16_d16_hi v1, v2 offset:1584
	v_cvt_pk_bf16_f32 v2, v68, v69
	ds_write_b16 v1, v2 offset:4224
	ds_write_b16_d16_hi v1, v2 offset:4752
	v_cvt_pk_bf16_f32 v2, v70, v71
	ds_write_b16 v1, v2 offset:5280
	ds_write_b16_d16_hi v1, v2 offset:5808
	v_cvt_pk_bf16_f32 v2, v72, v73
	ds_write_b16 v1, v2 offset:8448
	ds_write_b16_d16_hi v1, v2 offset:8976
	v_cvt_pk_bf16_f32 v2, v74, v75
	ds_write_b16 v1, v2 offset:9504
	ds_write_b16_d16_hi v1, v2 offset:10032
	v_cvt_pk_bf16_f32 v2, v76, v77
	ds_write_b16 v1, v2 offset:12672
	ds_write_b16_d16_hi v1, v2 offset:13200
	v_cvt_pk_bf16_f32 v2, v78, v79
	ds_write_b16 v1, v2 offset:13728
	ds_write_b16_d16_hi v1, v2 offset:14256
	v_cvt_pk_bf16_f32 v2, v48, v49
	ds_write_b16 v1, v2 offset:64
	ds_write_b16_d16_hi v1, v2 offset:592
	v_cvt_pk_bf16_f32 v2, v50, v51
	ds_write_b16 v1, v2 offset:1120
	ds_write_b16_d16_hi v1, v2 offset:1648
	v_cvt_pk_bf16_f32 v2, v52, v53
	ds_write_b16 v1, v2 offset:4288
	ds_write_b16_d16_hi v1, v2 offset:4816
	v_cvt_pk_bf16_f32 v2, v54, v55
	ds_write_b16 v1, v2 offset:5344
	ds_write_b16_d16_hi v1, v2 offset:5872
	s_xor_b64 s[18:19], s[16:17], -1
	v_cvt_pk_bf16_f32 v2, v56, v57
	ds_write_b16 v1, v2 offset:8512
	ds_write_b16_d16_hi v1, v2 offset:9040
	v_cvt_pk_bf16_f32 v2, v58, s0
	s_and_b64 s[0:1], s[16:17], exec
	s_cselect_b32 s72, 0, 0x780
	s_or_b64 s[20:21], s[72:73], s[10:11]
	v_lshl_add_u64 v[4:5], s[20:21], 0, v[168:169]
	ds_write_b16 v1, v2 offset:9568
	v_mad_u64_u32 v[2:3], s[0:1], v4, s68, v[170:171]
	v_mad_i32_i24 v3, v5, s68, v3
	global_load_dwordx4 v[152:155], v[2:3], off
	v_cvt_pk_bf16_f32 v4, v59, v60
	ds_write_b16 v1, v4 offset:10096
	ds_write_b16_d16_hi v1, v4 offset:12736
	v_cvt_pk_bf16_f32 v4, v61, v62
	ds_write_b16 v1, v4 offset:13264
	ds_write_b16_d16_hi v1, v4 offset:13792
	v_cvt_pk_bf16_f32 v4, v63, v32
	ds_write_b16 v1, v4 offset:14320
	ds_write_b16_d16_hi v1, v4 offset:16896
	v_cvt_pk_bf16_f32 v4, v33, v34
	ds_write_b16 v1, v4 offset:17424
	ds_write_b16_d16_hi v1, v4 offset:17952
	v_cvt_pk_bf16_f32 v4, v35, v36
	ds_write_b16 v1, v4 offset:18480
	ds_write_b16_d16_hi v1, v4 offset:21120
	v_cvt_pk_bf16_f32 v4, v37, v38
	ds_write_b16 v1, v4 offset:21648
	ds_write_b16_d16_hi v1, v4 offset:22176
	v_cvt_pk_bf16_f32 v4, v39, v40
	ds_write_b16 v1, v4 offset:22704
	ds_write_b16_d16_hi v1, v4 offset:25344
	v_cvt_pk_bf16_f32 v4, v41, v42
	ds_write_b16 v1, v4 offset:25872
	ds_write_b16_d16_hi v1, v4 offset:26400
	v_cvt_pk_bf16_f32 v4, v43, v44
	ds_write_b16 v1, v4 offset:26928
	ds_write_b16_d16_hi v1, v4 offset:29568
	v_cvt_pk_bf16_f32 v4, v45, v46
	ds_write_b16 v1, v4 offset:30096
	ds_write_b16_d16_hi v1, v4 offset:30624
	v_cvt_pk_bf16_f32 v4, v47, v16
	ds_write_b16 v1, v4 offset:31152
	ds_write_b16_d16_hi v1, v4 offset:16960
	v_cvt_pk_bf16_f32 v4, v17, v18
	ds_write_b16 v1, v4 offset:17488
	ds_write_b16_d16_hi v1, v4 offset:18016
	v_cvt_pk_bf16_f32 v4, v19, v20
	ds_write_b16 v1, v4 offset:18544
	ds_write_b16_d16_hi v1, v4 offset:21184
	v_cvt_pk_bf16_f32 v4, v21, v22
	ds_write_b16 v1, v4 offset:21712
	ds_write_b16_d16_hi v1, v4 offset:22240
	v_cvt_pk_bf16_f32 v4, v23, v24
	ds_write_b16 v1, v4 offset:22768
	ds_write_b16_d16_hi v1, v4 offset:25408
	v_cvt_pk_bf16_f32 v4, v25, v26
	ds_write_b16 v1, v4 offset:25936
	ds_write_b16_d16_hi v1, v4 offset:26464
	v_cvt_pk_bf16_f32 v4, v27, v28
	ds_write_b16 v1, v4 offset:26992
	ds_write_b16_d16_hi v1, v4 offset:29632
	v_cvt_pk_bf16_f32 v4, v29, v30
	ds_write_b16 v1, v4 offset:30160
	ds_write_b16_d16_hi v1, v4 offset:30688
	v_cvt_pk_bf16_f32 v4, v31, s0
	s_mov_b64 s[0:1], -1
	s_and_b64 vcc, exec, s[18:19]
	v_lshl_add_u64 v[6:7], s[20:21], 0, v[172:173]
	ds_write_b16 v1, v4 offset:31216
	s_cbranch_vccz .LBB0_1191
	v_mad_u64_u32 v[4:5], s[0:1], v6, s68, v[170:171]
	v_mad_i32_i24 v5, v7, s68, v5
	s_mov_b64 s[0:1], 0

.LBB0_1222:
	s_nop 7
	s_nop 3
	v_or_b32_e32 v117, v236, v242
	v_lshlrev_b32_e32 v118, 1, v117
	v_add_u32_e32 v120, s20, v14
	v_add_u32_e32 v121, s20, v180
	v_lshl_add_u32 v120, v120, 12, v118
	v_lshl_add_u32 v121, v121, 12, v118
	v_cvt_pk_bf16_f32 v122, v96, v97
	v_cvt_pk_bf16_f32 v123, v80, v81
	global_store_short v120, v122, s[0:1]
	global_store_short_d16_hi v121, v122, s[0:1]
	global_store_short v120, v123, s[0:1] offset:64
	global_store_short_d16_hi v121, v123, s[0:1] offset:64
	v_add_u32_e32 v120, s20, v182
	v_add_u32_e32 v121, s20, v184
	v_lshl_add_u32 v120, v120, 12, v118
	v_lshl_add_u32 v121, v121, 12, v118
	v_cvt_pk_bf16_f32 v122, v98, v99
	v_cvt_pk_bf16_f32 v123, v82, v83
	global_store_short v120, v122, s[0:1]
	global_store_short_d16_hi v121, v122, s[0:1]
	global_store_short v120, v123, s[0:1] offset:64
	global_store_short_d16_hi v121, v123, s[0:1] offset:64
	v_add_u32_e32 v120, s20, v186
	v_add_u32_e32 v121, s20, v188
	v_lshl_add_u32 v120, v120, 12, v118
	v_lshl_add_u32 v121, v121, 12, v118
	v_cvt_pk_bf16_f32 v122, v100, v101
	v_cvt_pk_bf16_f32 v123, v84, v85
	global_store_short v120, v122, s[0:1]
	global_store_short_d16_hi v121, v122, s[0:1]
	global_store_short v120, v123, s[0:1] offset:64
	global_store_short_d16_hi v121, v123, s[0:1] offset:64
	v_add_u32_e32 v120, s20, v190
	v_add_u32_e32 v121, s20, v192
	v_lshl_add_u32 v120, v120, 12, v118
	v_lshl_add_u32 v121, v121, 12, v118
	v_cvt_pk_bf16_f32 v122, v102, v103
	v_cvt_pk_bf16_f32 v123, v86, v87
	global_store_short v120, v122, s[0:1]
	global_store_short_d16_hi v121, v122, s[0:1]
	global_store_short v120, v123, s[0:1] offset:64
	global_store_short_d16_hi v121, v123, s[0:1] offset:64
	v_add_u32_e32 v120, s20, v194
	v_add_u32_e32 v121, s20, v196
	v_lshl_add_u32 v120, v120, 12, v118
	v_lshl_add_u32 v121, v121, 12, v118
	v_cvt_pk_bf16_f32 v122, v104, v105
	v_cvt_pk_bf16_f32 v123, v88, v89
	global_store_short v120, v122, s[0:1]
	global_store_short_d16_hi v121, v122, s[0:1]
	global_store_short v120, v123, s[0:1] offset:64
	global_store_short_d16_hi v121, v123, s[0:1] offset:64
	v_add_u32_e32 v120, s20, v198
	v_add_u32_e32 v121, s20, v200
	v_lshl_add_u32 v120, v120, 12, v118
	v_lshl_add_u32 v121, v121, 12, v118
	v_cvt_pk_bf16_f32 v122, v106, v107
	v_cvt_pk_bf16_f32 v123, v90, v91
	global_store_short v120, v122, s[0:1]
	global_store_short_d16_hi v121, v122, s[0:1]
	global_store_short v120, v123, s[0:1] offset:64
	global_store_short_d16_hi v121, v123, s[0:1] offset:64
	v_add_u32_e32 v120, s20, v202
	v_add_u32_e32 v121, s20, v204
	v_lshl_add_u32 v120, v120, 12, v118
	v_lshl_add_u32 v121, v121, 12, v118
	v_cvt_pk_bf16_f32 v122, v108, v109
	v_cvt_pk_bf16_f32 v123, v92, v93
	global_store_short v120, v122, s[0:1]
	global_store_short_d16_hi v121, v122, s[0:1]
	global_store_short v120, v123, s[0:1] offset:64
	global_store_short_d16_hi v121, v123, s[0:1] offset:64
	v_add_u32_e32 v120, s20, v206
	v_add_u32_e32 v121, s20, v208
	v_lshl_add_u32 v120, v120, 12, v118
	v_lshl_add_u32 v121, v121, 12, v118
	v_cvt_pk_bf16_f32 v122, v110, v111
	v_cvt_pk_bf16_f32 v123, v94, v95
	global_store_short v120, v122, s[0:1]
	global_store_short_d16_hi v121, v122, s[0:1]
	global_store_short v120, v123, s[0:1] offset:64
	global_store_short_d16_hi v121, v123, s[0:1] offset:64
	v_mul_f32_e32 v14, 0x43000000, v243
	v_exp_f32_e32 v14, v14
	s_nop 0
	v_pk_mul_f32 v[78:79], v[78:79], v[14:15] op_sel_hi:[1,0]
	v_pk_mul_f32 v[76:77], v[76:77], v[14:15] op_sel_hi:[1,0]
	v_pk_mul_f32 v[74:75], v[74:75], v[14:15] op_sel_hi:[1,0]
	v_pk_mul_f32 v[72:73], v[72:73], v[14:15] op_sel_hi:[1,0]
	v_pk_mul_f32 v[70:71], v[70:71], v[14:15] op_sel_hi:[1,0]
	v_pk_mul_f32 v[68:69], v[68:69], v[14:15] op_sel_hi:[1,0]
	v_pk_mul_f32 v[66:67], v[66:67], v[14:15] op_sel_hi:[1,0]
	v_pk_mul_f32 v[64:65], v[64:65], v[14:15] op_sel_hi:[1,0]
	v_pk_mul_f32 v[62:63], v[62:63], v[14:15] op_sel_hi:[1,0]
	v_pk_mul_f32 v[60:61], v[60:61], v[14:15] op_sel_hi:[1,0]
	v_pk_mul_f32 v[58:59], v[58:59], v[14:15] op_sel_hi:[1,0]
	v_pk_mul_f32 v[56:57], v[56:57], v[14:15] op_sel_hi:[1,0]
	v_pk_mul_f32 v[54:55], v[54:55], v[14:15] op_sel_hi:[1,0]
	v_pk_mul_f32 v[52:53], v[52:53], v[14:15] op_sel_hi:[1,0]
	v_pk_mul_f32 v[50:51], v[50:51], v[14:15] op_sel_hi:[1,0]
	v_pk_mul_f32 v[48:49], v[48:49], v[14:15] op_sel_hi:[1,0]
	v_pk_mul_f32 v[46:47], v[46:47], v[14:15] op_sel_hi:[1,0]
	v_pk_mul_f32 v[44:45], v[44:45], v[14:15] op_sel_hi:[1,0]
	v_pk_mul_f32 v[42:43], v[42:43], v[14:15] op_sel_hi:[1,0]
	v_pk_mul_f32 v[40:41], v[40:41], v[14:15] op_sel_hi:[1,0]
	v_pk_mul_f32 v[38:39], v[38:39], v[14:15] op_sel_hi:[1,0]
	v_pk_mul_f32 v[36:37], v[36:37], v[14:15] op_sel_hi:[1,0]
	v_pk_mul_f32 v[34:35], v[34:35], v[14:15] op_sel_hi:[1,0]
	v_pk_mul_f32 v[32:33], v[32:33], v[14:15] op_sel_hi:[1,0]
	v_pk_mul_f32 v[30:31], v[30:31], v[14:15] op_sel_hi:[1,0]
	v_pk_mul_f32 v[28:29], v[28:29], v[14:15] op_sel_hi:[1,0]
	v_pk_mul_f32 v[26:27], v[26:27], v[14:15] op_sel_hi:[1,0]
	v_pk_mul_f32 v[24:25], v[24:25], v[14:15] op_sel_hi:[1,0]
	v_pk_mul_f32 v[22:23], v[22:23], v[14:15] op_sel_hi:[1,0]
	v_pk_mul_f32 v[20:21], v[20:21], v[14:15] op_sel_hi:[1,0]
	v_sub_u32_e32 v15, 0x7f, v244
	v_cndmask_b32_e64 v15, v244, v15, s[16:17]
	v_cvt_f32_i32_e32 v15, v15
	s_barrier
	v_pk_mul_f32 v[18:19], v[18:19], v[14:15] op_sel_hi:[1,0]
	v_pk_mul_f32 v[16:17], v[16:17], v[14:15] op_sel_hi:[1,0]
	v_mul_f32_e32 v14, v243, v15
	v_exp_f32_e32 v15, v14
	s_waitcnt vmcnt(32)
	v_lshlrev_b32_e32 v14, 16, v112
	v_mul_f32_e32 v14, v15, v14
	v_cvt_pk_bf16_f32 v80, v14, s0
	v_lshlrev_b32_e32 v14, 1, v244
	v_add3_u32 v14, v246, v14, v239
	ds_write_b16 v14, v80
	v_and_b32_e32 v80, 0xffff0000, v112
	v_mul_f32_e32 v80, v15, v80
	v_cvt_pk_bf16_f32 v80, v80, s0
	ds_write_b16 v14, v80 offset:144
	v_lshlrev_b32_e32 v80, 16, v113
	v_mul_f32_e32 v80, v15, v80
	v_cvt_pk_bf16_f32 v80, v80, s0
	ds_write_b16 v14, v80 offset:288
	v_and_b32_e32 v80, 0xffff0000, v113
	v_mul_f32_e32 v80, v15, v80
	v_cvt_pk_bf16_f32 v80, v80, s0
	ds_write_b16 v14, v80 offset:432
	v_lshlrev_b32_e32 v80, 16, v114
	v_mul_f32_e32 v80, v15, v80
	v_cvt_pk_bf16_f32 v80, v80, s0
	ds_write_b16 v14, v80 offset:576
	v_and_b32_e32 v80, 0xffff0000, v114
	v_mul_f32_e32 v80, v15, v80
	v_cvt_pk_bf16_f32 v80, v80, s0
	ds_write_b16 v14, v80 offset:720
	v_lshlrev_b32_e32 v80, 16, v115
	v_mul_f32_e32 v80, v15, v80
	v_cvt_pk_bf16_f32 v80, v80, s0
	ds_write_b16 v14, v80 offset:864
	v_and_b32_e32 v80, 0xffff0000, v115
	v_mul_f32_e32 v80, v15, v80
	v_cvt_pk_bf16_f32 v80, v80, s0
	ds_write_b16 v14, v80 offset:1008
	v_lshlrev_b32_e32 v80, 16, v10
	v_and_b32_e32 v10, 0xffff0000, v10
	v_mul_f32_e32 v10, v15, v10
	v_cvt_pk_bf16_f32 v10, v10, s0
	ds_write_b16 v14, v10 offset:1296
	v_lshlrev_b32_e32 v10, 16, v11
	v_mul_f32_e32 v10, v15, v10
	v_cvt_pk_bf16_f32 v10, v10, s0
	ds_write_b16 v14, v10 offset:1440
	v_and_b32_e32 v10, 0xffff0000, v11
	v_mul_f32_e32 v10, v15, v10
	v_cvt_pk_bf16_f32 v10, v10, s0
	ds_write_b16 v14, v10 offset:1584
	v_lshlrev_b32_e32 v10, 16, v12
	v_mul_f32_e32 v10, v15, v10
	v_cvt_pk_bf16_f32 v10, v10, s0
	ds_write_b16 v14, v10 offset:1728
	v_and_b32_e32 v10, 0xffff0000, v12
	v_mul_f32_e32 v10, v15, v10
	v_cvt_pk_bf16_f32 v10, v10, s0
	ds_write_b16 v14, v10 offset:1872
	v_lshlrev_b32_e32 v10, 16, v13
	v_mul_f32_e32 v10, v15, v10
	v_cvt_pk_bf16_f32 v10, v10, s0
	ds_write_b16 v14, v10 offset:2016
	v_and_b32_e32 v10, 0xffff0000, v13
	v_mul_f32_e32 v10, v15, v10
	v_cvt_pk_bf16_f32 v10, v10, s0
	v_mul_f32_e32 v80, v15, v80
	ds_write_b16 v14, v10 offset:2160
	v_or_b32_e32 v10, s20, v174
	v_cvt_pk_bf16_f32 v80, v80, s0
	v_mad_u64_u32 v[10:11], s[0:1], v10, s68, v[178:179]
	ds_write_b16 v14, v80 offset:1152
	v_add_u32_e32 v11, s13, v11
	global_load_dwordx4 v[148:151], v[10:11], off offset:2096
	global_load_dwordx4 v[144:147], v[10:11], off offset:2080
	global_load_dwordx4 v[156:159], v[10:11], off offset:2064
	global_load_dwordx4 v[152:155], v[10:11], off offset:2048
	v_lshlrev_b32_e32 v10, 16, v6
	v_and_b32_e32 v6, 0xffff0000, v6
	v_mul_f32_e32 v6, v15, v6
	v_cvt_pk_bf16_f32 v6, v6, s0
	ds_write_b16 v14, v6 offset:2448
	v_lshlrev_b32_e32 v6, 16, v7
	v_mul_f32_e32 v6, v15, v6
	v_cvt_pk_bf16_f32 v6, v6, s0
	ds_write_b16 v14, v6 offset:2592
	v_and_b32_e32 v6, 0xffff0000, v7
	v_mul_f32_e32 v6, v15, v6
	v_cvt_pk_bf16_f32 v6, v6, s0
	ds_write_b16 v14, v6 offset:2736
	v_lshlrev_b32_e32 v6, 16, v8
	v_mul_f32_e32 v6, v15, v6
	v_cvt_pk_bf16_f32 v6, v6, s0
	ds_write_b16 v14, v6 offset:2880
	v_and_b32_e32 v6, 0xffff0000, v8
	v_mul_f32_e32 v6, v15, v6
	v_cvt_pk_bf16_f32 v6, v6, s0
	ds_write_b16 v14, v6 offset:3024
	v_lshlrev_b32_e32 v6, 16, v9
	v_mul_f32_e32 v6, v15, v6
	v_cvt_pk_bf16_f32 v6, v6, s0
	ds_write_b16 v14, v6 offset:3168
	v_and_b32_e32 v6, 0xffff0000, v9
	v_mul_f32_e32 v6, v15, v6
	v_cvt_pk_bf16_f32 v6, v6, s0
	ds_write_b16 v14, v6 offset:3312
	v_lshlrev_b32_e32 v6, 16, v2
	v_and_b32_e32 v2, 0xffff0000, v2
	v_mul_f32_e32 v2, v15, v2
	v_cvt_pk_bf16_f32 v2, v2, s0
	ds_write_b16 v14, v2 offset:3600
	v_lshlrev_b32_e32 v2, 16, v3
	v_mul_f32_e32 v2, v15, v2
	v_cvt_pk_bf16_f32 v2, v2, s0
	ds_write_b16 v14, v2 offset:3744
	v_and_b32_e32 v2, 0xffff0000, v3
	v_mul_f32_e32 v2, v15, v2
	v_cvt_pk_bf16_f32 v2, v2, s0
	ds_write_b16 v14, v2 offset:3888
	v_lshlrev_b32_e32 v2, 16, v4
	v_mul_f32_e32 v2, v15, v2
	v_cvt_pk_bf16_f32 v2, v2, s0
	ds_write_b16 v14, v2 offset:4032
	v_and_b32_e32 v2, 0xffff0000, v4
	v_mul_f32_e32 v2, v15, v2
	v_cvt_pk_bf16_f32 v2, v2, s0
	ds_write_b16 v14, v2 offset:4176
	v_lshlrev_b32_e32 v2, 16, v5
	v_mul_f32_e32 v2, v15, v2
	v_cvt_pk_bf16_f32 v2, v2, s0
	ds_write_b16 v14, v2 offset:4320
	v_and_b32_e32 v2, 0xffff0000, v5
	v_mul_f32_e32 v2, v15, v2
	v_cvt_pk_bf16_f32 v2, v2, s0
	ds_write_b16 v14, v2 offset:4464
	v_or_b32_e32 v2, 32, v242
	v_mul_f32_e32 v6, v15, v6
	v_mul_u32_u24_e32 v3, 0x88, v2
	v_mul_u32_u24_e32 v2, 0x48, v2
	v_lshl_add_u32 v4, v245, 1, v247
	v_mul_f32_e32 v10, v15, v10
	v_cvt_pk_bf16_f32 v6, v6, s0
	v_lshl_add_u32 v2, v2, 1, v247
	v_lshl_add_u32 v8, v3, 1, v4
	v_lshl_add_u32 v9, v116, 1, v4
	v_cvt_pk_bf16_f32 v10, v10, s0
	ds_write_b16 v14, v6 offset:3456
	v_add3_u32 v6, v2, v246, v234
	v_add_u32_e32 v7, v234, v248
	v_add_u32_e32 v2, v233, v8
	v_add_u32_e32 v3, v233, v9
	s_mov_b32 s0, 0
	ds_write_b16 v14, v10 offset:2304
	s_waitcnt lgkmcnt(0)
	s_barrier

.LBB0_1230:
	ds_read_b128 v[8:11], v3
	ds_read_b128 v[12:15], v7
	ds_read_b128 v[80:83], v6
	ds_read_b128 v[212:215], v2
	s_waitcnt lgkmcnt(2)
	v_mfma_f32_32x32x16_bf16 v[64:79], v[8:11], v[12:15], v[64:79]
	s_waitcnt lgkmcnt(1)
	v_mfma_f32_32x32x16_bf16 v[48:63], v[8:11], v[80:83], v[48:63]
	ds_read_b128 v[8:11], v3 offset:32
	ds_read_b128 v[216:219], v7 offset:32
	s_waitcnt lgkmcnt(2)
	v_mfma_f32_32x32x16_bf16 v[32:47], v[212:215], v[12:15], v[32:47]
	v_mfma_f32_32x32x16_bf16 v[16:31], v[212:215], v[80:83], v[16:31]
	ds_read_b128 v[80:83], v6 offset:32
	ds_read_b128 v[212:215], v2 offset:32
	s_waitcnt lgkmcnt(2)
	v_mfma_f32_32x32x16_bf16 v[64:79], v[8:11], v[216:219], v[64:79]
	s_waitcnt lgkmcnt(1)
	v_mfma_f32_32x32x16_bf16 v[48:63], v[8:11], v[80:83], v[48:63]
	ds_read_b128 v[8:11], v3 offset:64
	ds_read_b128 v[12:15], v7 offset:64
	s_waitcnt lgkmcnt(2)
	v_mfma_f32_32x32x16_bf16 v[32:47], v[212:215], v[216:219], v[32:47]
	v_mfma_f32_32x32x16_bf16 v[16:31], v[212:215], v[80:83], v[16:31]
	ds_read_b128 v[80:83], v6 offset:64
	ds_read_b128 v[212:215], v2 offset:64
	s_waitcnt lgkmcnt(2)
	v_mfma_f32_32x32x16_bf16 v[64:79], v[8:11], v[12:15], v[64:79]
	s_waitcnt lgkmcnt(1)
	v_mfma_f32_32x32x16_bf16 v[48:63], v[8:11], v[80:83], v[48:63]
	ds_read_b128 v[8:11], v3 offset:96
	ds_read_b128 v[216:219], v7 offset:96
	s_waitcnt lgkmcnt(2)
	v_mfma_f32_32x32x16_bf16 v[32:47], v[212:215], v[12:15], v[32:47]
	v_mfma_f32_32x32x16_bf16 v[16:31], v[212:215], v[80:83], v[16:31]
	ds_read_b128 v[80:83], v6 offset:96
	ds_read_b128 v[212:215], v2 offset:96
	s_waitcnt lgkmcnt(2)
	v_mfma_f32_32x32x16_bf16 v[64:79], v[8:11], v[216:219], v[64:79]
	s_waitcnt lgkmcnt(1)
	v_mfma_f32_32x32x16_bf16 v[48:63], v[8:11], v[80:83], v[48:63]
	s_waitcnt lgkmcnt(0)
	v_mfma_f32_32x32x16_bf16 v[32:47], v[212:215], v[216:219], v[32:47]
	v_mfma_f32_32x32x16_bf16 v[16:31], v[212:215], v[80:83], v[16:31]
	v_add_u32_e32 v1, v1, v175
	v_add_u32_e32 v2, v241, v223
	v_lshlrev_b32_e32 v3, 1, v242
	v_mul_lo_u32 v1, v1, s3
	v_add3_u32 v1, v2, v3, v1
	v_cvt_pk_bf16_f32 v2, v65, v66
	ds_write_b16 v1, v2 offset:528
	ds_write_b16_d16_hi v1, v2 offset:1056
	v_cvt_pk_bf16_f32 v2, v67, v68
	ds_write_b16 v1, v2 offset:1584
	ds_write_b16_d16_hi v1, v2 offset:4224
	v_cvt_pk_bf16_f32 v2, v69, v70
	ds_write_b16 v1, v2 offset:4752
	ds_write_b16_d16_hi v1, v2 offset:5280
	v_cvt_pk_bf16_f32 v2, v71, v72
	ds_write_b16 v1, v2 offset:5808
	ds_write_b16_d16_hi v1, v2 offset:8448
	v_cvt_pk_bf16_f32 v2, v73, v74
	ds_write_b16 v1, v2 offset:8976
	ds_write_b16_d16_hi v1, v2 offset:9504
	v_cvt_pk_bf16_f32 v2, v75, v76
	ds_write_b16 v1, v2 offset:10032
	ds_write_b16_d16_hi v1, v2 offset:12672
	v_cvt_pk_bf16_f32 v2, v77, v78
	ds_write_b16 v1, v2 offset:13200
	ds_write_b16_d16_hi v1, v2 offset:13728
	v_cvt_pk_bf16_f32 v2, v79, v48
	ds_write_b16 v1, v2 offset:14256
	ds_write_b16_d16_hi v1, v2 offset:64
	v_cvt_pk_bf16_f32 v2, v49, v50
	ds_write_b16 v1, v2 offset:592
	ds_write_b16_d16_hi v1, v2 offset:1120
	v_cvt_pk_bf16_f32 v2, v51, v52
	ds_write_b16 v1, v2 offset:1648
	ds_write_b16_d16_hi v1, v2 offset:4288
	v_cvt_pk_bf16_f32 v2, v53, v54
	ds_write_b16 v1, v2 offset:4816
	ds_write_b16_d16_hi v1, v2 offset:5344
	v_cvt_pk_bf16_f32 v2, v55, v56
	ds_write_b16 v1, v2 offset:5872
	ds_write_b16_d16_hi v1, v2 offset:8512
	v_cvt_pk_bf16_f32 v2, v57, v58
	ds_write_b16 v1, v2 offset:9040
	ds_write_b16_d16_hi v1, v2 offset:9568
	v_cvt_pk_bf16_f32 v2, v59, v60
	ds_write_b16 v1, v2 offset:10096
	ds_write_b16_d16_hi v1, v2 offset:12736
	v_cvt_pk_bf16_f32 v2, v61, v62
	ds_write_b16 v1, v2 offset:13264
	ds_write_b16_d16_hi v1, v2 offset:13792
	v_cvt_pk_bf16_f32 v2, v63, v32
	ds_write_b16 v1, v2 offset:14320
	ds_write_b16_d16_hi v1, v2 offset:16896
	v_cvt_pk_bf16_f32 v2, v33, v34
	ds_write_b16 v1, v2 offset:17424
	ds_write_b16_d16_hi v1, v2 offset:17952
	v_cvt_pk_bf16_f32 v2, v35, v36
	ds_write_b16 v1, v2 offset:18480
	ds_write_b16_d16_hi v1, v2 offset:21120
	v_cvt_pk_bf16_f32 v2, v37, v38
	ds_write_b16 v1, v2 offset:21648
	ds_write_b16_d16_hi v1, v2 offset:22176
	v_cvt_pk_bf16_f32 v2, v39, v40
	ds_write_b16 v1, v2 offset:22704
	ds_write_b16_d16_hi v1, v2 offset:25344
	v_cvt_pk_bf16_f32 v2, v41, v42
	ds_write_b16 v1, v2 offset:25872
	ds_write_b16_d16_hi v1, v2 offset:26400
	v_cvt_pk_bf16_f32 v2, v43, v44
	ds_write_b16 v1, v2 offset:26928
	ds_write_b16_d16_hi v1, v2 offset:29568
	v_cvt_pk_bf16_f32 v2, v45, v46
	ds_write_b16 v1, v2 offset:30096
	ds_write_b16_d16_hi v1, v2 offset:30624
	v_cvt_pk_bf16_f32 v2, v47, v16
	ds_write_b16 v1, v2 offset:31152
	ds_write_b16_d16_hi v1, v2 offset:16960
	v_cvt_pk_bf16_f32 v2, v17, v18
	ds_write_b16 v1, v2 offset:17488
	ds_write_b16_d16_hi v1, v2 offset:18016
	v_cvt_pk_bf16_f32 v2, v19, v20
	ds_write_b16 v1, v2 offset:18544
	ds_write_b16_d16_hi v1, v2 offset:21184
	v_cvt_pk_bf16_f32 v2, v21, v22
	ds_write_b16 v1, v2 offset:21712
	ds_write_b16_d16_hi v1, v2 offset:22240
	v_cvt_pk_bf16_f32 v2, v23, v24
	ds_write_b16 v1, v2 offset:22768
	ds_write_b16_d16_hi v1, v2 offset:25408
	v_cvt_pk_bf16_f32 v2, v25, v26
	ds_write_b16 v1, v2 offset:25936
	ds_write_b16_d16_hi v1, v2 offset:26464
	v_cvt_pk_bf16_f32 v2, v27, v28
	ds_write_b16 v1, v2 offset:26992
	ds_write_b16_d16_hi v1, v2 offset:29632
	v_cvt_pk_bf16_f32 v2, v29, s0
	ds_write_b16 v1, v2 offset:30160
	v_cvt_pk_bf16_f32 v2, v30, s0
	s_add_i32 s29, s29, 1
	v_cvt_pk_bf16_f32 v4, v64, s0
	ds_write_b16 v1, v2 offset:30688
	v_cvt_pk_bf16_f32 v2, v31, s0
	s_cmp_eq_u32 s29, 16
	ds_write_b16 v1, v4
	ds_write_b16 v1, v2 offset:31216
	s_cbranch_scc0 .LBB0_1194
	s_mov_b32 s0, 1
	s_mov_b64 s[16:17], 0
	s_and_b64 vcc, exec, s[18:19]
	s_waitcnt lgkmcnt(0)
	s_barrier
	s_cbranch_vccz .LBB0_1182
	s_add_i32 s24, s24, s74
	s_cmpk_lt_i32 s24, 0x100
	s_cbranch_scc1 .LBB0_1173

.LBB0_1494:
	s_or_b64 exec, exec, s[14:15]
	v_lshl_or_b32 v130, v137, 2, v138
	v_lshl_add_u32 v132, v130, 2, v220
	s_barrier
	ds_read_b128 v[138:141], v132
	s_lshl_b64 s[12:13], s[12:13], 1
	s_add_u32 s12, s35, s12
	s_addc_u32 s13, s36, s13
	s_mov_b32 s11, 0
	s_waitcnt lgkmcnt(0)
	v_mul_f32_e32 v114, v114, v138
	v_mul_f32_e32 v131, 0xbfb8aa3b, v114
	v_exp_f32_e32 v131, v131
	v_mul_f32_e32 v118, v118, v138
	v_mul_f32_e32 v122, v122, v138
	v_mul_f32_e32 v126, v126, v138
	v_add_f32_e32 v131, 1.0, v131
	v_rcp_f32_e32 v131, v131
	s_nop 0
	v_mul_f32_e32 v114, v114, v131
	v_mul_f32_e32 v131, 0xbfb8aa3b, v118
	v_exp_f32_e32 v131, v131
	v_cvt_pk_bf16_f32 v133, v114, s0
	v_lshlrev_b32_e32 v114, 1, v136
	v_lshl_or_b32 v114, v135, 6, v114
	v_add_f32_e32 v131, 1.0, v131
	v_rcp_f32_e32 v131, v131
	s_nop 0
	v_mul_f32_e32 v118, v118, v131
	v_mul_f32_e32 v131, 0xbfb8aa3b, v122
	v_exp_f32_e32 v131, v131
	s_nop 0
	v_add_f32_e32 v131, 1.0, v131
	v_rcp_f32_e32 v131, v131
	s_nop 0
	v_mul_f32_e32 v122, v122, v131
	v_mul_f32_e32 v131, 0xbfb8aa3b, v126
	v_exp_f32_e32 v131, v131
	s_nop 0
	v_add_f32_e32 v131, 1.0, v131
	v_rcp_f32_e32 v131, v131
	s_nop 0
	v_mul_f32_e32 v126, v126, v131
	v_mad_u64_u32 v[130:131], s[14:15], v130, s3, v[114:115]
	v_cvt_pk_bf16_f32 v114, v118, v122
	ds_write_b16 v130, v114 offset:32
	ds_write_b16_d16_hi v130, v114 offset:256
	v_cvt_pk_bf16_f32 v114, v126, s0
	ds_write_b16 v130, v114 offset:288
	v_mul_f32_e32 v114, v115, v139
	v_mul_f32_e32 v122, 0xbfb8aa3b, v114
	v_exp_f32_e32 v122, v122
	v_mul_f32_e32 v115, v119, v139
	v_mul_f32_e32 v118, v123, v139
	v_mul_f32_e32 v119, v127, v139
	v_add_f32_e32 v122, 1.0, v122
	v_rcp_f32_e32 v122, v122
	ds_write_b16 v130, v133
	v_mul_f32_e32 v114, v114, v122
	v_mul_f32_e32 v122, 0xbfb8aa3b, v115
	v_exp_f32_e32 v122, v122
	v_cvt_pk_bf16_f32 v114, v114, s0
	ds_write_b16 v130, v114 offset:528
	v_add_f32_e32 v122, 1.0, v122
	v_rcp_f32_e32 v122, v122
	s_nop 0
	v_mul_f32_e32 v115, v115, v122
	v_mul_f32_e32 v122, 0xbfb8aa3b, v118
	v_exp_f32_e32 v122, v122
	v_cvt_pk_bf16_f32 v114, v115, s0
	ds_write_b16 v130, v114 offset:560
	v_mul_f32_e32 v115, v120, v140
	v_add_f32_e32 v122, 1.0, v122
	v_rcp_f32_e32 v122, v122
	s_nop 0
	v_mul_f32_e32 v118, v118, v122
	v_mul_f32_e32 v122, 0xbfb8aa3b, v119
	v_exp_f32_e32 v122, v122
	v_cvt_pk_bf16_f32 v114, v118, s0
	ds_write_b16 v130, v114 offset:784
	v_mul_f32_e32 v118, v128, v140
	v_add_f32_e32 v122, 1.0, v122
	v_rcp_f32_e32 v122, v122
	s_nop 0
	v_mul_f32_e32 v119, v119, v122
	v_cvt_pk_bf16_f32 v114, v119, s0
	ds_write_b16 v130, v114 offset:816
	v_mul_f32_e32 v114, v116, v140
	v_mul_f32_e32 v119, 0xbfb8aa3b, v114
	v_exp_f32_e32 v119, v119
	v_mul_f32_e32 v116, v124, v140
	v_add_f32_e32 v119, 1.0, v119
	v_rcp_f32_e32 v119, v119
	s_nop 0
	v_mul_f32_e32 v114, v114, v119
	v_mul_f32_e32 v119, 0xbfb8aa3b, v115
	v_exp_f32_e32 v119, v119
	v_cvt_pk_bf16_f32 v114, v114, s0
	ds_write_b16 v130, v114 offset:1056
	v_add_f32_e32 v119, 1.0, v119
	v_rcp_f32_e32 v119, v119
	s_nop 0
	v_mul_f32_e32 v115, v115, v119
	v_mul_f32_e32 v119, 0xbfb8aa3b, v116
	v_exp_f32_e32 v119, v119
	v_cvt_pk_bf16_f32 v114, v115, s0
	ds_write_b16 v130, v114 offset:1088
	v_mul_f32_e32 v115, v121, v141
	v_add_f32_e32 v119, 1.0, v119
	v_rcp_f32_e32 v119, v119
	s_nop 0
	v_mul_f32_e32 v116, v116, v119
	v_mul_f32_e32 v119, 0xbfb8aa3b, v118
	v_exp_f32_e32 v119, v119
	v_cvt_pk_bf16_f32 v114, v116, s0
	ds_write_b16 v130, v114 offset:1312
	v_mul_f32_e32 v116, v125, v141
	v_add_f32_e32 v119, 1.0, v119
	v_rcp_f32_e32 v119, v119
	s_nop 0
	v_mul_f32_e32 v118, v118, v119
	v_cvt_pk_bf16_f32 v114, v118, s0
	ds_write_b16 v130, v114 offset:1344
	v_mul_f32_e32 v114, v117, v141
	v_mul_f32_e32 v118, 0xbfb8aa3b, v114
	v_exp_f32_e32 v118, v118
	v_mul_f32_e32 v117, v129, v141
	v_add_f32_e32 v118, 1.0, v118
	v_rcp_f32_e32 v118, v118
	s_nop 0
	v_mul_f32_e32 v114, v114, v118
	v_mul_f32_e32 v118, 0xbfb8aa3b, v115
	v_exp_f32_e32 v118, v118
	v_cvt_pk_bf16_f32 v114, v114, s0
	ds_write_b16 v130, v114 offset:1584
	v_add_f32_e32 v118, 1.0, v118
	v_rcp_f32_e32 v118, v118
	s_nop 0
	v_mul_f32_e32 v115, v115, v118
	v_mul_f32_e32 v118, 0xbfb8aa3b, v116
	v_exp_f32_e32 v118, v118
	v_cvt_pk_bf16_f32 v114, v115, s0
	ds_write_b16 v130, v114 offset:1616
	v_add_f32_e32 v118, 1.0, v118
	v_rcp_f32_e32 v118, v118
	s_nop 0
	v_mul_f32_e32 v116, v116, v118
	v_mul_f32_e32 v118, 0xbfb8aa3b, v117
	v_exp_f32_e32 v118, v118
	v_cvt_pk_bf16_f32 v114, v116, s0
	ds_write_b16 v130, v114 offset:1840
	v_add_f32_e32 v118, 1.0, v118
	v_rcp_f32_e32 v118, v118
	s_nop 0
	v_mul_f32_e32 v117, v117, v118
	v_cvt_pk_bf16_f32 v114, v117, s0
	ds_write_b16 v130, v114 offset:1872
	ds_read_b128 v[114:117], v132 offset:64
	s_waitcnt lgkmcnt(0)
	v_mul_f32_e32 v98, v98, v114
	v_mul_f32_e32 v102, v102, v114
	v_mul_f32_e32 v106, v106, v114
	v_mul_f32_e32 v110, v110, v114
	v_mul_f32_e32 v114, 0xbfb8aa3b, v98
	v_exp_f32_e32 v114, v114
	v_mul_f32_e32 v99, v99, v115
	v_add_f32_e32 v114, 1.0, v114
	v_rcp_f32_e32 v114, v114
	s_nop 0
	v_mul_f32_e32 v98, v98, v114
	v_mul_f32_e32 v114, 0xbfb8aa3b, v102
	v_exp_f32_e32 v114, v114
	s_nop 0
	v_add_f32_e32 v114, 1.0, v114
	v_rcp_f32_e32 v114, v114
	s_nop 0
	v_mul_f32_e32 v102, v102, v114
	v_mul_f32_e32 v114, 0xbfb8aa3b, v106
	v_exp_f32_e32 v114, v114
	v_cvt_pk_bf16_f32 v102, v102, s0
	ds_write_b16 v130, v102 offset:8480
	v_add_f32_e32 v114, 1.0, v114
	v_rcp_f32_e32 v114, v114
	s_nop 0
	v_mul_f32_e32 v106, v106, v114
	v_mul_f32_e32 v114, 0xbfb8aa3b, v110
	v_exp_f32_e32 v114, v114
	v_cvt_pk_bf16_f32 v102, v106, s0
	ds_write_b16 v130, v102 offset:8704
	v_mul_f32_e32 v106, v111, v115
	v_add_f32_e32 v114, 1.0, v114
	v_rcp_f32_e32 v114, v114
	s_nop 0
	v_mul_f32_e32 v110, v110, v114
	v_cvt_pk_bf16_f32 v102, v110, s0
	ds_write_b16 v130, v102 offset:8736
	v_mul_f32_e32 v102, v103, v115
	v_mul_f32_e32 v103, v107, v115
	v_mul_f32_e32 v107, 0xbfb8aa3b, v99
	v_exp_f32_e32 v107, v107
	v_cvt_pk_bf16_f32 v114, v98, s0
	v_add_u32_e32 v98, 0x2100, v130
	ds_write_b16 v130, v114 offset:8448
	v_add_f32_e32 v107, 1.0, v107
	v_rcp_f32_e32 v107, v107
	s_nop 0
	v_mul_f32_e32 v99, v99, v107
	v_mul_f32_e32 v107, 0xbfb8aa3b, v102
	v_exp_f32_e32 v107, v107
	v_cvt_pk_bf16_f32 v99, v99, s0
	ds_write_b16 v130, v99 offset:8976
	v_add_f32_e32 v107, 1.0, v107
	v_rcp_f32_e32 v107, v107
	s_nop 0
	v_mul_f32_e32 v102, v102, v107
	v_mul_f32_e32 v107, 0xbfb8aa3b, v103
	v_exp_f32_e32 v107, v107
	v_cvt_pk_bf16_f32 v99, v102, s0
	ds_write_b16 v130, v99 offset:9008
	v_mul_f32_e32 v102, v108, v116
	v_add_f32_e32 v107, 1.0, v107
	v_rcp_f32_e32 v107, v107
	s_nop 0
	v_mul_f32_e32 v103, v103, v107
	v_mul_f32_e32 v107, 0xbfb8aa3b, v106
	v_exp_f32_e32 v107, v107
	v_cvt_pk_bf16_f32 v99, v103, s0
	ds_write_b16 v130, v99 offset:9232
	v_mul_f32_e32 v103, v112, v116
	v_add_f32_e32 v107, 1.0, v107
	v_rcp_f32_e32 v107, v107
	s_nop 0
	v_mul_f32_e32 v106, v106, v107
	v_cvt_pk_bf16_f32 v99, v106, s0
	ds_write_b16 v130, v99 offset:9264
	v_mul_f32_e32 v99, v100, v116
	v_mul_f32_e32 v100, v104, v116
	v_mul_f32_e32 v104, 0xbfb8aa3b, v99
	v_exp_f32_e32 v104, v104
	s_nop 0
	v_add_f32_e32 v104, 1.0, v104
	v_rcp_f32_e32 v104, v104
	s_nop 0
	v_mul_f32_e32 v99, v99, v104
	v_mul_f32_e32 v104, 0xbfb8aa3b, v100
	v_exp_f32_e32 v104, v104
	v_cvt_pk_bf16_f32 v99, v99, s0
	ds_write_b16 v130, v99 offset:9504
	v_add_f32_e32 v104, 1.0, v104
	v_rcp_f32_e32 v104, v104
	s_nop 0
	v_mul_f32_e32 v100, v100, v104
	v_mul_f32_e32 v104, 0xbfb8aa3b, v102
	v_exp_f32_e32 v104, v104
	v_cvt_pk_bf16_f32 v99, v100, s0
	ds_write_b16 v130, v99 offset:9536
	v_mul_f32_e32 v100, v105, v117
	v_add_f32_e32 v104, 1.0, v104
	v_rcp_f32_e32 v104, v104
	s_nop 0
	v_mul_f32_e32 v102, v102, v104
	v_mul_f32_e32 v104, 0xbfb8aa3b, v103
	v_exp_f32_e32 v104, v104
	v_cvt_pk_bf16_f32 v99, v102, s0
	ds_write_b16 v130, v99 offset:9760
	v_mul_f32_e32 v102, v113, v117
	v_add_f32_e32 v104, 1.0, v104
	v_rcp_f32_e32 v104, v104
	s_nop 0
	v_mul_f32_e32 v103, v103, v104
	v_cvt_pk_bf16_f32 v99, v103, s0
	ds_write_b16 v130, v99 offset:9792
	v_mul_f32_e32 v99, v101, v117
	v_mul_f32_e32 v103, 0xbfb8aa3b, v99
	v_exp_f32_e32 v103, v103
	v_mul_f32_e32 v101, v109, v117
	v_add_f32_e32 v103, 1.0, v103
	v_rcp_f32_e32 v103, v103
	s_nop 0
	v_mul_f32_e32 v99, v99, v103
	v_mul_f32_e32 v103, 0xbfb8aa3b, v100
	v_exp_f32_e32 v103, v103
	v_cvt_pk_bf16_f32 v99, v99, s0
	ds_write_b16 v130, v99 offset:10032
	v_add_f32_e32 v103, 1.0, v103
	v_rcp_f32_e32 v103, v103
	s_nop 0
	v_mul_f32_e32 v100, v100, v103
	v_mul_f32_e32 v103, 0xbfb8aa3b, v101
	v_exp_f32_e32 v103, v103
	v_cvt_pk_bf16_f32 v99, v100, s0
	ds_write_b16 v130, v99 offset:10064
	v_add_f32_e32 v103, 1.0, v103
	v_rcp_f32_e32 v103, v103
	s_nop 0
	v_mul_f32_e32 v101, v101, v103
	v_mul_f32_e32 v103, 0xbfb8aa3b, v102
	v_exp_f32_e32 v103, v103
	v_cvt_pk_bf16_f32 v99, v101, s0
	ds_write_b16 v130, v99 offset:10288
	v_add_f32_e32 v103, 1.0, v103
	v_rcp_f32_e32 v103, v103
	s_nop 0
	v_mul_f32_e32 v102, v102, v103
	v_cvt_pk_bf16_f32 v99, v102, s0
	ds_read_b128 v[100:103], v132 offset:128
	ds_write_b16 v130, v99 offset:10320
	s_waitcnt lgkmcnt(1)
	v_mul_f32_e32 v82, v82, v100
	v_mul_f32_e32 v99, 0xbfb8aa3b, v82
	v_exp_f32_e32 v99, v99
	v_mul_f32_e32 v86, v86, v100
	v_mul_f32_e32 v90, v90, v100
	v_mul_f32_e32 v94, v94, v100
	v_add_f32_e32 v99, 1.0, v99
	v_rcp_f32_e32 v99, v99
	s_nop 0
	v_mul_f32_e32 v82, v82, v99
	v_mul_f32_e32 v99, 0xbfb8aa3b, v86
	v_exp_f32_e32 v99, v99
	v_cvt_pk_bf16_f32 v82, v82, s0
	ds_write_b16 v130, v82 offset:16896
	v_add_f32_e32 v99, 1.0, v99
	v_rcp_f32_e32 v99, v99
	s_nop 0
	v_mul_f32_e32 v99, v86, v99
	v_mul_f32_e32 v86, 0xbfb8aa3b, v90
	v_exp_f32_e32 v86, v86
	v_cvt_pk_bf16_f32 v82, v99, s0
	ds_write_b16 v130, v82 offset:16928
	v_add_f32_e32 v86, 1.0, v86
	v_rcp_f32_e32 v86, v86
	s_nop 0
	v_mul_f32_e32 v90, v90, v86
	v_mul_f32_e32 v86, 0xbfb8aa3b, v94
	v_exp_f32_e32 v86, v86
	v_cvt_pk_bf16_f32 v82, v90, s0
	ds_write_b16 v130, v82 offset:17152
	v_mul_f32_e32 v90, v95, v101
	v_add_f32_e32 v86, 1.0, v86
	v_rcp_f32_e32 v86, v86
	s_nop 0
	v_mul_f32_e32 v94, v94, v86
	v_cvt_pk_bf16_f32 v82, v94, s0
	ds_write_b16 v130, v82 offset:17184
	v_mul_f32_e32 v82, v83, v101
	v_mul_f32_e32 v83, v87, v101
	v_mul_f32_e32 v87, v91, v101
	v_mul_f32_e32 v91, 0xbfb8aa3b, v82
	v_exp_f32_e32 v91, v91
	v_add_u32_e32 v86, 0x4200, v130
	v_add_f32_e32 v91, 1.0, v91
	v_rcp_f32_e32 v91, v91
	s_nop 0
	v_mul_f32_e32 v82, v82, v91
	v_mul_f32_e32 v91, 0xbfb8aa3b, v83
	v_exp_f32_e32 v91, v91
	v_cvt_pk_bf16_f32 v82, v82, s0
	ds_write_b16 v130, v82 offset:17424
	v_add_f32_e32 v91, 1.0, v91
	v_rcp_f32_e32 v91, v91
	s_nop 0
	v_mul_f32_e32 v83, v83, v91
	v_mul_f32_e32 v91, 0xbfb8aa3b, v87
	v_exp_f32_e32 v91, v91
	v_cvt_pk_bf16_f32 v82, v83, s0
	ds_write_b16 v130, v82 offset:17456
	v_mul_f32_e32 v83, v88, v102
	v_add_f32_e32 v91, 1.0, v91
	v_rcp_f32_e32 v91, v91
	s_nop 0
	v_mul_f32_e32 v87, v87, v91
	v_mul_f32_e32 v91, 0xbfb8aa3b, v90
	v_exp_f32_e32 v91, v91
	v_cvt_pk_bf16_f32 v82, v87, s0
	ds_write_b16 v130, v82 offset:17680
	v_mul_f32_e32 v87, v96, v102
	v_add_f32_e32 v91, 1.0, v91
	v_rcp_f32_e32 v91, v91
	s_nop 0
	v_mul_f32_e32 v90, v90, v91
	v_cvt_pk_bf16_f32 v82, v90, s0
	ds_write_b16 v130, v82 offset:17712
	v_mul_f32_e32 v82, v84, v102
	v_mul_f32_e32 v88, 0xbfb8aa3b, v82
	v_exp_f32_e32 v88, v88
	v_mul_f32_e32 v84, v92, v102
	v_add_f32_e32 v88, 1.0, v88
	v_rcp_f32_e32 v88, v88
	s_nop 0
	v_mul_f32_e32 v82, v82, v88
	v_mul_f32_e32 v88, 0xbfb8aa3b, v83
	v_exp_f32_e32 v88, v88
	v_cvt_pk_bf16_f32 v82, v82, s0
	ds_write_b16 v130, v82 offset:17952
	v_add_f32_e32 v88, 1.0, v88
	v_rcp_f32_e32 v88, v88
	s_nop 0
	v_mul_f32_e32 v83, v83, v88
	v_mul_f32_e32 v88, 0xbfb8aa3b, v84
	v_exp_f32_e32 v88, v88
	v_cvt_pk_bf16_f32 v82, v83, s0
	ds_write_b16 v130, v82 offset:17984
	v_mul_f32_e32 v83, v89, v103
	v_add_f32_e32 v88, 1.0, v88
	v_rcp_f32_e32 v88, v88
	s_nop 0
	v_mul_f32_e32 v84, v84, v88
	v_mul_f32_e32 v88, 0xbfb8aa3b, v87
	v_exp_f32_e32 v88, v88
	v_cvt_pk_bf16_f32 v82, v84, s0
	ds_write_b16 v130, v82 offset:18208
	v_mul_f32_e32 v84, v93, v103
	v_add_f32_e32 v88, 1.0, v88
	v_rcp_f32_e32 v88, v88
	s_nop 0
	v_mul_f32_e32 v87, v87, v88
	v_cvt_pk_bf16_f32 v82, v87, s0
	ds_write_b16 v130, v82 offset:18240
	v_mul_f32_e32 v82, v85, v103
	v_mul_f32_e32 v87, 0xbfb8aa3b, v82
	v_exp_f32_e32 v87, v87
	v_mul_f32_e32 v85, v97, v103
	v_add_f32_e32 v87, 1.0, v87
	v_rcp_f32_e32 v87, v87
	s_nop 0
	v_mul_f32_e32 v82, v82, v87
	v_mul_f32_e32 v87, 0xbfb8aa3b, v83
	v_exp_f32_e32 v87, v87
	v_cvt_pk_bf16_f32 v82, v82, s0
	ds_write_b16 v130, v82 offset:18480
	v_add_f32_e32 v87, 1.0, v87
	v_rcp_f32_e32 v87, v87
	s_nop 0
	v_mul_f32_e32 v83, v83, v87
	v_mul_f32_e32 v87, 0xbfb8aa3b, v84
	v_exp_f32_e32 v87, v87
	v_cvt_pk_bf16_f32 v82, v83, s0
	ds_write_b16 v130, v82 offset:18512
	v_add_f32_e32 v87, 1.0, v87
	v_rcp_f32_e32 v87, v87
	s_nop 0
	v_mul_f32_e32 v84, v84, v87
	v_mul_f32_e32 v87, 0xbfb8aa3b, v85
	v_exp_f32_e32 v87, v87
	v_cvt_pk_bf16_f32 v82, v84, s0
	ds_write_b16 v130, v82 offset:18736
	v_add_f32_e32 v87, 1.0, v87
	v_rcp_f32_e32 v87, v87
	s_nop 0
	v_mul_f32_e32 v85, v85, v87
	v_cvt_pk_bf16_f32 v82, v85, s0
	ds_write_b16 v130, v82 offset:18768
	ds_read_b128 v[82:85], v132 offset:192
	s_waitcnt lgkmcnt(0)
	v_mul_f32_e32 v66, v66, v82
	v_mul_f32_e32 v70, v70, v82
	v_mul_f32_e32 v74, v74, v82
	v_mul_f32_e32 v78, v78, v82
	v_mul_f32_e32 v82, 0xbfb8aa3b, v66
	v_exp_f32_e32 v82, v82
	v_mul_f32_e32 v67, v67, v83
	v_add_f32_e32 v82, 1.0, v82
	v_rcp_f32_e32 v82, v82
	s_nop 0
	v_mul_f32_e32 v66, v66, v82
	v_mul_f32_e32 v82, 0xbfb8aa3b, v70
	v_exp_f32_e32 v82, v82
	s_nop 0
	v_add_f32_e32 v82, 1.0, v82
	v_rcp_f32_e32 v82, v82
	s_nop 0
	v_mul_f32_e32 v70, v70, v82
	v_mul_f32_e32 v82, 0xbfb8aa3b, v74
	v_exp_f32_e32 v82, v82
	v_cvt_pk_bf16_f32 v70, v70, s0
	ds_write_b16 v130, v70 offset:25376
	v_add_f32_e32 v82, 1.0, v82
	v_rcp_f32_e32 v82, v82
	s_nop 0
	v_mul_f32_e32 v74, v74, v82
	v_mul_f32_e32 v82, 0xbfb8aa3b, v78
	v_exp_f32_e32 v82, v82
	v_cvt_pk_bf16_f32 v70, v74, s0
	ds_write_b16 v130, v70 offset:25600
	v_mul_f32_e32 v74, v79, v83
	v_add_f32_e32 v82, 1.0, v82
	v_rcp_f32_e32 v82, v82
	s_nop 0
	v_mul_f32_e32 v78, v78, v82
	v_cvt_pk_bf16_f32 v70, v78, s0
	ds_write_b16 v130, v70 offset:25632
	v_mul_f32_e32 v70, v71, v83
	v_mul_f32_e32 v71, v75, v83
	v_mul_f32_e32 v75, 0xbfb8aa3b, v67
	v_exp_f32_e32 v75, v75
	v_cvt_pk_bf16_f32 v82, v66, s0
	ds_write_b16 v130, v82 offset:25344
	v_add_u32_e32 v66, 0x6300, v130
	v_add_f32_e32 v75, 1.0, v75
	v_rcp_f32_e32 v75, v75
	s_nop 0
	v_mul_f32_e32 v67, v67, v75
	v_mul_f32_e32 v75, 0xbfb8aa3b, v70
	v_exp_f32_e32 v75, v75
	v_cvt_pk_bf16_f32 v67, v67, s0
	ds_write_b16 v130, v67 offset:25872
	v_add_f32_e32 v75, 1.0, v75
	v_rcp_f32_e32 v75, v75
	s_nop 0
	v_mul_f32_e32 v70, v70, v75
	v_mul_f32_e32 v75, 0xbfb8aa3b, v71
	v_exp_f32_e32 v75, v75
	v_cvt_pk_bf16_f32 v67, v70, s0
	ds_write_b16 v130, v67 offset:25904
	v_mul_f32_e32 v70, v76, v84
	v_add_f32_e32 v75, 1.0, v75
	v_rcp_f32_e32 v75, v75
	s_nop 0
	v_mul_f32_e32 v71, v71, v75
	v_mul_f32_e32 v75, 0xbfb8aa3b, v74
	v_exp_f32_e32 v75, v75
	v_cvt_pk_bf16_f32 v67, v71, s0
	ds_write_b16 v130, v67 offset:26128
	v_mul_f32_e32 v71, v80, v84
	v_add_f32_e32 v75, 1.0, v75
	v_rcp_f32_e32 v75, v75
	s_nop 0
	v_mul_f32_e32 v74, v74, v75
	v_cvt_pk_bf16_f32 v67, v74, s0
	ds_write_b16 v130, v67 offset:26160
	v_mul_f32_e32 v67, v68, v84
	v_mul_f32_e32 v68, v72, v84
	v_mul_f32_e32 v72, 0xbfb8aa3b, v67
	v_exp_f32_e32 v72, v72
	s_nop 0
	v_add_f32_e32 v72, 1.0, v72
	v_rcp_f32_e32 v72, v72
	s_nop 0
	v_mul_f32_e32 v67, v67, v72
	v_mul_f32_e32 v72, 0xbfb8aa3b, v68
	v_exp_f32_e32 v72, v72
	v_cvt_pk_bf16_f32 v67, v67, s0
	ds_write_b16 v130, v67 offset:26400
	v_add_f32_e32 v72, 1.0, v72
	v_rcp_f32_e32 v72, v72
	s_nop 0
	v_mul_f32_e32 v68, v68, v72
	v_mul_f32_e32 v72, 0xbfb8aa3b, v70
	v_exp_f32_e32 v72, v72
	v_cvt_pk_bf16_f32 v67, v68, s0
	ds_write_b16 v130, v67 offset:26432
	v_mul_f32_e32 v68, v73, v85
	v_add_f32_e32 v72, 1.0, v72
	v_rcp_f32_e32 v72, v72
	s_nop 0
	v_mul_f32_e32 v70, v70, v72
	v_mul_f32_e32 v72, 0xbfb8aa3b, v71
	v_exp_f32_e32 v72, v72
	v_cvt_pk_bf16_f32 v67, v70, s0
	ds_write_b16 v130, v67 offset:26656
	v_mul_f32_e32 v70, v81, v85
	v_add_f32_e32 v72, 1.0, v72
	v_rcp_f32_e32 v72, v72
	s_nop 0
	v_mul_f32_e32 v71, v71, v72
	v_cvt_pk_bf16_f32 v67, v71, s0
	ds_write_b16 v130, v67 offset:26688
	v_mul_f32_e32 v67, v69, v85
	v_mul_f32_e32 v71, 0xbfb8aa3b, v67
	v_exp_f32_e32 v71, v71
	v_mul_f32_e32 v69, v77, v85
	v_add_f32_e32 v71, 1.0, v71
	v_rcp_f32_e32 v71, v71
	s_nop 0
	v_mul_f32_e32 v67, v67, v71
	v_mul_f32_e32 v71, 0xbfb8aa3b, v68
	v_exp_f32_e32 v71, v71
	v_cvt_pk_bf16_f32 v67, v67, s0
	ds_write_b16 v130, v67 offset:26928
	v_add_f32_e32 v71, 1.0, v71
	v_rcp_f32_e32 v71, v71
	s_nop 0
	v_mul_f32_e32 v68, v68, v71
	v_mul_f32_e32 v71, 0xbfb8aa3b, v69
	v_exp_f32_e32 v71, v71
	v_cvt_pk_bf16_f32 v67, v68, s0
	ds_write_b16 v130, v67 offset:26960
	v_add_f32_e32 v71, 1.0, v71
	v_rcp_f32_e32 v71, v71
	s_nop 0
	v_mul_f32_e32 v69, v69, v71
	v_mul_f32_e32 v71, 0xbfb8aa3b, v70
	v_exp_f32_e32 v71, v71
	v_cvt_pk_bf16_f32 v67, v69, s0
	ds_write_b16 v130, v67 offset:27184
	v_add_f32_e32 v71, 1.0, v71
	v_rcp_f32_e32 v71, v71
	s_nop 0
	v_mul_f32_e32 v70, v70, v71
	v_cvt_pk_bf16_f32 v67, v70, s0
	ds_read_b128 v[68:71], v132 offset:512
	ds_write_b16 v130, v67 offset:27216
	s_waitcnt lgkmcnt(1)
	v_mul_f32_e32 v50, v50, v68
	v_mul_f32_e32 v67, 0xbfb8aa3b, v50
	v_exp_f32_e32 v67, v67
	v_mul_f32_e32 v54, v54, v68
	v_mul_f32_e32 v58, v58, v68
	v_mul_f32_e32 v62, v62, v68
	v_add_f32_e32 v67, 1.0, v67
	v_rcp_f32_e32 v67, v67
	s_nop 0
	v_mul_f32_e32 v50, v50, v67
	v_mul_f32_e32 v67, 0xbfb8aa3b, v54
	v_exp_f32_e32 v67, v67
	v_cvt_pk_bf16_f32 v50, v50, s0
	ds_write_b16 v98, v50 offset:59136
	v_add_f32_e32 v67, 1.0, v67
	v_rcp_f32_e32 v67, v67
	s_nop 0
	v_mul_f32_e32 v67, v54, v67
	v_mul_f32_e32 v54, 0xbfb8aa3b, v58
	v_exp_f32_e32 v54, v54
	v_cvt_pk_bf16_f32 v50, v67, s0
	ds_write_b16 v98, v50 offset:59168
	v_add_f32_e32 v54, 1.0, v54
	v_rcp_f32_e32 v54, v54
	s_nop 0
	v_mul_f32_e32 v58, v58, v54
	v_mul_f32_e32 v54, 0xbfb8aa3b, v62
	v_exp_f32_e32 v54, v54
	v_cvt_pk_bf16_f32 v50, v58, s0
	ds_write_b16 v98, v50 offset:59392
	v_mul_f32_e32 v58, v63, v69
	v_add_f32_e32 v54, 1.0, v54
	v_rcp_f32_e32 v54, v54
	s_nop 0
	v_mul_f32_e32 v62, v62, v54
	v_cvt_pk_bf16_f32 v50, v62, s0
	ds_write_b16 v98, v50 offset:59424
	v_mul_f32_e32 v50, v51, v69
	v_mul_f32_e32 v51, v55, v69
	v_mul_f32_e32 v55, v59, v69
	v_mul_f32_e32 v59, 0xbfb8aa3b, v50
	v_exp_f32_e32 v59, v59
	v_add_u32_e32 v54, 0xe700, v98
	v_add_f32_e32 v59, 1.0, v59
	v_rcp_f32_e32 v59, v59
	s_nop 0
	v_mul_f32_e32 v50, v50, v59
	v_mul_f32_e32 v59, 0xbfb8aa3b, v51
	v_exp_f32_e32 v59, v59
	v_cvt_pk_bf16_f32 v50, v50, s0
	ds_write_b16 v98, v50 offset:59664
	v_add_f32_e32 v59, 1.0, v59
	v_rcp_f32_e32 v59, v59
	s_nop 0
	v_mul_f32_e32 v51, v51, v59
	v_mul_f32_e32 v59, 0xbfb8aa3b, v55
	v_exp_f32_e32 v59, v59
	v_cvt_pk_bf16_f32 v50, v51, s0
	ds_write_b16 v98, v50 offset:59696
	v_mul_f32_e32 v51, v56, v70
	v_add_f32_e32 v59, 1.0, v59
	v_rcp_f32_e32 v59, v59
	s_nop 0
	v_mul_f32_e32 v55, v55, v59
	v_mul_f32_e32 v59, 0xbfb8aa3b, v58
	v_exp_f32_e32 v59, v59
	v_cvt_pk_bf16_f32 v50, v55, s0
	ds_write_b16 v98, v50 offset:59920
	v_mul_f32_e32 v55, v64, v70
	v_add_f32_e32 v59, 1.0, v59
	v_rcp_f32_e32 v59, v59
	s_nop 0
	v_mul_f32_e32 v58, v58, v59
	v_cvt_pk_bf16_f32 v50, v58, s0
	ds_write_b16 v98, v50 offset:59952
	v_mul_f32_e32 v50, v52, v70
	v_mul_f32_e32 v56, 0xbfb8aa3b, v50
	v_exp_f32_e32 v56, v56
	v_mul_f32_e32 v52, v60, v70
	v_add_f32_e32 v56, 1.0, v56
	v_rcp_f32_e32 v56, v56
	s_nop 0
	v_mul_f32_e32 v50, v50, v56
	v_mul_f32_e32 v56, 0xbfb8aa3b, v51
	v_exp_f32_e32 v56, v56
	v_cvt_pk_bf16_f32 v50, v50, s0
	ds_write_b16 v98, v50 offset:60192
	v_add_f32_e32 v56, 1.0, v56
	v_rcp_f32_e32 v56, v56
	s_nop 0
	v_mul_f32_e32 v51, v51, v56
	v_mul_f32_e32 v56, 0xbfb8aa3b, v52
	v_exp_f32_e32 v56, v56
	v_cvt_pk_bf16_f32 v50, v51, s0
	ds_write_b16 v98, v50 offset:60224
	v_mul_f32_e32 v51, v57, v71
	v_add_f32_e32 v56, 1.0, v56
	v_rcp_f32_e32 v56, v56
	s_nop 0
	v_mul_f32_e32 v52, v52, v56
	v_mul_f32_e32 v56, 0xbfb8aa3b, v55
	v_exp_f32_e32 v56, v56
	v_cvt_pk_bf16_f32 v50, v52, s0
	ds_write_b16 v98, v50 offset:60448
	v_mul_f32_e32 v52, v61, v71
	v_add_f32_e32 v56, 1.0, v56
	v_rcp_f32_e32 v56, v56
	s_nop 0
	v_mul_f32_e32 v55, v55, v56
	v_cvt_pk_bf16_f32 v50, v55, s0
	ds_write_b16 v98, v50 offset:60480
	v_mul_f32_e32 v50, v53, v71
	v_mul_f32_e32 v55, 0xbfb8aa3b, v50
	v_exp_f32_e32 v55, v55
	v_mul_f32_e32 v53, v65, v71
	v_add_f32_e32 v55, 1.0, v55
	v_rcp_f32_e32 v55, v55
	s_nop 0
	v_mul_f32_e32 v50, v50, v55
	v_mul_f32_e32 v55, 0xbfb8aa3b, v51
	v_exp_f32_e32 v55, v55
	v_cvt_pk_bf16_f32 v50, v50, s0
	ds_write_b16 v98, v50 offset:60720
	v_add_f32_e32 v55, 1.0, v55
	v_rcp_f32_e32 v55, v55
	s_nop 0
	v_mul_f32_e32 v51, v51, v55
	v_mul_f32_e32 v55, 0xbfb8aa3b, v52
	v_exp_f32_e32 v55, v55
	v_cvt_pk_bf16_f32 v50, v51, s0
	ds_write_b16 v98, v50 offset:60752
	v_add_f32_e32 v55, 1.0, v55
	v_rcp_f32_e32 v55, v55
	s_nop 0
	v_mul_f32_e32 v52, v52, v55
	v_mul_f32_e32 v55, 0xbfb8aa3b, v53
	v_exp_f32_e32 v55, v55
	v_cvt_pk_bf16_f32 v50, v52, s0
	ds_write_b16 v98, v50 offset:60976
	v_add_f32_e32 v55, 1.0, v55
	v_rcp_f32_e32 v55, v55
	s_nop 0
	v_mul_f32_e32 v53, v53, v55
	v_cvt_pk_bf16_f32 v50, v53, s0
	ds_write_b16 v98, v50 offset:61008
	ds_read_b128 v[50:53], v132 offset:576
	s_waitcnt lgkmcnt(0)
	v_mul_f32_e32 v34, v34, v50
	v_mul_f32_e32 v38, v38, v50
	v_mul_f32_e32 v42, v42, v50
	v_mul_f32_e32 v46, v46, v50
	v_mul_f32_e32 v50, 0xbfb8aa3b, v34
	v_exp_f32_e32 v50, v50
	s_nop 0
	v_add_f32_e32 v50, 1.0, v50
	v_rcp_f32_e32 v50, v50
	s_nop 0
	v_mul_f32_e32 v34, v34, v50
	v_mul_f32_e32 v50, 0xbfb8aa3b, v38
	v_exp_f32_e32 v50, v50
	v_cvt_pk_bf16_f32 v34, v34, s0
	ds_write_b16 v86, v34 offset:59136
	v_add_f32_e32 v50, 1.0, v50
	v_rcp_f32_e32 v50, v50
	s_nop 0
	v_mul_f32_e32 v38, v38, v50
	v_mul_f32_e32 v50, 0xbfb8aa3b, v42
	v_exp_f32_e32 v50, v50
	v_cvt_pk_bf16_f32 v34, v38, s0
	ds_write_b16 v86, v34 offset:59168
	v_mul_f32_e32 v38, v43, v51
	v_add_f32_e32 v50, 1.0, v50
	v_rcp_f32_e32 v50, v50
	s_nop 0
	v_mul_f32_e32 v42, v42, v50
	v_mul_f32_e32 v50, 0xbfb8aa3b, v46
	v_exp_f32_e32 v50, v50
	v_cvt_pk_bf16_f32 v34, v42, s0
	ds_write_b16 v86, v34 offset:59392
	v_add_f32_e32 v50, 1.0, v50
	v_rcp_f32_e32 v50, v50
	s_nop 0
	v_mul_f32_e32 v46, v46, v50
	v_cvt_pk_bf16_f32 v34, v46, s0
	ds_write_b16 v86, v34 offset:59424
	v_mul_f32_e32 v34, v35, v51
	v_mul_f32_e32 v42, 0xbfb8aa3b, v34
	v_exp_f32_e32 v42, v42
	v_mul_f32_e32 v35, v39, v51
	v_mul_f32_e32 v39, v47, v51
	v_add_f32_e32 v42, 1.0, v42
	v_rcp_f32_e32 v42, v42
	s_nop 0
	v_mul_f32_e32 v34, v34, v42
	v_mul_f32_e32 v42, 0xbfb8aa3b, v35
	v_exp_f32_e32 v42, v42
	v_cvt_pk_bf16_f32 v34, v34, s0
	ds_write_b16 v86, v34 offset:59664
	v_add_f32_e32 v42, 1.0, v42
	v_rcp_f32_e32 v42, v42
	s_nop 0
	v_mul_f32_e32 v35, v35, v42
	v_mul_f32_e32 v42, 0xbfb8aa3b, v38
	v_exp_f32_e32 v42, v42
	v_cvt_pk_bf16_f32 v34, v35, s0
	ds_write_b16 v86, v34 offset:59696
	v_mul_f32_e32 v35, v40, v52
	v_add_f32_e32 v42, 1.0, v42
	v_rcp_f32_e32 v42, v42
	s_nop 0
	v_mul_f32_e32 v38, v38, v42
	v_mul_f32_e32 v42, 0xbfb8aa3b, v39
	v_exp_f32_e32 v42, v42
	v_cvt_pk_bf16_f32 v34, v38, s0
	ds_write_b16 v86, v34 offset:59920
	v_mul_f32_e32 v38, v48, v52
	v_add_f32_e32 v42, 1.0, v42
	v_rcp_f32_e32 v42, v42
	s_nop 0
	v_mul_f32_e32 v39, v39, v42
	v_cvt_pk_bf16_f32 v34, v39, s0
	ds_write_b16 v86, v34 offset:59952
	v_mul_f32_e32 v34, v36, v52
	v_mul_f32_e32 v39, 0xbfb8aa3b, v34
	v_exp_f32_e32 v39, v39
	v_mul_f32_e32 v36, v44, v52
	v_add_f32_e32 v39, 1.0, v39
	v_rcp_f32_e32 v39, v39
	s_nop 0
	v_mul_f32_e32 v34, v34, v39
	v_mul_f32_e32 v39, 0xbfb8aa3b, v35
	v_exp_f32_e32 v39, v39
	v_cvt_pk_bf16_f32 v34, v34, s0
	ds_write_b16 v86, v34 offset:60192
	v_add_f32_e32 v39, 1.0, v39
	v_rcp_f32_e32 v39, v39
	s_nop 0
	v_mul_f32_e32 v35, v35, v39
	v_mul_f32_e32 v39, 0xbfb8aa3b, v36
	v_exp_f32_e32 v39, v39
	v_cvt_pk_bf16_f32 v34, v35, s0
	ds_write_b16 v86, v34 offset:60224
	v_mul_f32_e32 v35, v41, v53
	v_add_f32_e32 v39, 1.0, v39
	v_rcp_f32_e32 v39, v39
	s_nop 0
	v_mul_f32_e32 v36, v36, v39
	v_mul_f32_e32 v39, 0xbfb8aa3b, v38
	v_exp_f32_e32 v39, v39
	v_cvt_pk_bf16_f32 v34, v36, s0
	ds_write_b16 v86, v34 offset:60448
	v_mul_f32_e32 v36, v45, v53
	v_add_f32_e32 v39, 1.0, v39
	v_rcp_f32_e32 v39, v39
	s_nop 0
	v_mul_f32_e32 v38, v38, v39
	v_cvt_pk_bf16_f32 v34, v38, s0
	ds_write_b16 v86, v34 offset:60480
	v_mul_f32_e32 v34, v37, v53
	v_mul_f32_e32 v38, 0xbfb8aa3b, v34
	v_exp_f32_e32 v38, v38
	v_mul_f32_e32 v37, v49, v53
	v_add_f32_e32 v38, 1.0, v38
	v_rcp_f32_e32 v38, v38
	s_nop 0
	v_mul_f32_e32 v34, v34, v38
	v_mul_f32_e32 v38, 0xbfb8aa3b, v35
	v_exp_f32_e32 v38, v38
	v_cvt_pk_bf16_f32 v34, v34, s0
	ds_write_b16 v86, v34 offset:60720
	v_add_f32_e32 v38, 1.0, v38
	v_rcp_f32_e32 v38, v38
	s_nop 0
	v_mul_f32_e32 v35, v35, v38
	v_mul_f32_e32 v38, 0xbfb8aa3b, v36
	v_exp_f32_e32 v38, v38
	v_cvt_pk_bf16_f32 v34, v35, s0
	ds_write_b16 v86, v34 offset:60752
	v_add_f32_e32 v38, 1.0, v38
	v_rcp_f32_e32 v38, v38
	s_nop 0
	v_mul_f32_e32 v36, v36, v38
	v_mul_f32_e32 v38, 0xbfb8aa3b, v37
	v_exp_f32_e32 v38, v38
	v_cvt_pk_bf16_f32 v34, v36, s0
	ds_write_b16 v86, v34 offset:60976
	v_add_f32_e32 v38, 1.0, v38
	v_rcp_f32_e32 v38, v38
	s_nop 0
	v_mul_f32_e32 v37, v37, v38
	v_cvt_pk_bf16_f32 v34, v37, s0
	ds_write_b16 v86, v34 offset:61008
	ds_read_b128 v[34:37], v132 offset:640
	s_waitcnt lgkmcnt(0)
	v_mul_f32_e32 v18, v18, v34
	v_mul_f32_e32 v22, v22, v34
	v_mul_f32_e32 v26, v26, v34
	v_mul_f32_e32 v30, v30, v34
	v_mul_f32_e32 v34, 0xbfb8aa3b, v18
	v_exp_f32_e32 v34, v34
	s_nop 0
	v_add_f32_e32 v34, 1.0, v34
	v_rcp_f32_e32 v34, v34
	s_nop 0
	v_mul_f32_e32 v18, v18, v34
	v_mul_f32_e32 v34, 0xbfb8aa3b, v22
	v_exp_f32_e32 v34, v34
	v_cvt_pk_bf16_f32 v18, v18, s0
	ds_write_b16 v66, v18 offset:59136
	v_add_f32_e32 v34, 1.0, v34
	v_rcp_f32_e32 v34, v34
	s_nop 0
	v_mul_f32_e32 v22, v22, v34
	v_mul_f32_e32 v34, 0xbfb8aa3b, v26
	v_exp_f32_e32 v34, v34
	v_cvt_pk_bf16_f32 v18, v22, s0
	ds_write_b16 v66, v18 offset:59168
	v_mul_f32_e32 v22, v27, v35
	v_add_f32_e32 v34, 1.0, v34
	v_rcp_f32_e32 v34, v34
	s_nop 0
	v_mul_f32_e32 v26, v26, v34
	v_mul_f32_e32 v34, 0xbfb8aa3b, v30
	v_exp_f32_e32 v34, v34
	v_cvt_pk_bf16_f32 v18, v26, s0
	ds_write_b16 v66, v18 offset:59392
	v_add_f32_e32 v34, 1.0, v34
	v_rcp_f32_e32 v34, v34
	s_nop 0
	v_mul_f32_e32 v30, v30, v34
	v_cvt_pk_bf16_f32 v18, v30, s0
	ds_write_b16 v66, v18 offset:59424
	v_mul_f32_e32 v18, v19, v35
	v_mul_f32_e32 v26, 0xbfb8aa3b, v18
	v_exp_f32_e32 v26, v26
	v_mul_f32_e32 v19, v23, v35
	v_mul_f32_e32 v23, v31, v35
	v_add_f32_e32 v26, 1.0, v26
	v_rcp_f32_e32 v26, v26
	s_nop 0
	v_mul_f32_e32 v18, v18, v26
	v_mul_f32_e32 v26, 0xbfb8aa3b, v19
	v_exp_f32_e32 v26, v26
	v_cvt_pk_bf16_f32 v18, v18, s0
	ds_write_b16 v66, v18 offset:59664
	v_add_f32_e32 v26, 1.0, v26
	v_rcp_f32_e32 v26, v26
	s_nop 0
	v_mul_f32_e32 v19, v19, v26
	v_mul_f32_e32 v26, 0xbfb8aa3b, v22
	v_exp_f32_e32 v26, v26
	v_cvt_pk_bf16_f32 v18, v19, s0
	ds_write_b16 v66, v18 offset:59696
	v_mul_f32_e32 v19, v24, v36
	v_add_f32_e32 v26, 1.0, v26
	v_rcp_f32_e32 v26, v26
	s_nop 0
	v_mul_f32_e32 v22, v22, v26
	v_mul_f32_e32 v26, 0xbfb8aa3b, v23
	v_exp_f32_e32 v26, v26
	v_cvt_pk_bf16_f32 v18, v22, s0
	ds_write_b16 v66, v18 offset:59920
	v_mul_f32_e32 v22, v32, v36
	v_add_f32_e32 v26, 1.0, v26
	v_rcp_f32_e32 v26, v26
	s_nop 0
	v_mul_f32_e32 v23, v23, v26
	v_cvt_pk_bf16_f32 v18, v23, s0
	ds_write_b16 v66, v18 offset:59952
	v_mul_f32_e32 v18, v20, v36
	v_mul_f32_e32 v23, 0xbfb8aa3b, v18
	v_exp_f32_e32 v23, v23
	v_mul_f32_e32 v20, v28, v36
	v_add_f32_e32 v23, 1.0, v23
	v_rcp_f32_e32 v23, v23
	s_nop 0
	v_mul_f32_e32 v18, v18, v23
	v_mul_f32_e32 v23, 0xbfb8aa3b, v19
	v_exp_f32_e32 v23, v23
	v_cvt_pk_bf16_f32 v18, v18, s0
	ds_write_b16 v66, v18 offset:60192
	v_add_f32_e32 v23, 1.0, v23
	v_rcp_f32_e32 v23, v23
	s_nop 0
	v_mul_f32_e32 v19, v19, v23
	v_mul_f32_e32 v23, 0xbfb8aa3b, v20
	v_exp_f32_e32 v23, v23
	v_cvt_pk_bf16_f32 v18, v19, s0
	ds_write_b16 v66, v18 offset:60224
	v_mul_f32_e32 v19, v25, v37
	v_add_f32_e32 v23, 1.0, v23
	v_rcp_f32_e32 v23, v23
	s_nop 0
	v_mul_f32_e32 v20, v20, v23
	v_mul_f32_e32 v23, 0xbfb8aa3b, v22
	v_exp_f32_e32 v23, v23
	v_cvt_pk_bf16_f32 v18, v20, s0
	ds_write_b16 v66, v18 offset:60448
	v_mul_f32_e32 v20, v29, v37
	v_add_f32_e32 v23, 1.0, v23
	v_rcp_f32_e32 v23, v23
	s_nop 0
	v_mul_f32_e32 v22, v22, v23
	v_cvt_pk_bf16_f32 v18, v22, s0
	ds_write_b16 v66, v18 offset:60480
	v_mul_f32_e32 v18, v21, v37
	v_mul_f32_e32 v22, 0xbfb8aa3b, v18
	v_exp_f32_e32 v22, v22
	v_mul_f32_e32 v21, v33, v37
	v_add_f32_e32 v22, 1.0, v22
	v_rcp_f32_e32 v22, v22
	s_nop 0
	v_mul_f32_e32 v18, v18, v22
	v_mul_f32_e32 v22, 0xbfb8aa3b, v19
	v_exp_f32_e32 v22, v22
	v_cvt_pk_bf16_f32 v18, v18, s0
	ds_write_b16 v66, v18 offset:60720
	v_add_f32_e32 v22, 1.0, v22
	v_rcp_f32_e32 v22, v22
	s_nop 0
	v_mul_f32_e32 v19, v19, v22
	v_mul_f32_e32 v22, 0xbfb8aa3b, v20
	v_exp_f32_e32 v22, v22
	v_cvt_pk_bf16_f32 v18, v19, s0
	ds_write_b16 v66, v18 offset:60752
	v_add_f32_e32 v22, 1.0, v22
	v_rcp_f32_e32 v22, v22
	s_nop 0
	v_mul_f32_e32 v20, v20, v22
	v_mul_f32_e32 v22, 0xbfb8aa3b, v21
	v_exp_f32_e32 v22, v22
	v_cvt_pk_bf16_f32 v18, v20, s0
	ds_write_b16 v66, v18 offset:60976
	v_add_f32_e32 v22, 1.0, v22
	v_rcp_f32_e32 v22, v22
	s_nop 0
	v_mul_f32_e32 v21, v21, v22
	v_cvt_pk_bf16_f32 v18, v21, s0
	ds_write_b16 v66, v18 offset:61008
	ds_read_b128 v[18:21], v132 offset:704
	s_waitcnt lgkmcnt(0)
	v_mul_f32_e32 v2, v2, v18
	v_mul_f32_e32 v6, v6, v18
	v_mul_f32_e32 v10, v10, v18
	v_mul_f32_e32 v14, v14, v18
	v_mul_f32_e32 v18, 0xbfb8aa3b, v2
	v_exp_f32_e32 v18, v18
	s_nop 0
	v_add_f32_e32 v18, 1.0, v18
	v_rcp_f32_e32 v18, v18
	s_nop 0
	v_mul_f32_e32 v2, v2, v18
	v_mul_f32_e32 v18, 0xbfb8aa3b, v6
	v_exp_f32_e32 v18, v18
	v_cvt_pk_bf16_f32 v2, v2, s0
	ds_write_b16 v54, v2 offset:25344
	v_add_f32_e32 v18, 1.0, v18
	v_rcp_f32_e32 v18, v18
	s_nop 0
	v_mul_f32_e32 v6, v6, v18
	v_mul_f32_e32 v18, 0xbfb8aa3b, v10
	v_exp_f32_e32 v18, v18
	v_cvt_pk_bf16_f32 v2, v6, s0
	ds_write_b16 v54, v2 offset:25376
	v_mul_f32_e32 v6, v11, v19
	v_add_f32_e32 v18, 1.0, v18
	v_rcp_f32_e32 v18, v18
	s_nop 0
	v_mul_f32_e32 v10, v10, v18
	v_mul_f32_e32 v18, 0xbfb8aa3b, v14
	v_exp_f32_e32 v18, v18
	v_cvt_pk_bf16_f32 v2, v10, s0
	ds_write_b16 v54, v2 offset:25600
	v_add_f32_e32 v18, 1.0, v18
	v_rcp_f32_e32 v18, v18
	s_nop 0
	v_mul_f32_e32 v14, v14, v18
	v_cvt_pk_bf16_f32 v2, v14, s0
	ds_write_b16 v54, v2 offset:25632
	v_mul_f32_e32 v2, v3, v19
	v_mul_f32_e32 v10, 0xbfb8aa3b, v2
	v_exp_f32_e32 v10, v10
	v_mul_f32_e32 v3, v7, v19
	v_mul_f32_e32 v7, v15, v19
	v_add_f32_e32 v10, 1.0, v10
	v_rcp_f32_e32 v10, v10
	s_nop 0
	v_mul_f32_e32 v2, v2, v10
	v_mul_f32_e32 v10, 0xbfb8aa3b, v3
	v_exp_f32_e32 v10, v10
	v_cvt_pk_bf16_f32 v2, v2, s0
	ds_write_b16 v54, v2 offset:25872
	v_add_f32_e32 v10, 1.0, v10
	v_rcp_f32_e32 v10, v10
	s_nop 0
	v_mul_f32_e32 v3, v3, v10
	v_mul_f32_e32 v10, 0xbfb8aa3b, v6
	v_exp_f32_e32 v10, v10
	v_cvt_pk_bf16_f32 v2, v3, s0
	ds_write_b16 v54, v2 offset:25904
	v_mul_f32_e32 v3, v8, v20
	v_add_f32_e32 v10, 1.0, v10
	v_rcp_f32_e32 v10, v10
	s_nop 0
	v_mul_f32_e32 v6, v6, v10
	v_mul_f32_e32 v10, 0xbfb8aa3b, v7
	v_exp_f32_e32 v10, v10
	v_cvt_pk_bf16_f32 v2, v6, s0
	ds_write_b16 v54, v2 offset:26128
	v_mul_f32_e32 v6, v16, v20
	v_add_f32_e32 v10, 1.0, v10
	v_rcp_f32_e32 v10, v10
	s_nop 0
	v_mul_f32_e32 v7, v7, v10
	v_cvt_pk_bf16_f32 v2, v7, s0
	ds_write_b16 v54, v2 offset:26160
	v_mul_f32_e32 v2, v4, v20
	v_mul_f32_e32 v7, 0xbfb8aa3b, v2
	v_exp_f32_e32 v7, v7
	v_mul_f32_e32 v4, v12, v20
	v_add_f32_e32 v7, 1.0, v7
	v_rcp_f32_e32 v7, v7
	s_nop 0
	v_mul_f32_e32 v2, v2, v7
	v_mul_f32_e32 v7, 0xbfb8aa3b, v3
	v_exp_f32_e32 v7, v7
	v_cvt_pk_bf16_f32 v2, v2, s0
	ds_write_b16 v54, v2 offset:26400
	v_add_f32_e32 v7, 1.0, v7
	v_rcp_f32_e32 v7, v7
	s_nop 0
	v_mul_f32_e32 v3, v3, v7
	v_mul_f32_e32 v7, 0xbfb8aa3b, v4
	v_exp_f32_e32 v7, v7
	v_cvt_pk_bf16_f32 v2, v3, s0
	ds_write_b16 v54, v2 offset:26432
	v_mul_f32_e32 v3, v9, v21
	v_add_f32_e32 v7, 1.0, v7
	v_rcp_f32_e32 v7, v7
	s_nop 0
	v_mul_f32_e32 v4, v4, v7
	v_mul_f32_e32 v7, 0xbfb8aa3b, v6
	v_exp_f32_e32 v7, v7
	v_cvt_pk_bf16_f32 v2, v4, s0
	ds_write_b16 v54, v2 offset:26656
	v_mul_f32_e32 v4, v13, v21
	v_add_f32_e32 v7, 1.0, v7
	v_rcp_f32_e32 v7, v7
	s_nop 0
	v_mul_f32_e32 v6, v6, v7
	v_cvt_pk_bf16_f32 v2, v6, s0
	ds_write_b16 v54, v2 offset:26688
	v_mul_f32_e32 v2, v5, v21
	v_mul_f32_e32 v6, 0xbfb8aa3b, v2
	v_exp_f32_e32 v6, v6
	v_mul_f32_e32 v5, v17, v21
	v_add_f32_e32 v6, 1.0, v6
	v_rcp_f32_e32 v6, v6
	s_nop 0
	v_mul_f32_e32 v2, v2, v6
	v_mul_f32_e32 v6, 0xbfb8aa3b, v3
	v_exp_f32_e32 v6, v6
	v_cvt_pk_bf16_f32 v2, v2, s0
	ds_write_b16 v54, v2 offset:26928
	v_add_f32_e32 v6, 1.0, v6
	v_rcp_f32_e32 v6, v6
	s_nop 0
	v_mul_f32_e32 v3, v3, v6
	v_mul_f32_e32 v6, 0xbfb8aa3b, v4
	v_exp_f32_e32 v6, v6
	v_cvt_pk_bf16_f32 v2, v3, s0
	ds_write_b16 v54, v2 offset:26960
	v_mov_b32_e32 v3, v0
	v_add_f32_e32 v6, 1.0, v6
	v_rcp_f32_e32 v6, v6
	s_nop 0
	v_mul_f32_e32 v4, v4, v6
	v_mul_f32_e32 v6, 0xbfb8aa3b, v5
	v_exp_f32_e32 v6, v6
	v_cvt_pk_bf16_f32 v2, v4, s0
	ds_write_b16 v54, v2 offset:27184
	v_add_f32_e32 v6, 1.0, v6
	v_rcp_f32_e32 v6, v6
	s_nop 0
	v_mul_f32_e32 v5, v5, v6
	v_cvt_pk_bf16_f32 v2, v5, s0
	v_mov_b32_e32 v6, v210
	ds_write_b16 v54, v2 offset:27216
	s_waitcnt lgkmcnt(0)
	s_barrier
	s_nop 0
	v_lshlrev_b32_e32 v2, 4, v6
	v_and_b32_e32 v2, 0x1f0, v2
	v_lshl_add_u64 v[4:5], s[12:13], 0, v[2:3]

.LBB0_1906:
	v_add_u32_e32 v126, 0x210, v126
	v_lshl_add_u32 v115, v134, 1, v126
	v_cvt_pk_bf16_f32 v114, v121, v125
	ds_write_b16 v115, v114
	ds_write_b16_d16_hi v115, v114 offset:32
	v_cvt_pk_bf16_f32 v114, v120, v124
	ds_write_b16 v115, v114 offset:256
	v_or_b32_e32 v127, 16, v144
	ds_write_b16_d16_hi v115, v114 offset:288
	v_lshl_add_u32 v114, v127, 2, v220
	v_mov_b32_e32 v114, v216
	v_mov_b32_e32 v116, v110
	v_mov_b32_e32 v117, v102
	v_mov_b32_e32 v120, v106
	v_mov_b32_e32 v121, v102
	v_mov_b32_e32 v122, v106
	v_mov_b32_e32 v123, v98
	v_pk_mul_f32 v[118:119], v[116:117], v[114:115] op_sel_hi:[1,0]
	v_pk_mul_f32 v[116:117], v[120:121], v[114:115] op_sel_hi:[1,0]
	v_pk_mul_f32 v[120:121], v[122:123], v[114:115] op_sel_hi:[1,0]
	v_mov_b32_e32 v114, v118
	v_mov_b32_e32 v115, v121
	s_cmp_gt_i32 s7, 1
	s_mov_b64 s[10:11], -1
	s_cbranch_scc0 .LBB0_1908
	v_mul_f32_e32 v98, 0xbfb8aa3b, v121
	v_exp_f32_e32 v98, v98
	v_mul_f32_e32 v102, 0xbfb8aa3b, v117
	v_mul_f32_e32 v106, 0xbfb8aa3b, v116
	v_exp_f32_e32 v102, v102
	v_add_f32_e32 v98, 1.0, v98
	v_rcp_f32_e32 v123, v98
	v_mul_f32_e32 v98, 0xbfb8aa3b, v118
	v_exp_f32_e32 v98, v98
	v_exp_f32_e32 v106, v106
	v_add_f32_e32 v102, 1.0, v102
	v_rcp_f32_e32 v125, v102
	v_add_f32_e32 v98, 1.0, v98
	v_rcp_f32_e32 v122, v98
	v_add_f32_e32 v98, 1.0, v106
	v_rcp_f32_e32 v124, v98
	s_mov_b64 s[10:11], 0
	v_pk_mul_f32 v[122:123], v[114:115], v[122:123]
	v_pk_mul_f32 v[124:125], v[116:117], v[124:125]

.LBB0_1914:
	v_add_u32_e32 v118, 0x1ad0, v126
	v_lshl_add_u32 v102, v134, 1, v118
	v_cvt_pk_bf16_f32 v98, v123, v125
	ds_write_b16 v102, v98
	ds_write_b16_d16_hi v102, v98 offset:32
	v_cvt_pk_bf16_f32 v98, v122, v124
	ds_write_b16 v102, v98 offset:256
	v_or_b32_e32 v119, 17, v144
	ds_write_b16_d16_hi v102, v98 offset:288
	v_lshl_add_u32 v98, v119, 2, v220
	v_mov_b32_e32 v114, v217
	v_mov_b32_e32 v102, v111
	v_mov_b32_e32 v98, v107
	s_cmp_gt_i32 s7, 1
	s_mov_b64 s[10:11], -1
	v_pk_mul_f32 v[110:111], v[102:103], v[114:115] op_sel_hi:[1,0]
	v_mov_b32_e32 v102, v107
	v_pk_mul_f32 v[106:107], v[98:99], v[114:115] op_sel_hi:[1,0]
	v_pk_mul_f32 v[102:103], v[102:103], v[114:115] op_sel_hi:[1,0]
	v_mov_b32_e32 v98, v110
	v_mov_b32_e32 v99, v107
	s_cbranch_scc0 .LBB0_1916
	v_mul_f32_e32 v114, 0xbfb8aa3b, v107
	v_exp_f32_e32 v114, v114
	v_mul_f32_e32 v115, 0xbfb8aa3b, v103
	v_exp_f32_e32 v115, v115
	v_mul_f32_e32 v117, 0xbfb8aa3b, v102
	v_add_f32_e32 v114, 1.0, v114
	v_exp_f32_e32 v120, v117
	v_add_f32_e32 v116, 1.0, v115
	v_rcp_f32_e32 v115, v114
	v_mul_f32_e32 v114, 0xbfb8aa3b, v110
	v_exp_f32_e32 v114, v114
	v_rcp_f32_e32 v117, v116
	v_add_f32_e32 v116, 1.0, v120
	v_rcp_f32_e32 v116, v116
	v_add_f32_e32 v114, 1.0, v114
	v_rcp_f32_e32 v114, v114
	s_mov_b64 s[10:11], 0
	v_pk_mul_f32 v[116:117], v[102:103], v[116:117]
	v_pk_mul_f32 v[114:115], v[98:99], v[114:115]

.LBB0_1922:
	v_add_u32_e32 v118, 0x210, v118
	v_lshl_add_u32 v99, v134, 1, v118
	v_cvt_pk_bf16_f32 v98, v115, v117
	ds_write_b16 v99, v98
	ds_write_b16_d16_hi v99, v98 offset:32
	v_cvt_pk_bf16_f32 v98, v114, v116
	ds_write_b16 v99, v98 offset:256
	v_or_b32_e32 v119, 18, v144
	ds_write_b16_d16_hi v99, v98 offset:288
	v_lshl_add_u32 v98, v119, 2, v220
	v_mov_b32_e32 v98, v218
	v_mov_b32_e32 v102, v112
	v_mov_b32_e32 v103, v104
	v_mov_b32_e32 v110, v108
	v_mov_b32_e32 v111, v104
	v_mov_b32_e32 v114, v108
	v_mov_b32_e32 v115, v100
	v_pk_mul_f32 v[106:107], v[102:103], v[98:99] op_sel_hi:[1,0]
	v_pk_mul_f32 v[102:103], v[110:111], v[98:99] op_sel_hi:[1,0]
	v_pk_mul_f32 v[110:111], v[114:115], v[98:99] op_sel_hi:[1,0]
	v_mov_b32_e32 v98, v106
	v_mov_b32_e32 v99, v111
	s_cmp_gt_i32 s7, 1
	s_mov_b64 s[10:11], -1
	s_cbranch_scc0 .LBB0_1924
	v_mul_f32_e32 v100, 0xbfb8aa3b, v111
	v_exp_f32_e32 v100, v100
	v_mul_f32_e32 v104, 0xbfb8aa3b, v103
	v_mul_f32_e32 v108, 0xbfb8aa3b, v102
	v_exp_f32_e32 v104, v104
	v_add_f32_e32 v100, 1.0, v100
	v_rcp_f32_e32 v115, v100
	v_mul_f32_e32 v100, 0xbfb8aa3b, v106
	v_exp_f32_e32 v100, v100
	v_exp_f32_e32 v108, v108
	v_add_f32_e32 v104, 1.0, v104
	v_rcp_f32_e32 v117, v104
	v_add_f32_e32 v100, 1.0, v100
	v_rcp_f32_e32 v114, v100
	v_add_f32_e32 v100, 1.0, v108
	v_rcp_f32_e32 v116, v100
	s_mov_b64 s[10:11], 0
	v_pk_mul_f32 v[114:115], v[98:99], v[114:115]
	v_pk_mul_f32 v[116:117], v[102:103], v[116:117]

.LBB0_1930:
	v_add_u32_e32 v110, 0x210, v118
	v_lshl_add_u32 v99, v134, 1, v110
	v_cvt_pk_bf16_f32 v98, v115, v117
	ds_write_b16 v99, v98
	ds_write_b16_d16_hi v99, v98 offset:32
	v_cvt_pk_bf16_f32 v98, v114, v116
	ds_write_b16 v99, v98 offset:256
	v_or_b32_e32 v111, 19, v144
	ds_write_b16_d16_hi v99, v98 offset:288
	v_lshl_add_u32 v98, v111, 2, v220
	v_mov_b32_e32 v98, v219
	v_mov_b32_e32 v104, v113
	v_mov_b32_e32 v100, v109
	s_cmp_gt_i32 s7, 1
	s_mov_b64 s[10:11], -1
	v_pk_mul_f32 v[102:103], v[104:105], v[98:99] op_sel_hi:[1,0]
	v_mov_b32_e32 v104, v109
	v_pk_mul_f32 v[106:107], v[100:101], v[98:99] op_sel_hi:[1,0]
	v_pk_mul_f32 v[100:101], v[104:105], v[98:99] op_sel_hi:[1,0]
	v_mov_b32_e32 v98, v102
	v_mov_b32_e32 v99, v107
	s_cbranch_scc0 .LBB0_1932
	v_mul_f32_e32 v104, 0xbfb8aa3b, v107
	v_exp_f32_e32 v104, v104
	v_mul_f32_e32 v105, 0xbfb8aa3b, v101
	v_exp_f32_e32 v105, v105
	v_mul_f32_e32 v109, 0xbfb8aa3b, v100
	v_add_f32_e32 v104, 1.0, v104
	v_exp_f32_e32 v112, v109
	v_add_f32_e32 v108, 1.0, v105
	v_rcp_f32_e32 v105, v104
	v_mul_f32_e32 v104, 0xbfb8aa3b, v102
	v_exp_f32_e32 v104, v104
	v_rcp_f32_e32 v109, v108
	v_add_f32_e32 v108, 1.0, v112
	v_rcp_f32_e32 v108, v108
	v_add_f32_e32 v104, 1.0, v104
	v_rcp_f32_e32 v104, v104
	s_mov_b64 s[10:11], 0
	v_pk_mul_f32 v[108:109], v[100:101], v[108:109]
	v_pk_mul_f32 v[104:105], v[98:99], v[104:105]

.LBB0_1938:
	v_add_u32_e32 v110, 0x210, v110
	v_lshl_add_u32 v99, v134, 1, v110
	v_cvt_pk_bf16_f32 v98, v105, v109
	ds_write_b16 v99, v98
	ds_write_b16_d16_hi v99, v98 offset:32
	v_cvt_pk_bf16_f32 v98, v104, v108
	ds_write_b16 v99, v98 offset:256
	v_or_b32_e32 v111, 32, v144
	ds_write_b16_d16_hi v99, v98 offset:288
	v_lshl_add_u32 v98, v111, 2, v220
	v_mov_b32_e32 v98, v224
	v_mov_b32_e32 v100, v94
	v_mov_b32_e32 v101, v86
	v_mov_b32_e32 v104, v90
	v_mov_b32_e32 v105, v86
	v_mov_b32_e32 v106, v90
	v_mov_b32_e32 v107, v82
	v_pk_mul_f32 v[102:103], v[100:101], v[98:99] op_sel_hi:[1,0]
	v_pk_mul_f32 v[100:101], v[104:105], v[98:99] op_sel_hi:[1,0]
	v_pk_mul_f32 v[104:105], v[106:107], v[98:99] op_sel_hi:[1,0]
	v_mov_b32_e32 v98, v102
	v_mov_b32_e32 v99, v105
	s_cmp_gt_i32 s7, 1
	s_mov_b64 s[10:11], -1
	s_cbranch_scc0 .LBB0_1940
	v_mul_f32_e32 v82, 0xbfb8aa3b, v105
	v_exp_f32_e32 v82, v82
	v_mul_f32_e32 v86, 0xbfb8aa3b, v101
	v_mul_f32_e32 v90, 0xbfb8aa3b, v100
	v_exp_f32_e32 v86, v86
	v_add_f32_e32 v82, 1.0, v82
	v_rcp_f32_e32 v107, v82
	v_mul_f32_e32 v82, 0xbfb8aa3b, v102
	v_exp_f32_e32 v82, v82
	v_exp_f32_e32 v90, v90
	v_add_f32_e32 v86, 1.0, v86
	v_rcp_f32_e32 v109, v86
	v_add_f32_e32 v82, 1.0, v82
	v_rcp_f32_e32 v106, v82
	v_add_f32_e32 v82, 1.0, v90
	v_rcp_f32_e32 v108, v82
	s_mov_b64 s[10:11], 0
	v_pk_mul_f32 v[106:107], v[98:99], v[106:107]
	v_pk_mul_f32 v[108:109], v[100:101], v[108:109]

.LBB0_1946:
	v_add_u32_e32 v102, 0x1ad0, v110
	v_lshl_add_u32 v86, v134, 1, v102
	v_cvt_pk_bf16_f32 v82, v107, v109
	ds_write_b16 v86, v82
	ds_write_b16_d16_hi v86, v82 offset:32
	v_cvt_pk_bf16_f32 v82, v106, v108
	ds_write_b16 v86, v82 offset:256
	v_or_b32_e32 v103, 33, v144
	ds_write_b16_d16_hi v86, v82 offset:288
	v_lshl_add_u32 v82, v103, 2, v220
	v_mov_b32_e32 v98, v225
	v_mov_b32_e32 v86, v95
	v_mov_b32_e32 v82, v91
	s_cmp_gt_i32 s7, 1
	s_mov_b64 s[10:11], -1
	v_pk_mul_f32 v[94:95], v[86:87], v[98:99] op_sel_hi:[1,0]
	v_mov_b32_e32 v86, v91
	v_pk_mul_f32 v[90:91], v[82:83], v[98:99] op_sel_hi:[1,0]
	v_pk_mul_f32 v[86:87], v[86:87], v[98:99] op_sel_hi:[1,0]
	v_mov_b32_e32 v82, v94
	v_mov_b32_e32 v83, v91
	s_cbranch_scc0 .LBB0_1948
	v_mul_f32_e32 v98, 0xbfb8aa3b, v91
	v_exp_f32_e32 v98, v98
	v_mul_f32_e32 v99, 0xbfb8aa3b, v87
	v_exp_f32_e32 v99, v99
	v_mul_f32_e32 v101, 0xbfb8aa3b, v86
	v_add_f32_e32 v98, 1.0, v98
	v_exp_f32_e32 v104, v101
	v_add_f32_e32 v100, 1.0, v99
	v_rcp_f32_e32 v99, v98
	v_mul_f32_e32 v98, 0xbfb8aa3b, v94
	v_exp_f32_e32 v98, v98
	v_rcp_f32_e32 v101, v100
	v_add_f32_e32 v100, 1.0, v104
	v_rcp_f32_e32 v100, v100
	v_add_f32_e32 v98, 1.0, v98
	v_rcp_f32_e32 v98, v98
	s_mov_b64 s[10:11], 0
	v_pk_mul_f32 v[100:101], v[86:87], v[100:101]
	v_pk_mul_f32 v[98:99], v[82:83], v[98:99]

.LBB0_1954:
	v_add_u32_e32 v102, 0x210, v102
	v_lshl_add_u32 v83, v134, 1, v102
	v_cvt_pk_bf16_f32 v82, v99, v101
	ds_write_b16 v83, v82
	ds_write_b16_d16_hi v83, v82 offset:32
	v_cvt_pk_bf16_f32 v82, v98, v100
	ds_write_b16 v83, v82 offset:256
	v_or_b32_e32 v103, 34, v144
	ds_write_b16_d16_hi v83, v82 offset:288
	v_lshl_add_u32 v82, v103, 2, v220
	v_mov_b32_e32 v82, v226
	v_mov_b32_e32 v86, v96
	v_mov_b32_e32 v87, v88
	v_mov_b32_e32 v94, v92
	v_mov_b32_e32 v95, v88
	v_mov_b32_e32 v98, v92
	v_mov_b32_e32 v99, v84
	v_pk_mul_f32 v[90:91], v[86:87], v[82:83] op_sel_hi:[1,0]
	v_pk_mul_f32 v[86:87], v[94:95], v[82:83] op_sel_hi:[1,0]
	v_pk_mul_f32 v[94:95], v[98:99], v[82:83] op_sel_hi:[1,0]
	v_mov_b32_e32 v82, v90
	v_mov_b32_e32 v83, v95
	s_cmp_gt_i32 s7, 1
	s_mov_b64 s[10:11], -1
	s_cbranch_scc0 .LBB0_1956
	v_mul_f32_e32 v84, 0xbfb8aa3b, v95
	v_exp_f32_e32 v84, v84
	v_mul_f32_e32 v88, 0xbfb8aa3b, v87
	v_mul_f32_e32 v92, 0xbfb8aa3b, v86
	v_exp_f32_e32 v88, v88
	v_add_f32_e32 v84, 1.0, v84
	v_rcp_f32_e32 v99, v84
	v_mul_f32_e32 v84, 0xbfb8aa3b, v90
	v_exp_f32_e32 v84, v84
	v_exp_f32_e32 v92, v92
	v_add_f32_e32 v88, 1.0, v88
	v_rcp_f32_e32 v101, v88
	v_add_f32_e32 v84, 1.0, v84
	v_rcp_f32_e32 v98, v84
	v_add_f32_e32 v84, 1.0, v92
	v_rcp_f32_e32 v100, v84
	s_mov_b64 s[10:11], 0
	v_pk_mul_f32 v[98:99], v[82:83], v[98:99]
	v_pk_mul_f32 v[100:101], v[86:87], v[100:101]

.LBB0_1962:
	v_add_u32_e32 v94, 0x210, v102
	v_lshl_add_u32 v83, v134, 1, v94
	v_cvt_pk_bf16_f32 v82, v99, v101
	ds_write_b16 v83, v82
	ds_write_b16_d16_hi v83, v82 offset:32
	v_cvt_pk_bf16_f32 v82, v98, v100
	ds_write_b16 v83, v82 offset:256
	v_or_b32_e32 v95, 35, v144
	ds_write_b16_d16_hi v83, v82 offset:288
	v_lshl_add_u32 v82, v95, 2, v220
	v_mov_b32_e32 v82, v227
	v_mov_b32_e32 v88, v97
	v_mov_b32_e32 v84, v93
	s_cmp_gt_i32 s7, 1
	s_mov_b64 s[10:11], -1
	v_pk_mul_f32 v[86:87], v[88:89], v[82:83] op_sel_hi:[1,0]
	v_mov_b32_e32 v88, v93
	v_pk_mul_f32 v[90:91], v[84:85], v[82:83] op_sel_hi:[1,0]
	v_pk_mul_f32 v[84:85], v[88:89], v[82:83] op_sel_hi:[1,0]
	v_mov_b32_e32 v82, v86
	v_mov_b32_e32 v83, v91
	s_cbranch_scc0 .LBB0_1964
	v_mul_f32_e32 v88, 0xbfb8aa3b, v91
	v_exp_f32_e32 v88, v88
	v_mul_f32_e32 v89, 0xbfb8aa3b, v85
	v_exp_f32_e32 v89, v89
	v_mul_f32_e32 v93, 0xbfb8aa3b, v84
	v_add_f32_e32 v88, 1.0, v88
	v_exp_f32_e32 v96, v93
	v_add_f32_e32 v92, 1.0, v89
	v_rcp_f32_e32 v89, v88
	v_mul_f32_e32 v88, 0xbfb8aa3b, v86
	v_exp_f32_e32 v88, v88
	v_rcp_f32_e32 v93, v92
	v_add_f32_e32 v92, 1.0, v96
	v_rcp_f32_e32 v92, v92
	v_add_f32_e32 v88, 1.0, v88
	v_rcp_f32_e32 v88, v88
	s_mov_b64 s[10:11], 0
	v_pk_mul_f32 v[92:93], v[84:85], v[92:93]
	v_pk_mul_f32 v[88:89], v[82:83], v[88:89]

.LBB0_1970:
	v_add_u32_e32 v94, 0x210, v94
	v_lshl_add_u32 v83, v134, 1, v94
	v_cvt_pk_bf16_f32 v82, v89, v93
	ds_write_b16 v83, v82
	ds_write_b16_d16_hi v83, v82 offset:32
	v_cvt_pk_bf16_f32 v82, v88, v92
	ds_write_b16 v83, v82 offset:256
	v_or_b32_e32 v95, 48, v144
	ds_write_b16_d16_hi v83, v82 offset:288
	v_lshl_add_u32 v82, v95, 2, v220
	v_mov_b32_e32 v82, v228
	v_mov_b32_e32 v84, v78
	v_mov_b32_e32 v85, v70
	v_mov_b32_e32 v88, v74
	v_mov_b32_e32 v89, v70
	v_mov_b32_e32 v90, v74
	v_mov_b32_e32 v91, v66
	v_pk_mul_f32 v[86:87], v[84:85], v[82:83] op_sel_hi:[1,0]
	v_pk_mul_f32 v[84:85], v[88:89], v[82:83] op_sel_hi:[1,0]
	v_pk_mul_f32 v[88:89], v[90:91], v[82:83] op_sel_hi:[1,0]
	v_mov_b32_e32 v82, v86
	v_mov_b32_e32 v83, v89
	s_cmp_gt_i32 s7, 1
	s_mov_b64 s[10:11], -1
	s_cbranch_scc0 .LBB0_1972
	v_mul_f32_e32 v66, 0xbfb8aa3b, v89
	v_exp_f32_e32 v66, v66
	v_mul_f32_e32 v70, 0xbfb8aa3b, v85
	v_mul_f32_e32 v74, 0xbfb8aa3b, v84
	v_exp_f32_e32 v70, v70
	v_add_f32_e32 v66, 1.0, v66
	v_rcp_f32_e32 v91, v66
	v_mul_f32_e32 v66, 0xbfb8aa3b, v86
	v_exp_f32_e32 v66, v66
	v_exp_f32_e32 v74, v74
	v_add_f32_e32 v70, 1.0, v70
	v_rcp_f32_e32 v93, v70
	v_add_f32_e32 v66, 1.0, v66
	v_rcp_f32_e32 v90, v66
	v_add_f32_e32 v66, 1.0, v74
	v_rcp_f32_e32 v92, v66
	s_mov_b64 s[10:11], 0
	v_pk_mul_f32 v[90:91], v[82:83], v[90:91]
	v_pk_mul_f32 v[92:93], v[84:85], v[92:93]

.LBB0_1978:
	v_add_u32_e32 v86, 0x1ad0, v94
	v_lshl_add_u32 v70, v134, 1, v86
	v_cvt_pk_bf16_f32 v66, v91, v93
	ds_write_b16 v70, v66
	ds_write_b16_d16_hi v70, v66 offset:32
	v_cvt_pk_bf16_f32 v66, v90, v92
	ds_write_b16 v70, v66 offset:256
	v_or_b32_e32 v87, 49, v144
	ds_write_b16_d16_hi v70, v66 offset:288
	v_lshl_add_u32 v66, v87, 2, v220
	v_mov_b32_e32 v82, v229
	v_mov_b32_e32 v70, v79
	v_mov_b32_e32 v66, v75
	s_cmp_gt_i32 s7, 1
	s_mov_b64 s[10:11], -1
	v_pk_mul_f32 v[78:79], v[70:71], v[82:83] op_sel_hi:[1,0]
	v_mov_b32_e32 v70, v75
	v_pk_mul_f32 v[74:75], v[66:67], v[82:83] op_sel_hi:[1,0]
	v_pk_mul_f32 v[70:71], v[70:71], v[82:83] op_sel_hi:[1,0]
	v_mov_b32_e32 v66, v78
	v_mov_b32_e32 v67, v75
	s_cbranch_scc0 .LBB0_1980
	v_mul_f32_e32 v82, 0xbfb8aa3b, v75
	v_exp_f32_e32 v82, v82
	v_mul_f32_e32 v83, 0xbfb8aa3b, v71
	v_exp_f32_e32 v83, v83
	v_mul_f32_e32 v85, 0xbfb8aa3b, v70
	v_add_f32_e32 v82, 1.0, v82
	v_exp_f32_e32 v88, v85
	v_add_f32_e32 v84, 1.0, v83
	v_rcp_f32_e32 v83, v82
	v_mul_f32_e32 v82, 0xbfb8aa3b, v78
	v_exp_f32_e32 v82, v82
	v_rcp_f32_e32 v85, v84
	v_add_f32_e32 v84, 1.0, v88
	v_rcp_f32_e32 v84, v84
	v_add_f32_e32 v82, 1.0, v82
	v_rcp_f32_e32 v82, v82
	s_mov_b64 s[10:11], 0
	v_pk_mul_f32 v[84:85], v[70:71], v[84:85]
	v_pk_mul_f32 v[82:83], v[66:67], v[82:83]

.LBB0_1986:
	v_add_u32_e32 v86, 0x210, v86
	v_lshl_add_u32 v67, v134, 1, v86
	v_cvt_pk_bf16_f32 v66, v83, v85
	ds_write_b16 v67, v66
	ds_write_b16_d16_hi v67, v66 offset:32
	v_cvt_pk_bf16_f32 v66, v82, v84
	ds_write_b16 v67, v66 offset:256
	v_or_b32_e32 v87, 50, v144
	ds_write_b16_d16_hi v67, v66 offset:288
	v_lshl_add_u32 v66, v87, 2, v220
	v_mov_b32_e32 v66, v230
	v_mov_b32_e32 v70, v80
	v_mov_b32_e32 v71, v72
	v_mov_b32_e32 v78, v76
	v_mov_b32_e32 v79, v72
	v_mov_b32_e32 v82, v76
	v_mov_b32_e32 v83, v68
	v_pk_mul_f32 v[74:75], v[70:71], v[66:67] op_sel_hi:[1,0]
	v_pk_mul_f32 v[70:71], v[78:79], v[66:67] op_sel_hi:[1,0]
	v_pk_mul_f32 v[78:79], v[82:83], v[66:67] op_sel_hi:[1,0]
	v_mov_b32_e32 v66, v74
	v_mov_b32_e32 v67, v79
	s_cmp_gt_i32 s7, 1
	s_mov_b64 s[10:11], -1
	s_cbranch_scc0 .LBB0_1988
	v_mul_f32_e32 v68, 0xbfb8aa3b, v79
	v_exp_f32_e32 v68, v68
	v_mul_f32_e32 v72, 0xbfb8aa3b, v71
	v_mul_f32_e32 v76, 0xbfb8aa3b, v70
	v_exp_f32_e32 v72, v72
	v_add_f32_e32 v68, 1.0, v68
	v_rcp_f32_e32 v83, v68
	v_mul_f32_e32 v68, 0xbfb8aa3b, v74
	v_exp_f32_e32 v68, v68
	v_exp_f32_e32 v76, v76
	v_add_f32_e32 v72, 1.0, v72
	v_rcp_f32_e32 v85, v72
	v_add_f32_e32 v68, 1.0, v68
	v_rcp_f32_e32 v82, v68
	v_add_f32_e32 v68, 1.0, v76
	v_rcp_f32_e32 v84, v68
	s_mov_b64 s[10:11], 0
	v_pk_mul_f32 v[82:83], v[66:67], v[82:83]
	v_pk_mul_f32 v[84:85], v[70:71], v[84:85]

.LBB0_1994:
	v_add_u32_e32 v78, 0x210, v86
	v_lshl_add_u32 v67, v134, 1, v78
	v_cvt_pk_bf16_f32 v66, v83, v85
	ds_write_b16 v67, v66
	ds_write_b16_d16_hi v67, v66 offset:32
	v_cvt_pk_bf16_f32 v66, v82, v84
	ds_write_b16 v67, v66 offset:256
	v_or_b32_e32 v79, 51, v144
	ds_write_b16_d16_hi v67, v66 offset:288
	v_lshl_add_u32 v66, v79, 2, v220
	v_mov_b32_e32 v66, v231
	v_mov_b32_e32 v72, v81
	v_mov_b32_e32 v68, v77
	s_cmp_gt_i32 s7, 1
	s_mov_b64 s[10:11], -1
	v_pk_mul_f32 v[70:71], v[72:73], v[66:67] op_sel_hi:[1,0]
	v_mov_b32_e32 v72, v77
	v_pk_mul_f32 v[74:75], v[68:69], v[66:67] op_sel_hi:[1,0]
	v_pk_mul_f32 v[68:69], v[72:73], v[66:67] op_sel_hi:[1,0]
	v_mov_b32_e32 v66, v70
	v_mov_b32_e32 v67, v75
	s_cbranch_scc0 .LBB0_1996
	v_mul_f32_e32 v72, 0xbfb8aa3b, v75
	v_exp_f32_e32 v72, v72
	v_mul_f32_e32 v73, 0xbfb8aa3b, v69
	v_exp_f32_e32 v73, v73
	v_mul_f32_e32 v77, 0xbfb8aa3b, v68
	v_add_f32_e32 v72, 1.0, v72
	v_exp_f32_e32 v80, v77
	v_add_f32_e32 v76, 1.0, v73
	v_rcp_f32_e32 v73, v72
	v_mul_f32_e32 v72, 0xbfb8aa3b, v70
	v_exp_f32_e32 v72, v72
	v_rcp_f32_e32 v77, v76
	v_add_f32_e32 v76, 1.0, v80
	v_rcp_f32_e32 v76, v76
	v_add_f32_e32 v72, 1.0, v72
	v_rcp_f32_e32 v72, v72
	s_mov_b64 s[10:11], 0
	v_pk_mul_f32 v[76:77], v[68:69], v[76:77]
	v_pk_mul_f32 v[72:73], v[66:67], v[72:73]

.LBB0_2002:
	v_add_u32_e32 v78, 0x210, v78
	v_lshl_add_u32 v67, v134, 1, v78
	v_cvt_pk_bf16_f32 v66, v73, v77
	ds_write_b16 v67, v66
	ds_write_b16_d16_hi v67, v66 offset:32
	v_cvt_pk_bf16_f32 v66, v72, v76
	ds_write_b16 v67, v66 offset:256
	ds_write_b16_d16_hi v67, v66 offset:288
	v_mov_b32_e32 v66, v232
	v_mov_b32_e32 v68, v62
	v_mov_b32_e32 v69, v54
	v_mov_b32_e32 v72, v58
	v_mov_b32_e32 v73, v54
	v_mov_b32_e32 v74, v58
	v_mov_b32_e32 v75, v50
	v_pk_mul_f32 v[70:71], v[68:69], v[66:67] op_sel_hi:[1,0]
	v_pk_mul_f32 v[68:69], v[72:73], v[66:67] op_sel_hi:[1,0]
	v_pk_mul_f32 v[72:73], v[74:75], v[66:67] op_sel_hi:[1,0]
	v_mov_b32_e32 v66, v70
	v_mov_b32_e32 v67, v73
	s_cmp_gt_i32 s7, 1
	s_mov_b64 s[10:11], -1
	s_cbranch_scc0 .LBB0_2004
	v_mul_f32_e32 v50, 0xbfb8aa3b, v73
	v_exp_f32_e32 v50, v50
	v_mul_f32_e32 v54, 0xbfb8aa3b, v69
	v_mul_f32_e32 v58, 0xbfb8aa3b, v68
	v_exp_f32_e32 v54, v54
	v_add_f32_e32 v50, 1.0, v50
	v_rcp_f32_e32 v75, v50
	v_mul_f32_e32 v50, 0xbfb8aa3b, v70
	v_exp_f32_e32 v50, v50
	v_exp_f32_e32 v58, v58
	v_add_f32_e32 v54, 1.0, v54
	v_rcp_f32_e32 v77, v54
	v_add_f32_e32 v50, 1.0, v50
	v_rcp_f32_e32 v74, v50
	v_add_f32_e32 v50, 1.0, v58
	v_rcp_f32_e32 v76, v50
	s_mov_b64 s[10:11], 0
	v_pk_mul_f32 v[74:75], v[66:67], v[74:75]
	v_pk_mul_f32 v[76:77], v[68:69], v[76:77]

.LBB0_2010:
	v_add_u32_e32 v70, 0x9ed0, v78
	v_lshl_add_u32 v54, v134, 1, v70
	v_mov_b32_e32 v66, v233
	v_cvt_pk_bf16_f32 v50, v75, v77
	ds_write_b16 v54, v50
	ds_write_b16_d16_hi v54, v50 offset:32
	v_cvt_pk_bf16_f32 v50, v74, v76
	ds_write_b16 v54, v50 offset:256
	ds_write_b16_d16_hi v54, v50 offset:288
	v_mov_b32_e32 v54, v63
	v_mov_b32_e32 v50, v59
	v_pk_mul_f32 v[62:63], v[54:55], v[66:67] op_sel_hi:[1,0]
	v_mov_b32_e32 v54, v59
	v_pk_mul_f32 v[58:59], v[50:51], v[66:67] op_sel_hi:[1,0]
	v_pk_mul_f32 v[54:55], v[54:55], v[66:67] op_sel_hi:[1,0]
	v_mov_b32_e32 v50, v62
	v_mov_b32_e32 v51, v59
	s_cmp_gt_i32 s7, 1
	s_mov_b64 s[10:11], -1
	s_cbranch_scc0 .LBB0_2012
	v_mul_f32_e32 v66, 0xbfb8aa3b, v59
	v_exp_f32_e32 v66, v66
	v_mul_f32_e32 v67, 0xbfb8aa3b, v55
	v_exp_f32_e32 v67, v67
	v_mul_f32_e32 v69, 0xbfb8aa3b, v54
	v_add_f32_e32 v66, 1.0, v66
	v_exp_f32_e32 v71, v69
	v_add_f32_e32 v68, 1.0, v67
	v_rcp_f32_e32 v67, v66
	v_mul_f32_e32 v66, 0xbfb8aa3b, v62
	v_exp_f32_e32 v66, v66
	v_rcp_f32_e32 v69, v68
	v_add_f32_e32 v68, 1.0, v71
	v_rcp_f32_e32 v68, v68
	v_add_f32_e32 v66, 1.0, v66
	v_rcp_f32_e32 v66, v66
	s_mov_b64 s[10:11], 0
	v_pk_mul_f32 v[68:69], v[54:55], v[68:69]
	v_pk_mul_f32 v[66:67], v[50:51], v[66:67]

.LBB0_2018:
	v_add_u32_e32 v70, 0x210, v70
	v_lshl_add_u32 v51, v134, 1, v70
	v_cvt_pk_bf16_f32 v50, v67, v69
	ds_write_b16 v51, v50
	ds_write_b16_d16_hi v51, v50 offset:32
	v_cvt_pk_bf16_f32 v50, v66, v68
	ds_write_b16 v51, v50 offset:256
	ds_write_b16_d16_hi v51, v50 offset:288
	v_mov_b32_e32 v50, v234
	v_mov_b32_e32 v54, v64
	v_mov_b32_e32 v55, v56
	v_mov_b32_e32 v62, v60
	v_mov_b32_e32 v63, v56
	v_mov_b32_e32 v66, v60
	v_mov_b32_e32 v67, v52
	v_pk_mul_f32 v[58:59], v[54:55], v[50:51] op_sel_hi:[1,0]
	v_pk_mul_f32 v[54:55], v[62:63], v[50:51] op_sel_hi:[1,0]
	v_pk_mul_f32 v[62:63], v[66:67], v[50:51] op_sel_hi:[1,0]
	v_mov_b32_e32 v50, v58
	v_mov_b32_e32 v51, v63
	s_cmp_gt_i32 s7, 1
	s_mov_b64 s[10:11], -1
	s_cbranch_scc0 .LBB0_2020
	v_mul_f32_e32 v52, 0xbfb8aa3b, v63
	v_exp_f32_e32 v52, v52
	v_mul_f32_e32 v56, 0xbfb8aa3b, v55
	v_mul_f32_e32 v60, 0xbfb8aa3b, v54
	v_exp_f32_e32 v56, v56
	v_add_f32_e32 v52, 1.0, v52
	v_rcp_f32_e32 v67, v52
	v_mul_f32_e32 v52, 0xbfb8aa3b, v58
	v_exp_f32_e32 v52, v52
	v_exp_f32_e32 v60, v60
	v_add_f32_e32 v56, 1.0, v56
	v_rcp_f32_e32 v69, v56
	v_add_f32_e32 v52, 1.0, v52
	v_rcp_f32_e32 v66, v52
	v_add_f32_e32 v52, 1.0, v60
	v_rcp_f32_e32 v68, v52
	s_mov_b64 s[10:11], 0
	v_pk_mul_f32 v[66:67], v[50:51], v[66:67]
	v_pk_mul_f32 v[68:69], v[54:55], v[68:69]

.LBB0_2026:
	v_add_u32_e32 v62, 0x210, v70
	v_lshl_add_u32 v51, v134, 1, v62
	v_cvt_pk_bf16_f32 v50, v67, v69
	ds_write_b16 v51, v50
	ds_write_b16_d16_hi v51, v50 offset:32
	v_cvt_pk_bf16_f32 v50, v66, v68
	ds_write_b16 v51, v50 offset:256
	ds_write_b16_d16_hi v51, v50 offset:288
	v_mov_b32_e32 v50, v235
	v_mov_b32_e32 v56, v65
	v_mov_b32_e32 v52, v61
	s_cmp_gt_i32 s7, 1
	s_mov_b64 s[10:11], -1
	v_pk_mul_f32 v[54:55], v[56:57], v[50:51] op_sel_hi:[1,0]
	v_mov_b32_e32 v56, v61
	v_pk_mul_f32 v[58:59], v[52:53], v[50:51] op_sel_hi:[1,0]
	v_pk_mul_f32 v[52:53], v[56:57], v[50:51] op_sel_hi:[1,0]
	v_mov_b32_e32 v50, v54
	v_mov_b32_e32 v51, v59
	s_cbranch_scc0 .LBB0_2028
	v_mul_f32_e32 v56, 0xbfb8aa3b, v59
	v_exp_f32_e32 v56, v56
	v_mul_f32_e32 v57, 0xbfb8aa3b, v53
	v_exp_f32_e32 v57, v57
	v_mul_f32_e32 v61, 0xbfb8aa3b, v52
	v_add_f32_e32 v56, 1.0, v56
	v_exp_f32_e32 v63, v61
	v_add_f32_e32 v60, 1.0, v57
	v_rcp_f32_e32 v57, v56
	v_mul_f32_e32 v56, 0xbfb8aa3b, v54
	v_exp_f32_e32 v56, v56
	v_rcp_f32_e32 v61, v60
	v_add_f32_e32 v60, 1.0, v63
	v_rcp_f32_e32 v60, v60
	v_add_f32_e32 v56, 1.0, v56
	v_rcp_f32_e32 v56, v56
	s_mov_b64 s[10:11], 0
	v_pk_mul_f32 v[60:61], v[52:53], v[60:61]
	v_pk_mul_f32 v[56:57], v[50:51], v[56:57]

.LBB0_2034:
	v_add_u32_e32 v62, 0x210, v62
	v_lshl_add_u32 v51, v134, 1, v62
	v_cvt_pk_bf16_f32 v50, v57, v61
	ds_write_b16 v51, v50
	ds_write_b16_d16_hi v51, v50 offset:32
	v_cvt_pk_bf16_f32 v50, v56, v60
	ds_write_b16 v51, v50 offset:256
	ds_write_b16_d16_hi v51, v50 offset:288
	v_mov_b32_e32 v50, v236
	v_mov_b32_e32 v52, v46
	v_mov_b32_e32 v53, v38
	v_mov_b32_e32 v56, v42
	v_mov_b32_e32 v57, v38
	v_mov_b32_e32 v58, v42
	v_mov_b32_e32 v59, v34
	v_pk_mul_f32 v[54:55], v[52:53], v[50:51] op_sel_hi:[1,0]
	v_pk_mul_f32 v[52:53], v[56:57], v[50:51] op_sel_hi:[1,0]
	v_pk_mul_f32 v[56:57], v[58:59], v[50:51] op_sel_hi:[1,0]
	v_mov_b32_e32 v50, v54
	v_mov_b32_e32 v51, v57
	s_cmp_gt_i32 s7, 1
	s_mov_b64 s[10:11], -1
	s_cbranch_scc0 .LBB0_2036
	v_mul_f32_e32 v34, 0xbfb8aa3b, v57
	v_exp_f32_e32 v34, v34
	v_mul_f32_e32 v38, 0xbfb8aa3b, v53
	v_mul_f32_e32 v42, 0xbfb8aa3b, v52
	v_exp_f32_e32 v38, v38
	v_add_f32_e32 v34, 1.0, v34
	v_rcp_f32_e32 v59, v34
	v_mul_f32_e32 v34, 0xbfb8aa3b, v54
	v_exp_f32_e32 v34, v34
	v_exp_f32_e32 v42, v42
	v_add_f32_e32 v38, 1.0, v38
	v_rcp_f32_e32 v61, v38
	v_add_f32_e32 v34, 1.0, v34
	v_rcp_f32_e32 v58, v34
	v_add_f32_e32 v34, 1.0, v42
	v_rcp_f32_e32 v60, v34
	s_mov_b64 s[10:11], 0
	v_pk_mul_f32 v[58:59], v[50:51], v[58:59]
	v_pk_mul_f32 v[60:61], v[52:53], v[60:61]

.LBB0_2042:
	v_add_u32_e32 v54, 0x1ad0, v62
	v_lshl_add_u32 v38, v134, 1, v54
	v_mov_b32_e32 v50, v237
	v_cvt_pk_bf16_f32 v34, v59, v61
	ds_write_b16 v38, v34
	ds_write_b16_d16_hi v38, v34 offset:32
	v_cvt_pk_bf16_f32 v34, v58, v60
	ds_write_b16 v38, v34 offset:256
	ds_write_b16_d16_hi v38, v34 offset:288
	v_mov_b32_e32 v38, v47
	v_mov_b32_e32 v34, v43
	v_pk_mul_f32 v[46:47], v[38:39], v[50:51] op_sel_hi:[1,0]
	v_mov_b32_e32 v38, v43
	v_pk_mul_f32 v[42:43], v[34:35], v[50:51] op_sel_hi:[1,0]
	v_pk_mul_f32 v[38:39], v[38:39], v[50:51] op_sel_hi:[1,0]
	v_mov_b32_e32 v34, v46
	v_mov_b32_e32 v35, v43
	s_cmp_gt_i32 s7, 1
	s_mov_b64 s[10:11], -1
	s_cbranch_scc0 .LBB0_2044
	v_mul_f32_e32 v50, 0xbfb8aa3b, v43
	v_exp_f32_e32 v50, v50
	v_mul_f32_e32 v51, 0xbfb8aa3b, v39
	v_exp_f32_e32 v51, v51
	v_mul_f32_e32 v53, 0xbfb8aa3b, v38
	v_add_f32_e32 v50, 1.0, v50
	v_exp_f32_e32 v55, v53
	v_add_f32_e32 v52, 1.0, v51
	v_rcp_f32_e32 v51, v50
	v_mul_f32_e32 v50, 0xbfb8aa3b, v46
	v_exp_f32_e32 v50, v50
	v_rcp_f32_e32 v53, v52
	v_add_f32_e32 v52, 1.0, v55
	v_rcp_f32_e32 v52, v52
	v_add_f32_e32 v50, 1.0, v50
	v_rcp_f32_e32 v50, v50
	s_mov_b64 s[10:11], 0
	v_pk_mul_f32 v[52:53], v[38:39], v[52:53]
	v_pk_mul_f32 v[50:51], v[34:35], v[50:51]

.LBB0_2050:
	v_add_u32_e32 v54, 0x210, v54
	v_lshl_add_u32 v35, v134, 1, v54
	v_cvt_pk_bf16_f32 v34, v51, v53
	ds_write_b16 v35, v34
	ds_write_b16_d16_hi v35, v34 offset:32
	v_cvt_pk_bf16_f32 v34, v50, v52
	ds_write_b16 v35, v34 offset:256
	ds_write_b16_d16_hi v35, v34 offset:288
	v_mov_b32_e32 v34, v238
	v_mov_b32_e32 v38, v48
	v_mov_b32_e32 v39, v40
	v_mov_b32_e32 v46, v44
	v_mov_b32_e32 v47, v40
	v_mov_b32_e32 v50, v44
	v_mov_b32_e32 v51, v36
	v_pk_mul_f32 v[42:43], v[38:39], v[34:35] op_sel_hi:[1,0]
	v_pk_mul_f32 v[38:39], v[46:47], v[34:35] op_sel_hi:[1,0]
	v_pk_mul_f32 v[46:47], v[50:51], v[34:35] op_sel_hi:[1,0]
	v_mov_b32_e32 v34, v42
	v_mov_b32_e32 v35, v47
	s_cmp_gt_i32 s7, 1
	s_mov_b64 s[10:11], -1
	s_cbranch_scc0 .LBB0_2052
	v_mul_f32_e32 v36, 0xbfb8aa3b, v47
	v_exp_f32_e32 v36, v36
	v_mul_f32_e32 v40, 0xbfb8aa3b, v39
	v_mul_f32_e32 v44, 0xbfb8aa3b, v38
	v_exp_f32_e32 v40, v40
	v_add_f32_e32 v36, 1.0, v36
	v_rcp_f32_e32 v51, v36
	v_mul_f32_e32 v36, 0xbfb8aa3b, v42
	v_exp_f32_e32 v36, v36
	v_exp_f32_e32 v44, v44
	v_add_f32_e32 v40, 1.0, v40
	v_rcp_f32_e32 v53, v40
	v_add_f32_e32 v36, 1.0, v36
	v_rcp_f32_e32 v50, v36
	v_add_f32_e32 v36, 1.0, v44
	v_rcp_f32_e32 v52, v36
	s_mov_b64 s[10:11], 0
	v_pk_mul_f32 v[50:51], v[34:35], v[50:51]
	v_pk_mul_f32 v[52:53], v[38:39], v[52:53]

.LBB0_2058:
	v_add_u32_e32 v46, 0x210, v54
	v_lshl_add_u32 v35, v134, 1, v46
	v_cvt_pk_bf16_f32 v34, v51, v53
	ds_write_b16 v35, v34
	ds_write_b16_d16_hi v35, v34 offset:32
	v_cvt_pk_bf16_f32 v34, v50, v52
	ds_write_b16 v35, v34 offset:256
	ds_write_b16_d16_hi v35, v34 offset:288
	v_mov_b32_e32 v34, v239
	v_mov_b32_e32 v40, v49
	v_mov_b32_e32 v36, v45
	s_cmp_gt_i32 s7, 1
	s_mov_b64 s[10:11], -1
	v_pk_mul_f32 v[38:39], v[40:41], v[34:35] op_sel_hi:[1,0]
	v_mov_b32_e32 v40, v45
	v_pk_mul_f32 v[42:43], v[36:37], v[34:35] op_sel_hi:[1,0]
	v_pk_mul_f32 v[36:37], v[40:41], v[34:35] op_sel_hi:[1,0]
	v_mov_b32_e32 v34, v38
	v_mov_b32_e32 v35, v43
	s_cbranch_scc0 .LBB0_2060
	v_mul_f32_e32 v40, 0xbfb8aa3b, v43
	v_exp_f32_e32 v40, v40
	v_mul_f32_e32 v41, 0xbfb8aa3b, v37
	v_exp_f32_e32 v41, v41
	v_mul_f32_e32 v45, 0xbfb8aa3b, v36
	v_add_f32_e32 v40, 1.0, v40
	v_exp_f32_e32 v47, v45
	v_add_f32_e32 v44, 1.0, v41
	v_rcp_f32_e32 v41, v40
	v_mul_f32_e32 v40, 0xbfb8aa3b, v38
	v_exp_f32_e32 v40, v40
	v_rcp_f32_e32 v45, v44
	v_add_f32_e32 v44, 1.0, v47
	v_rcp_f32_e32 v44, v44
	v_add_f32_e32 v40, 1.0, v40
	v_rcp_f32_e32 v40, v40
	s_mov_b64 s[10:11], 0
	v_pk_mul_f32 v[44:45], v[36:37], v[44:45]
	v_pk_mul_f32 v[40:41], v[34:35], v[40:41]

.LBB0_2066:
	v_add_u32_e32 v46, 0x210, v46
	v_lshl_add_u32 v35, v134, 1, v46
	v_cvt_pk_bf16_f32 v34, v41, v45
	ds_write_b16 v35, v34
	ds_write_b16_d16_hi v35, v34 offset:32
	v_cvt_pk_bf16_f32 v34, v40, v44
	ds_write_b16 v35, v34 offset:256
	ds_write_b16_d16_hi v35, v34 offset:288
	v_mov_b32_e32 v34, v240
	v_mov_b32_e32 v36, v30
	v_mov_b32_e32 v37, v22
	v_mov_b32_e32 v40, v26
	v_mov_b32_e32 v41, v22
	v_mov_b32_e32 v42, v26
	v_mov_b32_e32 v43, v18
	v_pk_mul_f32 v[38:39], v[36:37], v[34:35] op_sel_hi:[1,0]
	v_pk_mul_f32 v[36:37], v[40:41], v[34:35] op_sel_hi:[1,0]
	v_pk_mul_f32 v[40:41], v[42:43], v[34:35] op_sel_hi:[1,0]
	v_mov_b32_e32 v34, v38
	v_mov_b32_e32 v35, v41
	s_cmp_gt_i32 s7, 1
	s_mov_b64 s[10:11], -1
	s_cbranch_scc0 .LBB0_2068
	v_mul_f32_e32 v18, 0xbfb8aa3b, v41
	v_exp_f32_e32 v18, v18
	v_mul_f32_e32 v22, 0xbfb8aa3b, v37
	v_mul_f32_e32 v26, 0xbfb8aa3b, v36
	v_exp_f32_e32 v22, v22
	v_add_f32_e32 v18, 1.0, v18
	v_rcp_f32_e32 v43, v18
	v_mul_f32_e32 v18, 0xbfb8aa3b, v38
	v_exp_f32_e32 v18, v18
	v_exp_f32_e32 v26, v26
	v_add_f32_e32 v22, 1.0, v22
	v_rcp_f32_e32 v45, v22
	v_add_f32_e32 v18, 1.0, v18
	v_rcp_f32_e32 v42, v18
	v_add_f32_e32 v18, 1.0, v26
	v_rcp_f32_e32 v44, v18
	s_mov_b64 s[10:11], 0
	v_pk_mul_f32 v[42:43], v[34:35], v[42:43]
	v_pk_mul_f32 v[44:45], v[36:37], v[44:45]

.LBB0_2074:
	v_add_u32_e32 v38, 0x1ad0, v46
	v_lshl_add_u32 v22, v134, 1, v38
	v_mov_b32_e32 v34, v241
	v_cvt_pk_bf16_f32 v18, v43, v45
	ds_write_b16 v22, v18
	ds_write_b16_d16_hi v22, v18 offset:32
	v_cvt_pk_bf16_f32 v18, v42, v44
	ds_write_b16 v22, v18 offset:256
	ds_write_b16_d16_hi v22, v18 offset:288
	v_mov_b32_e32 v22, v31
	v_mov_b32_e32 v18, v27
	v_pk_mul_f32 v[30:31], v[22:23], v[34:35] op_sel_hi:[1,0]
	v_mov_b32_e32 v22, v27
	v_pk_mul_f32 v[26:27], v[18:19], v[34:35] op_sel_hi:[1,0]
	v_pk_mul_f32 v[22:23], v[22:23], v[34:35] op_sel_hi:[1,0]
	v_mov_b32_e32 v18, v30
	v_mov_b32_e32 v19, v27
	s_cmp_gt_i32 s7, 1
	s_mov_b64 s[10:11], -1
	s_cbranch_scc0 .LBB0_2076
	v_mul_f32_e32 v34, 0xbfb8aa3b, v27
	v_exp_f32_e32 v34, v34
	v_mul_f32_e32 v35, 0xbfb8aa3b, v23
	v_exp_f32_e32 v35, v35
	v_mul_f32_e32 v37, 0xbfb8aa3b, v22
	v_add_f32_e32 v34, 1.0, v34
	v_exp_f32_e32 v39, v37
	v_add_f32_e32 v36, 1.0, v35
	v_rcp_f32_e32 v35, v34
	v_mul_f32_e32 v34, 0xbfb8aa3b, v30
	v_exp_f32_e32 v34, v34
	v_rcp_f32_e32 v37, v36
	v_add_f32_e32 v36, 1.0, v39
	v_rcp_f32_e32 v36, v36
	v_add_f32_e32 v34, 1.0, v34
	v_rcp_f32_e32 v34, v34
	s_mov_b64 s[10:11], 0
	v_pk_mul_f32 v[36:37], v[22:23], v[36:37]
	v_pk_mul_f32 v[34:35], v[18:19], v[34:35]

.LBB0_2082:
	v_add_u32_e32 v38, 0x210, v38
	v_lshl_add_u32 v19, v134, 1, v38
	v_cvt_pk_bf16_f32 v18, v35, v37
	ds_write_b16 v19, v18
	ds_write_b16_d16_hi v19, v18 offset:32
	v_cvt_pk_bf16_f32 v18, v34, v36
	ds_write_b16 v19, v18 offset:256
	ds_write_b16_d16_hi v19, v18 offset:288
	v_mov_b32_e32 v18, v242
	v_mov_b32_e32 v22, v32
	v_mov_b32_e32 v23, v24
	v_mov_b32_e32 v30, v28
	v_mov_b32_e32 v31, v24
	v_mov_b32_e32 v34, v28
	v_mov_b32_e32 v35, v20
	v_pk_mul_f32 v[26:27], v[22:23], v[18:19] op_sel_hi:[1,0]
	v_pk_mul_f32 v[22:23], v[30:31], v[18:19] op_sel_hi:[1,0]
	v_pk_mul_f32 v[30:31], v[34:35], v[18:19] op_sel_hi:[1,0]
	v_mov_b32_e32 v18, v26
	v_mov_b32_e32 v19, v31
	s_cmp_gt_i32 s7, 1
	s_mov_b64 s[10:11], -1
	s_cbranch_scc0 .LBB0_2084
	v_mul_f32_e32 v20, 0xbfb8aa3b, v31
	v_exp_f32_e32 v20, v20
	v_mul_f32_e32 v24, 0xbfb8aa3b, v23
	v_mul_f32_e32 v28, 0xbfb8aa3b, v22
	v_exp_f32_e32 v24, v24
	v_add_f32_e32 v20, 1.0, v20
	v_rcp_f32_e32 v35, v20
	v_mul_f32_e32 v20, 0xbfb8aa3b, v26
	v_exp_f32_e32 v20, v20
	v_exp_f32_e32 v28, v28
	v_add_f32_e32 v24, 1.0, v24
	v_rcp_f32_e32 v37, v24
	v_add_f32_e32 v20, 1.0, v20
	v_rcp_f32_e32 v34, v20
	v_add_f32_e32 v20, 1.0, v28
	v_rcp_f32_e32 v36, v20
	s_mov_b64 s[10:11], 0
	v_pk_mul_f32 v[34:35], v[18:19], v[34:35]
	v_pk_mul_f32 v[36:37], v[22:23], v[36:37]

.LBB0_2090:
	v_add_u32_e32 v30, 0x210, v38
	v_lshl_add_u32 v19, v134, 1, v30
	v_cvt_pk_bf16_f32 v18, v35, v37
	ds_write_b16 v19, v18
	ds_write_b16_d16_hi v19, v18 offset:32
	v_cvt_pk_bf16_f32 v18, v34, v36
	ds_write_b16 v19, v18 offset:256
	ds_write_b16_d16_hi v19, v18 offset:288
	v_mov_b32_e32 v18, v243
	v_mov_b32_e32 v24, v33
	v_mov_b32_e32 v20, v29
	s_cmp_gt_i32 s7, 1
	s_mov_b64 s[10:11], -1
	v_pk_mul_f32 v[22:23], v[24:25], v[18:19] op_sel_hi:[1,0]
	v_mov_b32_e32 v24, v29
	v_pk_mul_f32 v[26:27], v[20:21], v[18:19] op_sel_hi:[1,0]
	v_pk_mul_f32 v[20:21], v[24:25], v[18:19] op_sel_hi:[1,0]
	v_mov_b32_e32 v18, v22
	v_mov_b32_e32 v19, v27
	s_cbranch_scc0 .LBB0_2092
	v_mul_f32_e32 v24, 0xbfb8aa3b, v27
	v_exp_f32_e32 v24, v24
	v_mul_f32_e32 v25, 0xbfb8aa3b, v21
	v_exp_f32_e32 v25, v25
	v_mul_f32_e32 v29, 0xbfb8aa3b, v20
	v_add_f32_e32 v24, 1.0, v24
	v_exp_f32_e32 v31, v29
	v_add_f32_e32 v28, 1.0, v25
	v_rcp_f32_e32 v25, v24
	v_mul_f32_e32 v24, 0xbfb8aa3b, v22
	v_exp_f32_e32 v24, v24
	v_rcp_f32_e32 v29, v28
	v_add_f32_e32 v28, 1.0, v31
	v_rcp_f32_e32 v28, v28
	v_add_f32_e32 v24, 1.0, v24
	v_rcp_f32_e32 v24, v24
	s_mov_b64 s[10:11], 0
	v_pk_mul_f32 v[28:29], v[20:21], v[28:29]
	v_pk_mul_f32 v[24:25], v[18:19], v[24:25]

.LBB0_2098:
	v_add_u32_e32 v30, 0x210, v30
	v_lshl_add_u32 v19, v134, 1, v30
	v_cvt_pk_bf16_f32 v18, v25, v29
	ds_write_b16 v19, v18
	ds_write_b16_d16_hi v19, v18 offset:32
	v_cvt_pk_bf16_f32 v18, v24, v28
	ds_write_b16 v19, v18 offset:256
	ds_write_b16_d16_hi v19, v18 offset:288
	v_mov_b32_e32 v18, v244
	v_mov_b32_e32 v20, v14
	v_mov_b32_e32 v21, v6
	v_mov_b32_e32 v24, v10
	v_mov_b32_e32 v25, v6
	v_mov_b32_e32 v26, v10
	v_mov_b32_e32 v27, v2
	v_pk_mul_f32 v[22:23], v[20:21], v[18:19] op_sel_hi:[1,0]
	v_pk_mul_f32 v[20:21], v[24:25], v[18:19] op_sel_hi:[1,0]
	v_pk_mul_f32 v[24:25], v[26:27], v[18:19] op_sel_hi:[1,0]
	v_mov_b32_e32 v18, v22
	v_mov_b32_e32 v19, v25
	s_cmp_gt_i32 s7, 1
	s_mov_b64 s[10:11], -1
	s_cbranch_scc0 .LBB0_2100
	v_mul_f32_e32 v2, 0xbfb8aa3b, v25
	v_exp_f32_e32 v2, v2
	v_mul_f32_e32 v6, 0xbfb8aa3b, v21
	v_mul_f32_e32 v10, 0xbfb8aa3b, v20
	v_exp_f32_e32 v6, v6
	v_add_f32_e32 v2, 1.0, v2
	v_rcp_f32_e32 v27, v2
	v_mul_f32_e32 v2, 0xbfb8aa3b, v22
	v_exp_f32_e32 v2, v2
	v_exp_f32_e32 v10, v10
	v_add_f32_e32 v6, 1.0, v6
	v_rcp_f32_e32 v29, v6
	v_add_f32_e32 v2, 1.0, v2
	v_rcp_f32_e32 v26, v2
	v_add_f32_e32 v2, 1.0, v10
	v_rcp_f32_e32 v28, v2
	s_mov_b64 s[10:11], 0
	v_pk_mul_f32 v[26:27], v[18:19], v[26:27]
	v_pk_mul_f32 v[28:29], v[20:21], v[28:29]

.LBB0_2106:
	v_add_u32_e32 v22, 0x1ad0, v30
	v_lshl_add_u32 v6, v134, 1, v22
	v_mov_b32_e32 v18, v245
	v_cvt_pk_bf16_f32 v2, v27, v29
	ds_write_b16 v6, v2
	ds_write_b16_d16_hi v6, v2 offset:32
	v_cvt_pk_bf16_f32 v2, v26, v28
	ds_write_b16 v6, v2 offset:256
	ds_write_b16_d16_hi v6, v2 offset:288
	v_mov_b32_e32 v6, v15
	v_mov_b32_e32 v2, v11
	v_pk_mul_f32 v[14:15], v[6:7], v[18:19] op_sel_hi:[1,0]
	v_mov_b32_e32 v6, v11
	v_pk_mul_f32 v[10:11], v[2:3], v[18:19] op_sel_hi:[1,0]
	v_pk_mul_f32 v[6:7], v[6:7], v[18:19] op_sel_hi:[1,0]
	v_mov_b32_e32 v2, v14
	v_mov_b32_e32 v3, v11
	s_cmp_gt_i32 s7, 1
	s_mov_b64 s[10:11], -1
	s_cbranch_scc0 .LBB0_2108
	v_mul_f32_e32 v18, 0xbfb8aa3b, v11
	v_exp_f32_e32 v18, v18
	v_mul_f32_e32 v19, 0xbfb8aa3b, v7
	v_exp_f32_e32 v19, v19
	v_mul_f32_e32 v21, 0xbfb8aa3b, v6
	v_add_f32_e32 v18, 1.0, v18
	v_exp_f32_e32 v23, v21
	v_add_f32_e32 v20, 1.0, v19
	v_rcp_f32_e32 v19, v18
	v_mul_f32_e32 v18, 0xbfb8aa3b, v14
	v_exp_f32_e32 v18, v18
	v_rcp_f32_e32 v21, v20
	v_add_f32_e32 v20, 1.0, v23
	v_rcp_f32_e32 v20, v20
	v_add_f32_e32 v18, 1.0, v18
	v_rcp_f32_e32 v18, v18
	s_mov_b64 s[10:11], 0
	v_pk_mul_f32 v[20:21], v[6:7], v[20:21]
	v_pk_mul_f32 v[18:19], v[2:3], v[18:19]

.LBB0_2114:
	v_add_u32_e32 v22, 0x210, v22
	v_lshl_add_u32 v3, v134, 1, v22
	v_cvt_pk_bf16_f32 v2, v19, v21
	ds_write_b16 v3, v2
	ds_write_b16_d16_hi v3, v2 offset:32
	v_cvt_pk_bf16_f32 v2, v18, v20
	ds_write_b16 v3, v2 offset:256
	ds_write_b16_d16_hi v3, v2 offset:288
	v_mov_b32_e32 v2, v246
	v_mov_b32_e32 v6, v16
	v_mov_b32_e32 v7, v8
	v_mov_b32_e32 v14, v12
	v_mov_b32_e32 v15, v8
	v_mov_b32_e32 v18, v12
	v_mov_b32_e32 v19, v4
	v_pk_mul_f32 v[10:11], v[6:7], v[2:3] op_sel_hi:[1,0]
	v_pk_mul_f32 v[6:7], v[14:15], v[2:3] op_sel_hi:[1,0]
	v_pk_mul_f32 v[14:15], v[18:19], v[2:3] op_sel_hi:[1,0]
	v_mov_b32_e32 v2, v10
	v_mov_b32_e32 v3, v15
	s_cmp_gt_i32 s7, 1
	s_mov_b64 s[10:11], -1
	s_cbranch_scc0 .LBB0_2116
	v_mul_f32_e32 v4, 0xbfb8aa3b, v15
	v_exp_f32_e32 v4, v4
	v_mul_f32_e32 v8, 0xbfb8aa3b, v7
	v_mul_f32_e32 v12, 0xbfb8aa3b, v6
	v_exp_f32_e32 v8, v8
	v_add_f32_e32 v4, 1.0, v4
	v_rcp_f32_e32 v19, v4
	v_mul_f32_e32 v4, 0xbfb8aa3b, v10
	v_exp_f32_e32 v4, v4
	v_exp_f32_e32 v12, v12
	v_add_f32_e32 v8, 1.0, v8
	v_rcp_f32_e32 v21, v8
	v_add_f32_e32 v4, 1.0, v4
	v_rcp_f32_e32 v18, v4
	v_add_f32_e32 v4, 1.0, v12
	v_rcp_f32_e32 v20, v4
	s_mov_b64 s[10:11], 0
	v_pk_mul_f32 v[18:19], v[2:3], v[18:19]
	v_pk_mul_f32 v[20:21], v[6:7], v[20:21]

.LBB0_2122:
	v_add_u32_e32 v3, 0x210, v22
	v_lshl_add_u32 v14, v134, 1, v3
	v_cvt_pk_bf16_f32 v2, v19, v21
	ds_write_b16 v14, v2
	ds_write_b16_d16_hi v14, v2 offset:32
	v_cvt_pk_bf16_f32 v2, v18, v20
	ds_write_b16 v14, v2 offset:256
	ds_write_b16_d16_hi v14, v2 offset:288
	v_mov_b32_e32 v2, v247
	v_mov_b32_e32 v8, v17
	v_mov_b32_e32 v4, v13
	s_cmp_gt_i32 s7, 1
	s_mov_b64 s[10:11], -1
	v_pk_mul_f32 v[6:7], v[8:9], v[2:3] op_sel_hi:[1,0]
	v_mov_b32_e32 v8, v13
	v_pk_mul_f32 v[10:11], v[4:5], v[2:3] op_sel_hi:[1,0]
	v_pk_mul_f32 v[4:5], v[8:9], v[2:3] op_sel_hi:[1,0]
	v_mov_b32_e32 v2, v6
	v_mov_b32_e32 v3, v11
	s_cbranch_scc0 .LBB0_2124
	v_mul_f32_e32 v8, 0xbfb8aa3b, v11
	v_exp_f32_e32 v8, v8
	v_mul_f32_e32 v9, 0xbfb8aa3b, v5
	v_exp_f32_e32 v9, v9
	v_mul_f32_e32 v13, 0xbfb8aa3b, v4
	v_add_f32_e32 v8, 1.0, v8
	v_exp_f32_e32 v15, v13
	v_add_f32_e32 v12, 1.0, v9
	v_rcp_f32_e32 v9, v8
	v_mul_f32_e32 v8, 0xbfb8aa3b, v6
	v_exp_f32_e32 v8, v8
	v_rcp_f32_e32 v13, v12
	v_add_f32_e32 v12, 1.0, v15
	v_rcp_f32_e32 v12, v12
	v_add_f32_e32 v8, 1.0, v8
	v_rcp_f32_e32 v8, v8
	s_mov_b64 s[10:11], 0
	v_pk_mul_f32 v[12:13], v[4:5], v[12:13]
	v_pk_mul_f32 v[8:9], v[2:3], v[8:9]

.LBB0_2130:
	v_cvt_pk_bf16_f32 v1, v9, v13
	ds_write_b16 v14, v1 offset:528
	ds_write_b16_d16_hi v14, v1 offset:560
	v_cvt_pk_bf16_f32 v1, v8, v12
	ds_write_b16 v14, v1 offset:784
	ds_write_b16_d16_hi v14, v1 offset:816
	v_mov_b32_e32 v1, v210
	s_lshl_b64 s[0:1], s[8:9], 1
	s_waitcnt lgkmcnt(0)
	s_barrier
	s_add_u32 s0, s25, s0
	v_lshlrev_b32_e32 v2, 4, v1
	v_and_b32_e32 v2, 0x1f0, v2
	s_addc_u32 s1, s26, s1
	v_mov_b32_e32 v3, v0
	v_lshl_add_u64 v[4:5], s[0:1], 0, v[2:3]
	s_mov_b32 s0, 0
